# adds: sample-mLSTM units request n0/gates/biases/m0/old-n row at unit start and the epilogue operands before the reductions (both copies)
# baseline (speedup 1.0000x reference)
; __device__ __forceinline__ float bf2f(bf16_t h) { return __uint_as_float((unsigned)h << 16); }
; __device__ __forceinline__ void mlstm_sample_unit(const Frame& F, int b, int h) {
;     ...
;     for (int i = tid; i < 1024; i += 512) { const int t = i >> 8, d = i & 255; const bf16_t* row = P + (size_t)(SP + b * 4 + t) * NIN;
;         sq[i] = bf2f(row[C_MQ + h * 256 + d]) * 0.0625f; sk[i] = bf2f(row[C_MK + h * 256 + d]); sv[i] = bf2f(row[C_MV + h * 256 + d]); }
;     if (tid < 64) sS[tid] = 0.f;
;     __syncthreads();
;     {
;         const int pair = tid >> 5, sub = tid & 31, t = pair >> 2, s = pair & 3; float a = 0.f, c = 0.f;
; #pragma unroll
;         for (int e = 0; e < 8; ++e) { const int d = sub * 8 + e; a += sq[t * 256 + d] * sk[s * 256 + d]; if (s == 0) c += sq[t * 256 + d] * F.in[5][(size_t)bh * 256 + d]; }
; #pragma unroll
;         for (int o = 16; o >= 1; o >>= 1) { a += __shfl_xor(a, o); c += __shfl_xor(c, o); }
;         if (sub == 0) { sS[pair] = a; if (s == 0) sS[16 + t] = c; } }
.LBB0_351:
	s_movk_i32 s35, 0x2c00
	v_mad_i64_i32 v[10:11], s[46:47], v6, s35, v[96:97]
	v_lshl_add_u64 v[12:13], v[10:11], 0, v[0:1]
	v_lshl_add_u64 v[14:15], v[10:11], 0, v[2:3]
	v_lshl_add_u64 v[10:11], v[10:11], 0, v[4:5]
	global_load_ushort v9, v[12:13], off offset:3072
	global_load_ushort v12, v[14:15], off
	global_load_ushort v10, v[10:11], off
	v_add_u32_e32 v6, 2, v6
	v_mad_i64_i32 v[16:17], s[46:47], v6, s35, v[96:97]
	v_lshl_add_u64 v[18:19], v[16:17], 0, v[0:1]
	v_lshl_add_u64 v[20:21], v[16:17], 0, v[2:3]
	v_lshl_add_u64 v[16:17], v[16:17], 0, v[4:5]
	global_load_ushort v22, v[18:19], off offset:3072
	global_load_ushort v23, v[20:21], off
	global_load_ushort v24, v[16:17], off
	s_ashr_i32 s35, s34, 31
	v_readlane_b32 s60, v245, 47
	v_readlane_b32 s61, v245, 48
	v_readlane_b32 s92, v245, 49
	v_readlane_b32 s93, v245, 50
	v_readlane_b32 vcc_lo, v245, 17
	v_readlane_b32 vcc_hi, v245, 18
	s_lshl_b64 s[54:55], s[34:35], 10
	s_add_u32 s60, s60, s54
	s_addc_u32 s61, s61, s55
	s_lshl_b64 s[54:55], s[34:35], 2
	s_add_u32 s92, s92, s54
	s_addc_u32 s93, s93, s55
	s_lshl_b32 s54, s29, 2
	v_mov_b32_e32 v56, s54
	s_add_u32 s48, s95, s54
	s_addc_u32 s49, s96, 0
	s_add_i32 s54, s28, 0x2000
	s_ashr_i32 s55, s54, 31
	s_lshl_b64 s[54:55], s[54:55], 5
	s_add_u32 s48, s48, s54
	s_addc_u32 s49, s49, s55
	v_readlane_b32 s54, v245, 21
	v_readlane_b32 s55, v245, 22
	v_lshlrev_b32_e32 v57, 2, v82
	global_load_dwordx4 v[58:61], v57, s[60:61]
	global_load_dwordx4 v[62:65], v57, s[60:61] offset:16
	global_load_dword v55, v1, s[48:49] offset:16
	global_load_dword v46, v1, s[48:49] offset:48
	global_load_dword v47, v1, s[48:49] offset:80
	global_load_dword v49, v1, s[48:49]
	global_load_dword v50, v1, s[48:49] offset:32
	global_load_dword v51, v1, s[48:49] offset:64
	global_load_dword v52, v1, s[48:49] offset:112
	global_load_dword v53, v1, s[48:49] offset:96
	global_load_dword v54, v1, s[92:93]
	global_load_dword v48, v56, vcc
	global_load_dword v66, v56, s[54:55]
	s_and_saveexec_b64 s[54:55], s[36:37]
	global_load_dword v202, v94, s[60:61]
	s_or_b64 exec, exec, s[54:55]
	v_add_u32_e32 v6, 2, v6
	s_waitcnt vmcnt(17)
	v_lshlrev_b32_e32 v9, 16, v9
	v_lshlrev_b32_e32 v11, 16, v12
	v_lshlrev_b32_e32 v10, 16, v10
	v_mul_f32_e32 v9, 0x3d800000, v9
	ds_write_b32 v7, v10 offset:8192
	ds_write2st64_b32 v7, v9, v11 offset1:16
	v_add_u32_e32 v7, 0x800, v7
	s_waitcnt vmcnt(14)
	v_lshlrev_b32_e32 v22, 16, v22
	v_lshlrev_b32_e32 v23, 16, v23
	v_lshlrev_b32_e32 v24, 16, v24
	v_mul_f32_e32 v22, 0x3d800000, v22
	ds_write_b32 v7, v24 offset:8192
	ds_write2st64_b32 v7, v22, v23 offset1:16
	v_add_u32_e32 v7, 0x800, v7
	s_or_b64 exec, exec, s[42:43]
	s_and_saveexec_b64 s[42:43], s[70:71]
	ds_write_b32 v113, v1 offset:12288
	s_or_b64 exec, exec, s[42:43]
	s_waitcnt lgkmcnt(0)
	s_barrier
	ds_read_b32 v0, v115
	ds_read_b32 v2, v117 offset:4096
	s_ashr_i32 s35, s34, 31
	v_readlane_b32 s12, v245, 37
	s_lshl_b64 s[64:65], s[34:35], 10
	v_readlane_b32 s22, v245, 47
	v_readlane_b32 s23, v245, 48
	s_add_u32 s46, s22, s64
	s_addc_u32 s47, s23, s65
	v_mov_b32_e32 v3, 0
	v_lshlrev_b32_e32 v4, 2, v82
	v_readlane_b32 s13, v245, 38
	v_readlane_b32 s14, v245, 39
	v_readlane_b32 s15, v245, 40
	v_readlane_b32 s16, v245, 41
	v_readlane_b32 s17, v245, 42
	v_readlane_b32 s18, v245, 43
	v_readlane_b32 s19, v245, 44
	v_readlane_b32 s20, v245, 45
	v_readlane_b32 s21, v245, 46
	v_readlane_b32 s24, v245, 49
	v_readlane_b32 s25, v245, 50
	v_readlane_b32 s26, v245, 51
	v_readlane_b32 s27, v245, 52
	ds_read_b32 v5, v115 offset:4
	ds_read_b32 v6, v117 offset:4100
	ds_read_b32 v7, v115 offset:8
	ds_read_b32 v8, v117 offset:4104
	ds_read_b32 v9, v115 offset:12
	ds_read_b32 v10, v117 offset:4108
	ds_read_b32 v11, v115 offset:16
	ds_read_b32 v12, v117 offset:4112
	ds_read_b32 v13, v115 offset:20
	ds_read_b32 v14, v117 offset:4116
	ds_read_b32 v15, v115 offset:24
	ds_read_b32 v16, v117 offset:4120
	ds_read_b32 v17, v115 offset:28
	ds_read_b32 v18, v117 offset:4124
	s_waitcnt lgkmcnt(0)
	s_and_saveexec_b64 s[42:43], s[2:3]
	s_waitcnt vmcnt(12)
	v_fma_f32 v3, v0, v58, 0
	v_fmac_f32_e32 v3, v5, v59
	v_fmac_f32_e32 v3, v7, v60
	v_fmac_f32_e32 v3, v9, v61
	v_fmac_f32_e32 v3, v11, v62
	v_fmac_f32_e32 v3, v13, v63
	v_fmac_f32_e32 v3, v15, v64
	v_fmac_f32_e32 v3, v17, v65
	s_or_b64 exec, exec, s[42:43]
	v_fma_f32 v0, v0, v2, 0
	v_fmac_f32_e32 v0, v5, v6
	v_fmac_f32_e32 v0, v7, v8
	v_fmac_f32_e32 v0, v9, v10
	v_fmac_f32_e32 v0, v11, v12
	v_fmac_f32_e32 v0, v13, v14
	v_fmac_f32_e32 v0, v15, v16
	v_fmac_f32_e32 v0, v17, v18
	ds_bpermute_b32 v2, v83, v3
	ds_bpermute_b32 v4, v83, v0
	s_waitcnt lgkmcnt(1)
	v_add_f32_e32 v2, v3, v2
	s_waitcnt lgkmcnt(0)
	v_add_f32_e32 v0, v0, v4
	ds_bpermute_b32 v3, v101, v2
	ds_bpermute_b32 v4, v101, v0
	s_waitcnt lgkmcnt(1)
	v_add_f32_e32 v2, v2, v3
	s_waitcnt lgkmcnt(0)
	v_add_f32_e32 v0, v0, v4
	ds_bpermute_b32 v3, v105, v2
	ds_bpermute_b32 v4, v105, v0
	s_waitcnt lgkmcnt(1)
	v_add_f32_e32 v2, v2, v3
	s_waitcnt lgkmcnt(0)
	v_add_f32_e32 v4, v0, v4
	ds_bpermute_b32 v3, v107, v2
	ds_bpermute_b32 v5, v107, v4
	s_waitcnt lgkmcnt(1)
	v_add_f32_e32 v0, v2, v3
	s_waitcnt lgkmcnt(0)
	v_add_f32_e32 v3, v4, v5
	ds_bpermute_b32 v4, v109, v3
	ds_bpermute_b32 v2, v109, v0
	s_and_saveexec_b64 s[42:43], s[74:75]
	s_cbranch_execz .LBB0_373
	s_waitcnt lgkmcnt(1)
	v_add_f32_e32 v3, v3, v4
	ds_write_b32 v119, v3 offset:12288
	s_and_b64 exec, exec, s[2:3]
	s_cbranch_execz .LBB0_373
	s_waitcnt lgkmcnt(1)
	v_add_f32_e32 v0, v0, v2
	ds_write_b32 v121, v0 offset:12352
; __device__ __forceinline__ float logsigmoid_fast(float x) { return fminf(x, 0.f) - __logf(1.f + __expf(-fabsf(x))); }
; __device__ __forceinline__ void mlstm_sample_unit(const Frame& F, int b, int h) {
;     ...
;     float li[4], bcum[4], mt[4], at[4], gs[4], sm[4][4], den[4];
;     const float m0 = F.in[6][bh];
;     { float acc = 0.f;
; #pragma unroll
;       for (int t = 0; t < 4; ++t) { const float* gp = gates + (size_t)(SP + b * 4 + t) * 8; li[t] = gp[h] + F.in[15][h]; acc += logsigmoid_fast(gp[4 + h] + F.in[16][h]); bcum[t] = acc; } }
; #pragma unroll
;     for (int t = 0; t < 4; ++t) { const float mi = bcum[t] + m0; float m = mi;
; #pragma unroll
;         for (int s = 0; s < 4; ++s) if (s <= t) m = fmaxf(m, bcum[t] - bcum[s] + li[s]);
;         mt[t] = m; at[t] = __expf(mi - m); float dsum = at[t] * sS[16 + t];
; #pragma unroll
;         for (int s = 0; s < 4; ++s) { sm[t][s] = (s <= t) ? sS[t * 4 + s] * __expf(bcum[t] - bcum[s] + li[s] - m) : 0.f; dsum += sm[t][s]; }
;         den[t] = fmaxf(fabsf(dsum), __expf(-m)); }
.LBB0_373:
	s_or_b64 exec, exec, s[42:43]
	v_readlane_b32 s12, v245, 37
	s_add_i32 s62, s28, 0x2000
	s_lshl_b64 s[82:83], s[34:35], 2
	v_readlane_b32 s24, v245, 49
	v_readlane_b32 s25, v245, 50
	s_add_u32 s46, s24, s82
	s_addc_u32 s47, s25, s83
	s_lshl_b32 s29, s29, 2
	s_add_u32 s53, s95, s29
	s_addc_u32 s91, s96, 0
	s_ashr_i32 s63, s62, 31
	v_readlane_b32 s13, v245, 38
	v_readlane_b32 s14, v245, 39
	v_readlane_b32 s15, v245, 40
	v_readlane_b32 s16, v245, 41
	v_readlane_b32 s17, v245, 42
	v_readlane_b32 s18, v245, 43
	v_readlane_b32 s19, v245, 44
	v_readlane_b32 s20, v245, 45
	v_readlane_b32 s21, v245, 46
	v_readlane_b32 s22, v245, 47
	v_readlane_b32 s23, v245, 48
	v_readlane_b32 s26, v245, 51
	v_readlane_b32 s27, v245, 52
	s_lshl_b64 s[42:43], s[62:63], 5
	v_readlane_b32 s12, v245, 21
	s_add_u32 s48, s53, s42
	v_mov_b32_e32 v0, s29
	v_readlane_b32 s13, v245, 22
	s_addc_u32 s49, s91, s43
	s_waitcnt lgkmcnt(0)
	s_barrier
	v_readlane_b32 s14, v245, 23
	v_readlane_b32 s15, v245, 24
	v_readlane_b32 s16, v245, 25
	v_readlane_b32 s17, v245, 26
	v_readlane_b32 s18, v245, 27
	v_readlane_b32 s19, v245, 28
	v_readlane_b32 s20, v245, 29
	v_readlane_b32 s21, v245, 30
	v_readlane_b32 s22, v245, 31
	v_readlane_b32 s23, v245, 32
	v_readlane_b32 s24, v245, 33
	v_readlane_b32 s25, v245, 34
	v_readlane_b32 s26, v245, 35
	v_readlane_b32 s27, v245, 36
	v_readlane_b32 s12, v245, 3
	v_readlane_b32 s26, v245, 17
	v_readlane_b32 s27, v245, 18
	v_add_u32_e32 v161, 0x2000, v85
	v_add_u32_e32 v159, 0x2400, v85
	v_add_u32_e32 v158, 0x2800, v85
	v_add_u32_e32 v95, 0x2c00, v85
	v_readlane_b32 s13, v245, 4
	v_readlane_b32 s12, v245, 1
	v_readlane_b32 s13, v245, 2
	v_readlane_b32 s14, v245, 5
	v_readlane_b32 s15, v245, 6
	v_readlane_b32 s16, v245, 7
	v_readlane_b32 s17, v245, 8
	v_readlane_b32 s18, v245, 9
	v_readlane_b32 s19, v245, 10
	v_readlane_b32 s20, v245, 11
	v_readlane_b32 s21, v245, 12
	v_readlane_b32 s22, v245, 13
	v_readlane_b32 s23, v245, 14
	v_readlane_b32 s24, v245, 15
	v_readlane_b32 s25, v245, 16
	s_waitcnt vmcnt(0)
	v_mov_b32_e32 v3, v55
	v_mov_b32_e32 v2, v66
	v_add_f32_e32 v3, v2, v3
	v_mul_f32_e64 v4, |v3|, s30
	v_exp_f32_e32 v4, v4
	v_min_f32_e32 v3, 0, v3
	v_add_f32_e32 v18, 1.0, v4
	v_cmp_gt_f32_e32 vcc, s31, v18
	s_and_b64 s[42:43], vcc, exec
	s_cselect_b32 s29, 32, 0
	s_add_i32 s60, s28, 0x2001
	s_ashr_i32 s61, s60, 31
	s_lshl_b64 s[42:43], s[60:61], 5
	s_add_u32 s92, s53, s42
	s_addc_u32 s93, s91, s43
	v_mov_b32_e32 v4, v46
	v_cndmask_b32_e32 v21, 0, v133, vcc
	v_ldexp_f32 v18, v18, s29
	v_log_f32_e32 v33, v18
	s_waitcnt vmcnt(0)
	v_add_f32_e32 v22, v2, v4
	v_mul_f32_e64 v4, |v22|, s30
	v_exp_f32_e32 v4, v4
	v_mul_f32_e32 v34, 0x3f317217, v33
	v_fma_f32 v34, v33, s90, -v34
	v_fmac_f32_e32 v34, 0x3377d1cf, v33
	v_add_f32_e32 v23, 1.0, v4
	v_cmp_gt_f32_e32 vcc, s31, v23
	s_and_b64 s[42:43], vcc, exec
	s_cselect_b32 s42, 32, 0
	s_add_i32 s54, s28, 0x2002
	s_ashr_i32 s55, s54, 31
	v_cndmask_b32_e32 v24, 0, v133, vcc
	s_lshl_b64 vcc, s[54:55], 5
	s_add_u32 vcc_lo, s53, vcc_lo
	s_addc_u32 vcc_hi, s91, vcc_hi
	v_mov_b32_e32 v4, v47
	v_mov_b32_e32 v25, v48
	v_mov_b32_e32 v20, v49
	v_mov_b32_e32 v26, v50
	v_mov_b32_e32 v28, v51
	v_fmac_f32_e32 v34, 0x3f317217, v33
	v_min_f32_e32 v22, 0, v22
	s_waitcnt vmcnt(2)
	v_add_f32_e32 v20, v25, v20
	v_add_f32_e32 v27, v2, v4
	v_mul_f32_e64 v0, |v27|, s30
	v_exp_f32_e32 v0, v0
	s_nop 0
	v_add_f32_e32 v29, 1.0, v0
	v_cmp_gt_f32_e32 vcc, s31, v29
	s_and_b64 s[48:49], vcc, exec
	s_cselect_b32 s43, 32, 0
	s_add_i32 s48, s28, 0x2003
	s_ashr_i32 s49, s48, 31
	s_lshl_b64 s[92:93], s[48:49], 5
	s_add_u32 s92, s53, s92
	s_addc_u32 s93, s91, s93
	v_mov_b32_e32 v31, v52
	v_mov_b32_e32 v32, v53
	v_mov_b32_e32 v0, v54
	v_cndmask_b32_e32 v30, 0, v133, vcc
	v_cmp_lt_f32_e64 vcc, |v33|, s94
	ds_read2_b32 v[4:5], v161 offset1:8
	ds_read2_b32 v[6:7], v159 offset1:8
	ds_read2_b32 v[8:9], v158 offset1:8
	ds_read2_b32 v[16:17], v95 offset1:8
	ds_read2_b32 v[10:11], v161 offset0:16 offset1:24
	ds_read2_b32 v[12:13], v159 offset0:16 offset1:24
	ds_read2_b32 v[14:15], v158 offset0:16 offset1:24
	v_cndmask_b32_e32 v33, v33, v34, vcc
	v_sub_f32_e32 v21, v33, v21
	v_sub_f32_e32 v3, v3, v21
	v_ldexp_f32 v21, v23, s42
	v_log_f32_e32 v23, v21
	s_waitcnt vmcnt(4)
	v_add_f32_e32 v21, v25, v26
	v_add_f32_e32 v3, 0, v3
	ds_read2_b32 v[18:19], v95 offset0:16 offset1:24
	v_mul_f32_e32 v26, 0x3f317217, v23
	v_fma_f32 v26, v23, s90, -v26
	v_fmac_f32_e32 v26, 0x3377d1cf, v23
	v_fmac_f32_e32 v26, 0x3f317217, v23
	v_cmp_lt_f32_e64 vcc, |v23|, s94
	s_nop 1
	v_cndmask_b32_e32 v23, v23, v26, vcc
	v_sub_f32_e32 v23, v23, v24
	v_sub_f32_e32 v22, v22, v23
	v_ldexp_f32 v23, v29, s43
	v_log_f32_e32 v24, v23
	s_waitcnt vmcnt(3)
	v_add_f32_e32 v23, v25, v28
	v_min_f32_e32 v26, 0, v27
	v_add_f32_e32 v22, v3, v22
	v_mul_f32_e32 v27, 0x3f317217, v24
	v_fma_f32 v27, v24, s90, -v27
	v_fmac_f32_e32 v27, 0x3377d1cf, v24
	v_fmac_f32_e32 v27, 0x3f317217, v24
	v_cmp_lt_f32_e64 vcc, |v24|, s94
	s_waitcnt vmcnt(2)
	v_add_f32_e32 v28, v2, v31
	v_mul_f32_e64 v2, |v28|, s30
	v_exp_f32_e32 v2, v2
	v_cndmask_b32_e32 v24, v24, v27, vcc
	v_sub_f32_e32 v24, v24, v30
	v_sub_f32_e32 v24, v26, v24
	v_add_f32_e32 v2, 1.0, v2
	v_cmp_gt_f32_e32 vcc, s31, v2
	s_and_b64 s[28:29], vcc, exec
	s_cselect_b32 s28, 32, 0
	v_ldexp_f32 v2, v2, s28
	v_log_f32_e32 v27, v2
	v_add_f32_e32 v2, v22, v24
	s_waitcnt vmcnt(1)
	v_add_f32_e32 v24, v25, v32
	v_min_f32_e32 v25, 0, v28
	v_mul_f32_e32 v28, 0x3f317217, v27
	v_fma_f32 v28, v27, s90, -v28
	v_fmac_f32_e32 v28, 0x3377d1cf, v27
	v_cndmask_b32_e32 v26, 0, v133, vcc
	v_fmac_f32_e32 v28, 0x3f317217, v27
	v_cmp_lt_f32_e64 vcc, |v27|, s94
	s_nop 1
	v_cndmask_b32_e32 v27, v27, v28, vcc
	v_sub_f32_e32 v26, v27, v26
	v_sub_f32_e32 v25, v25, v26
	v_add_f32_e32 v25, v2, v25
	v_sub_f32_e32 v27, v25, v3
	v_sub_f32_e32 v28, v25, v22
	s_waitcnt vmcnt(0)
	v_add_f32_e32 v26, v0, v25
	v_sub_f32_e32 v29, v25, v2
	v_sub_f32_e32 v25, v25, v25
	v_add_f32_e32 v27, v20, v27
	v_add_f32_e32 v28, v21, v28
	v_add_f32_e32 v29, v23, v29
	v_add_f32_e32 v24, v24, v25
	v_max3_f32 v25, v26, v27, v28
	v_max3_f32 v157, v25, v29, v24
	v_sub_f32_e32 v25, v26, v157
	v_sub_f32_e32 v24, v24, v157
	v_sub_f32_e32 v26, v27, v157
	v_sub_f32_e32 v27, v28, v157
	v_sub_f32_e32 v28, v29, v157
	v_mul_f32_e32 v25, 0x3fb8aa3b, v25
	v_mul_f32_e32 v24, 0x3fb8aa3b, v24
	v_mul_f32_e32 v26, 0x3fb8aa3b, v26
	v_mul_f32_e32 v27, 0x3fb8aa3b, v27
	v_mul_f32_e32 v28, 0x3fb8aa3b, v28
	v_exp_f32_e32 v100, v25
	v_exp_f32_e32 v99, v24
	v_exp_f32_e32 v102, v26
	v_exp_f32_e32 v103, v27
	v_exp_f32_e32 v98, v28
	s_and_saveexec_b64 s[46:47], s[12:13]
	s_cbranch_execz .LBB0_375
; #define LAS __attribute__((address_space(3)))
; __device__ __forceinline__ void mlstm_sample_unit(const Frame& F, int b, int h) {
;     ...
;     if (tid == 0) {
; #pragma unroll
;         for (int t = 0; t < 4; ++t) { sS[40 + t] = at[t]; sS[44 + t] = den[t];
; #pragma unroll
;             for (int s2 = 0; s2 < 4; ++s2) sS[48 + t * 4 + s2] = sm[t][s2]; } }
;     f32x4 c[2][2][4];
; #pragma unroll
;     for (int i2 = 0; i2 < 2; ++i2)
; #pragma unroll
;         for (int rg = 0; rg < 4; ++rg) c[0][i2][rg] = __builtin_nontemporal_load((const f32x4*)(c0b + rg * 2048 + i2 * 32));
; #pragma unroll
;     for (int hh = 0; hh < 4; ++hh) {
;         if (hh < 3) {
; #pragma unroll
;             for (int i2 = 0; i2 < 2; ++i2)
; #pragma unroll
;                 for (int rg = 0; rg < 4; ++rg) c[(hh + 1) & 1][i2][rg] = __builtin_nontemporal_load((const f32x4*)(c0b + rg * 2048 + ((hh + 1) * 2 + i2) * 32)); }
; #pragma unroll
;         for (int i2 = 0; i2 < 2; ++i2) { const int it = hh * 2 + i2; const int d = it * 32 + seg * 4;
;             f32x4 q[4], k[4];
; #pragma unroll
;             for (int t = 0; t < 4; ++t) { q[t] = *(const LAS f32x4*)(sq + t * 256 + d); k[t] = *(const LAS f32x4*)(sk + t * 256 + d); }
; #pragma unroll
;             for (int rg = 0; rg < 4; ++rg) { const f32x4 cv = c[hh & 1][i2][rg]; f32x4 nv = cv * decay;
; #pragma unroll
;                 for (int t = 0; t < 4; ++t) { acc[rg][t] += cv[0] * q[t][0] + cv[1] * q[t][1] + cv[2] * q[t][2] + cv[3] * q[t][3]; nv += k[t] * gv[rg][t]; }
;                 __builtin_nontemporal_store(nv, (f32x4*)(c1b + rg * 2048 + it * 32)); } }
	v_sub_f32_e32 v25, v2, v3
	v_add_f32_e32 v24, v0, v2
	v_add_f32_e32 v25, v20, v25
	v_sub_f32_e32 v27, v2, v22
	v_sub_f32_e32 v2, v2, v2
	v_max_f32_e32 v26, v24, v25
	v_add_f32_e32 v27, v21, v27
	v_add_f32_e32 v2, v23, v2
	v_max3_f32 v23, v26, v27, v2
	v_sub_f32_e32 v25, v25, v23
	v_mul_f32_e32 v25, 0x3fb8aa3b, v25
	v_sub_f32_e32 v2, v2, v23
	v_exp_f32_e32 v34, v25
	v_sub_f32_e32 v25, v27, v23
	v_mul_f32_e32 v2, 0x3fb8aa3b, v2
	v_mul_f32_e32 v25, 0x3fb8aa3b, v25
	v_exp_f32_e32 v45, v2
	v_mul_f32_e32 v2, 0xbfb8aa3b, v23
	v_sub_f32_e32 v24, v24, v23
	v_exp_f32_e32 v35, v25
	v_exp_f32_e32 v25, v2
	v_add_f32_e32 v2, v0, v22
	v_sub_f32_e32 v23, v22, v3
	v_sub_f32_e32 v22, v22, v22
	v_add_f32_e32 v40, v20, v23
	v_add_f32_e32 v21, v21, v22
	v_max3_f32 v22, v2, v40, v21
	v_sub_f32_e32 v2, v2, v22
	v_mul_f32_e32 v2, 0x3fb8aa3b, v2
	v_add_f32_e32 v0, v0, v3
	v_sub_f32_e32 v3, v3, v3
	v_exp_f32_e32 v23, v2
	v_sub_f32_e32 v2, v40, v22
	v_add_f32_e32 v3, v20, v3
	v_mul_f32_e32 v2, 0x3fb8aa3b, v2
	v_max_f32_e32 v20, v0, v3
	v_exp_f32_e32 v40, v2
	v_sub_f32_e32 v2, v21, v22
	v_sub_f32_e32 v0, v0, v20
	v_mul_f32_e32 v2, 0x3fb8aa3b, v2
	v_mul_f32_e32 v0, 0x3fb8aa3b, v0
	v_exp_f32_e32 v41, v2
	v_mul_f32_e32 v2, 0xbfb8aa3b, v22
	v_exp_f32_e32 v22, v0
	v_sub_f32_e32 v0, v3, v20
	v_mul_f32_e32 v0, 0x3fb8aa3b, v0
	v_exp_f32_e32 v0, v0
	ds_read_b32 v37, v1 offset:12288
	ds_read_b64 v[38:39], v1 offset:12304
	ds_read_b96 v[42:44], v1 offset:12320
	ds_read_b128 v[26:29], v1 offset:12352
	ds_read_b128 v[30:33], v1 offset:12336
	v_mul_f32_e32 v3, 0xbfb8aa3b, v20
	v_exp_f32_e32 v3, v3
	s_waitcnt lgkmcnt(4)
	v_mul_f32_e32 v0, v0, v37
	v_mul_f32_e32 v24, 0x3fb8aa3b, v24
	v_exp_f32_e32 v20, v2
	s_waitcnt lgkmcnt(1)
	v_fma_f32 v2, v22, v26, v0
	v_exp_f32_e32 v24, v24
	v_max_f32_e64 v26, |v2|, v3
	v_mul_f32_e32 v2, 0xbfb8aa3b, v157
	v_exp_f32_e32 v46, v2
	v_mov_b32_e32 v2, v1
	v_mov_b32_e32 v3, v1
	v_pk_mul_f32 v[38:39], v[40:41], v[38:39]
	ds_write_b128 v1, v[0:3] offset:12480
	v_fma_f32 v0, v23, v27, v38
	v_add_f32_e32 v0, v0, v39
	v_pk_mul_f32 v[34:35], v[34:35], v[42:43]
	v_max_f32_e64 v27, |v0|, v20
	v_fma_f32 v0, v24, v28, v34
	v_add_f32_e32 v0, v0, v35
	v_fmac_f32_e32 v0, v45, v44
	s_waitcnt lgkmcnt(1)
	v_pk_mul_f32 v[20:21], v[102:103], v[30:31]
	v_max_f32_e64 v28, |v0|, v25
	v_mov_b32_e32 v25, v100
	v_fma_f32 v0, v100, v29, v20
	ds_write_b128 v1, v[22:25] offset:12448
	v_add_f32_e32 v0, v0, v21
	v_pk_mul_f32 v[22:23], v[98:99], v[32:33]
	v_mul_f32_e32 v36, v45, v44
	v_add_f32_e32 v0, v0, v22
	v_add_f32_e32 v0, v23, v0
	v_mov_b32_e32 v40, v1
	v_mov_b32_e32 v41, v1
	v_mov_b32_e32 v37, v1
	v_max_f32_e64 v29, |v0|, v46
	ds_write_b128 v1, v[38:41] offset:12496
	ds_write_b128 v1, v[34:37] offset:12512
	ds_write_b128 v1, v[26:29] offset:12464
	ds_write_b128 v1, v[20:23] offset:12528
.LBB0_375:
	s_or_b64 exec, exec, s[46:47]
	s_lshl_b64 s[28:29], s[34:35], 18
	v_lshl_add_u64 v[142:143], v[86:87], 0, s[28:29]
	global_load_dwordx4 v[62:65], v[142:143], off nt
	v_add_co_u32_e32 v148, vcc, s97, v142
	s_waitcnt lgkmcnt(7)
	v_mul_f32_e32 v132, v4, v102
	v_addc_co_u32_e32 v149, vcc, 0, v143, vcc
	global_load_dwordx4 v[66:69], v[148:149], off nt
	v_add_co_u32_e32 v150, vcc, s73, v142
	s_waitcnt lgkmcnt(6)
	v_mul_f32_e32 v130, v6, v103
	v_addc_co_u32_e32 v151, vcc, 0, v143, vcc
	global_load_dwordx4 v[58:61], v[150:151], off nt
	v_add_co_u32_e32 v152, vcc, s52, v142
	s_waitcnt lgkmcnt(5)
	v_mul_f32_e32 v128, v8, v98
	v_addc_co_u32_e32 v153, vcc, 0, v143, vcc
	s_waitcnt lgkmcnt(4)
	v_mul_f32_e32 v126, v16, v99
	v_mul_f32_e32 v124, v5, v102
	v_mul_f32_e32 v122, v7, v103
	v_mul_f32_e32 v120, v9, v98
	v_mul_f32_e32 v118, v17, v99
	s_waitcnt lgkmcnt(3)
	v_mul_f32_e32 v116, v10, v102
	s_waitcnt lgkmcnt(2)
	v_mul_f32_e32 v114, v12, v103
	s_waitcnt lgkmcnt(1)
	v_mul_f32_e32 v112, v14, v98
	s_waitcnt lgkmcnt(0)
	v_mul_f32_e32 v110, v18, v99
	v_mul_f32_e32 v108, v11, v102
	v_mul_f32_e32 v106, v103, v13
	v_mul_f32_e32 v104, v98, v15
	v_mul_f32_e32 v0, v99, v19
	global_load_dwordx4 v[50:53], v[152:153], off nt
	global_load_dwordx4 v[30:33], v[142:143], off offset:128 nt
	global_load_dwordx4 v[26:29], v[148:149], off offset:128 nt
	global_load_dwordx4 v[22:25], v[150:151], off offset:128 nt
	global_load_dwordx4 v[18:21], v[152:153], off offset:128 nt
	global_load_dwordx4 v[46:49], v[142:143], off offset:256 nt
	global_load_dwordx4 v[42:45], v[148:149], off offset:256 nt
	global_load_dwordx4 v[38:41], v[150:151], off offset:256 nt
	global_load_dwordx4 v[34:37], v[152:153], off offset:256 nt
	global_load_dwordx4 v[14:17], v[142:143], off offset:384 nt
	global_load_dwordx4 v[10:13], v[148:149], off offset:384 nt
	global_load_dwordx4 v[6:9], v[150:151], off offset:384 nt
	global_load_dwordx4 v[2:5], v[152:153], off offset:384 nt
	ds_read_b128 v[70:73], v123
	ds_read_b128 v[74:77], v123 offset:4096
	ds_read_b128 v[54:57], v123 offset:1024
	ds_read_b128 v[78:81], v123 offset:5120
	ds_read_b128 v[178:181], v123 offset:2048
	ds_read_b128 v[182:185], v123 offset:6144
	ds_read_b128 v[186:189], v123 offset:3072
	ds_read_b128 v[190:193], v123 offset:7168
	s_waitcnt lgkmcnt(6)
	v_pk_mul_f32 v[138:139], v[132:133], v[74:75] op_sel_hi:[0,1]
	v_lshl_add_u64 v[134:135], v[88:89], 0, s[28:29]
	s_waitcnt vmcnt(15)
	v_mul_f32_e32 v136, v63, v71
	v_fmac_f32_e32 v136, v62, v70
	s_waitcnt lgkmcnt(5)
	v_mul_f32_e32 v140, v63, v55
	v_fmac_f32_e32 v136, v64, v72
	v_fmac_f32_e32 v140, v62, v54
	v_fmac_f32_e32 v136, v65, v73
	v_fmac_f32_e32 v140, v64, v56
	v_add_f32_e32 v177, 0, v136
	v_pk_mul_f32 v[136:137], v[132:133], v[76:77] op_sel_hi:[0,1]
	v_fmac_f32_e32 v140, v65, v57
	v_pk_fma_f32 v[136:137], v[100:101], v[64:65], v[136:137] op_sel_hi:[0,1,1]
	v_pk_fma_f32 v[138:139], v[100:101], v[62:63], v[138:139] op_sel_hi:[0,1,1]
	v_add_f32_e32 v176, 0, v140
	s_waitcnt lgkmcnt(3)
; #define LAS __attribute__((address_space(3)))
; __device__ __forceinline__ void mlstm_sample_unit(const Frame& F, int b, int h) {
;     ...
;         for (int i2 = 0; i2 < 2; ++i2) { const int it = hh * 2 + i2; const int d = it * 32 + seg * 4;
;             f32x4 q[4], k[4];
; #pragma unroll
;             for (int t = 0; t < 4; ++t) { q[t] = *(const LAS f32x4*)(sq + t * 256 + d); k[t] = *(const LAS f32x4*)(sk + t * 256 + d); }
; #pragma unroll
;             for (int rg = 0; rg < 4; ++rg) { const f32x4 cv = c[hh & 1][i2][rg]; f32x4 nv = cv * decay;
; #pragma unroll
;                 for (int t = 0; t < 4; ++t) { acc[rg][t] += cv[0] * q[t][0] + cv[1] * q[t][1] + cv[2] * q[t][2] + cv[3] * q[t][3]; nv += k[t] * gv[rg][t]; }
;                 __builtin_nontemporal_store(nv, (f32x4*)(c1b + rg * 2048 + it * 32)); } }
	v_mul_f32_e32 v140, v63, v179
	s_waitcnt lgkmcnt(1)
	v_mul_f32_e32 v63, v63, v187
	v_pk_fma_f32 v[136:137], v[130:131], v[80:81], v[136:137] op_sel_hi:[0,1,1]
	v_fmac_f32_e32 v140, v62, v178
	v_fmac_f32_e32 v63, v62, v186
	v_fmac_f32_e32 v140, v64, v180
	v_pk_fma_f32 v[136:137], v[128:129], v[184:185], v[136:137] op_sel_hi:[0,1,1]
	v_fmac_f32_e32 v63, v64, v188
	v_fmac_f32_e32 v140, v65, v181
	v_fmac_f32_e32 v63, v65, v189
	s_waitcnt lgkmcnt(0)
	v_pk_fma_f32 v[64:65], v[126:127], v[192:193], v[136:137] op_sel_hi:[0,1,1]
	s_waitcnt vmcnt(14)
	v_mul_f32_e32 v136, v67, v55
	v_pk_fma_f32 v[138:139], v[130:131], v[78:79], v[138:139] op_sel_hi:[0,1,1]
	v_fmac_f32_e32 v136, v66, v54
	v_pk_fma_f32 v[138:139], v[128:129], v[182:183], v[138:139] op_sel_hi:[0,1,1]
	v_fmac_f32_e32 v136, v68, v56
	v_add_f32_e32 v174, 0, v63
	v_pk_fma_f32 v[62:63], v[126:127], v[190:191], v[138:139] op_sel_hi:[0,1,1]
	v_fmac_f32_e32 v136, v69, v57
	global_store_dwordx4 v[134:135], v[62:65], off nt
	v_add_f32_e32 v172, 0, v136
	v_mul_f32_e32 v136, v67, v179
	v_mul_f32_e32 v62, v67, v71
	v_fmac_f32_e32 v62, v66, v70
	v_pk_mul_f32 v[64:65], v[124:125], v[74:75] op_sel_hi:[0,1]
	v_fmac_f32_e32 v136, v66, v178
	v_fmac_f32_e32 v62, v68, v72
	v_pk_fma_f32 v[64:65], v[100:101], v[66:67], v[64:65] op_sel_hi:[0,1,1]
	v_fmac_f32_e32 v136, v68, v180
	v_fmac_f32_e32 v62, v69, v73
	v_pk_fma_f32 v[64:65], v[122:123], v[78:79], v[64:65] op_sel_hi:[0,1,1]
	v_fmac_f32_e32 v136, v69, v181
	v_add_f32_e32 v173, 0, v62
	v_pk_mul_f32 v[62:63], v[124:125], v[76:77] op_sel_hi:[0,1]
	v_add_f32_e32 v171, 0, v136
	v_pk_fma_f32 v[136:137], v[120:121], v[182:183], v[64:65] op_sel_hi:[0,1,1]
	v_mul_f32_e32 v64, v67, v187
	v_pk_fma_f32 v[62:63], v[100:101], v[68:69], v[62:63] op_sel_hi:[0,1,1]
	v_fmac_f32_e32 v64, v66, v186
	v_pk_fma_f32 v[62:63], v[122:123], v[80:81], v[62:63] op_sel_hi:[0,1,1]
	v_fmac_f32_e32 v64, v68, v188
	v_add_f32_e32 v175, 0, v140
	v_pk_fma_f32 v[62:63], v[120:121], v[184:185], v[62:63] op_sel_hi:[0,1,1]
	v_fmac_f32_e32 v64, v69, v189
	v_add_co_u32_e32 v140, vcc, s97, v134
	v_add_f32_e32 v170, 0, v64
	v_pk_fma_f32 v[64:65], v[118:119], v[192:193], v[62:63] op_sel_hi:[0,1,1]
	v_pk_fma_f32 v[62:63], v[118:119], v[190:191], v[136:137] op_sel_hi:[0,1,1]
	v_addc_co_u32_e32 v141, vcc, 0, v135, vcc
	global_store_dwordx4 v[140:141], v[62:65], off nt
	s_waitcnt vmcnt(15)
	v_mul_f32_e32 v66, v59, v55
	v_fmac_f32_e32 v66, v58, v54
	v_mul_f32_e32 v62, v59, v71
	v_fmac_f32_e32 v62, v58, v70
	v_fmac_f32_e32 v62, v60, v72
	v_fmac_f32_e32 v66, v60, v56
	v_fmac_f32_e32 v62, v61, v73
	v_pk_mul_f32 v[64:65], v[116:117], v[74:75] op_sel_hi:[0,1]
	v_fmac_f32_e32 v66, v61, v57
	v_add_f32_e32 v169, 0, v62
	v_pk_mul_f32 v[62:63], v[116:117], v[76:77] op_sel_hi:[0,1]
	v_pk_fma_f32 v[64:65], v[100:101], v[58:59], v[64:65] op_sel_hi:[0,1,1]
	v_add_f32_e32 v168, 0, v66
	v_mul_f32_e32 v66, v59, v179
	v_mul_f32_e32 v59, v59, v187
	v_pk_fma_f32 v[62:63], v[100:101], v[60:61], v[62:63] op_sel_hi:[0,1,1]
	v_fmac_f32_e32 v59, v58, v186
	v_pk_fma_f32 v[62:63], v[114:115], v[80:81], v[62:63] op_sel_hi:[0,1,1]
	v_pk_fma_f32 v[64:65], v[114:115], v[78:79], v[64:65] op_sel_hi:[0,1,1]
	v_fmac_f32_e32 v66, v58, v178
	v_fmac_f32_e32 v59, v60, v188
	v_fmac_f32_e32 v66, v60, v180
	v_pk_fma_f32 v[62:63], v[112:113], v[184:185], v[62:63] op_sel_hi:[0,1,1]
	v_pk_fma_f32 v[64:65], v[112:113], v[182:183], v[64:65] op_sel_hi:[0,1,1]
	v_fmac_f32_e32 v59, v61, v189
	v_add_co_u32_e32 v138, vcc, s73, v134
	v_fmac_f32_e32 v66, v61, v181
	v_add_f32_e32 v166, 0, v59
	v_pk_fma_f32 v[60:61], v[110:111], v[192:193], v[62:63] op_sel_hi:[0,1,1]
	v_pk_fma_f32 v[58:59], v[110:111], v[190:191], v[64:65] op_sel_hi:[0,1,1]
	v_addc_co_u32_e32 v139, vcc, 0, v135, vcc
	global_store_dwordx4 v[138:139], v[58:61], off nt
	s_waitcnt vmcnt(15)
	v_mul_f32_e32 v55, v51, v55
	v_fmac_f32_e32 v55, v50, v54
	v_mul_f32_e32 v58, v51, v71
	v_fmac_f32_e32 v58, v50, v70
	v_fmac_f32_e32 v58, v52, v72
	v_fmac_f32_e32 v58, v53, v73
	v_add_f32_e32 v165, 0, v58
	v_pk_mul_f32 v[58:59], v[108:109], v[76:77] op_sel_hi:[0,1]
	v_fmac_f32_e32 v55, v52, v56
	v_pk_mul_f32 v[60:61], v[108:109], v[74:75] op_sel_hi:[0,1]
	v_pk_fma_f32 v[58:59], v[100:101], v[52:53], v[58:59] op_sel_hi:[0,1,1]
	v_fmac_f32_e32 v55, v53, v57
	v_pk_fma_f32 v[60:61], v[100:101], v[50:51], v[60:61] op_sel_hi:[0,1,1]
	v_add_f32_e32 v164, 0, v55
	v_pk_fma_f32 v[54:55], v[106:107], v[80:81], v[58:59] op_sel_hi:[0,1,1]
	v_mul_f32_e32 v58, v51, v179
	v_mul_f32_e32 v51, v51, v187
	v_fmac_f32_e32 v51, v50, v186
	v_pk_fma_f32 v[56:57], v[106:107], v[78:79], v[60:61] op_sel_hi:[0,1,1]
	v_fmac_f32_e32 v58, v50, v178
	v_fmac_f32_e32 v51, v52, v188
	v_fmac_f32_e32 v58, v52, v180
	v_pk_fma_f32 v[54:55], v[104:105], v[184:185], v[54:55] op_sel_hi:[0,1,1]
	v_pk_fma_f32 v[56:57], v[104:105], v[182:183], v[56:57] op_sel_hi:[0,1,1]
	v_fmac_f32_e32 v51, v53, v189
	v_add_co_u32_e32 v136, vcc, s52, v134
	v_fmac_f32_e32 v58, v53, v181
	v_add_f32_e32 v162, 0, v51
	v_pk_fma_f32 v[52:53], v[0:1], v[192:193], v[54:55] op_sel_hi:[0,1,1]
	v_pk_fma_f32 v[50:51], v[0:1], v[190:191], v[56:57] op_sel_hi:[0,1,1]
	v_addc_co_u32_e32 v137, vcc, 0, v135, vcc
	global_store_dwordx4 v[136:137], v[50:53], off nt
	v_add_f32_e32 v167, 0, v66
	v_add_f32_e32 v163, 0, v58
	ds_read_b128 v[74:77], v123 offset:128
	ds_read_b128 v[70:73], v123 offset:4224
	ds_read_b128 v[66:69], v123 offset:1152
	ds_read_b128 v[58:61], v123 offset:5248
	ds_read_b128 v[62:65], v123 offset:2176
	ds_read_b128 v[50:53], v123 offset:6272
	ds_read_b128 v[54:57], v123 offset:3200
	ds_read_b128 v[78:81], v123 offset:7296
	s_waitcnt vmcnt(15) lgkmcnt(7)
; #define LAS __attribute__((address_space(3)))
; __device__ __forceinline__ void mlstm_sample_unit(const Frame& F, int b, int h) {
;     ...
;         for (int i2 = 0; i2 < 2; ++i2) { const int it = hh * 2 + i2; const int d = it * 32 + seg * 4;
;             f32x4 q[4], k[4];
; #pragma unroll
;             for (int t = 0; t < 4; ++t) { q[t] = *(const LAS f32x4*)(sq + t * 256 + d); k[t] = *(const LAS f32x4*)(sk + t * 256 + d); }
; #pragma unroll
;             for (int rg = 0; rg < 4; ++rg) { const f32x4 cv = c[hh & 1][i2][rg]; f32x4 nv = cv * decay;
; #pragma unroll
;                 for (int t = 0; t < 4; ++t) { acc[rg][t] += cv[0] * q[t][0] + cv[1] * q[t][1] + cv[2] * q[t][2] + cv[3] * q[t][3]; nv += k[t] * gv[rg][t]; }
;                 __builtin_nontemporal_store(nv, (f32x4*)(c1b + rg * 2048 + it * 32)); } }
	v_mul_f32_e32 v178, v31, v75
	v_fmac_f32_e32 v178, v30, v74
	v_fmac_f32_e32 v178, v32, v76
	v_fmac_f32_e32 v178, v33, v77
	v_add_f32_e32 v194, v177, v178
	s_waitcnt lgkmcnt(5)
	v_mul_f32_e32 v177, v31, v67
	v_fmac_f32_e32 v177, v30, v66
	v_pk_mul_f32 v[180:181], v[132:133], v[70:71] op_sel_hi:[0,1]
	v_fmac_f32_e32 v177, v32, v68
	v_pk_fma_f32 v[180:181], v[100:101], v[30:31], v[180:181] op_sel_hi:[0,1,1]
	v_fmac_f32_e32 v177, v33, v69
	v_pk_mul_f32 v[178:179], v[132:133], v[72:73] op_sel_hi:[0,1]
	v_add_f32_e32 v195, v176, v177
	s_waitcnt lgkmcnt(4)
	v_pk_fma_f32 v[176:177], v[130:131], v[58:59], v[180:181] op_sel_hi:[0,1,1]
	s_waitcnt lgkmcnt(3)
	v_mul_f32_e32 v180, v31, v63
	s_waitcnt lgkmcnt(1)
	v_mul_f32_e32 v31, v31, v55
	v_pk_fma_f32 v[178:179], v[100:101], v[32:33], v[178:179] op_sel_hi:[0,1,1]
	v_fmac_f32_e32 v31, v30, v54
	v_pk_fma_f32 v[178:179], v[130:131], v[60:61], v[178:179] op_sel_hi:[0,1,1]
	v_fmac_f32_e32 v180, v30, v62
	v_fmac_f32_e32 v31, v32, v56
	v_fmac_f32_e32 v180, v32, v64
	v_pk_fma_f32 v[178:179], v[128:129], v[52:53], v[178:179] op_sel_hi:[0,1,1]
	v_pk_fma_f32 v[176:177], v[128:129], v[50:51], v[176:177] op_sel_hi:[0,1,1]
	v_fmac_f32_e32 v31, v33, v57
	v_fmac_f32_e32 v180, v33, v65
	v_add_f32_e32 v174, v174, v31
	s_waitcnt lgkmcnt(0)
	v_pk_fma_f32 v[30:31], v[126:127], v[78:79], v[176:177] op_sel_hi:[0,1,1]
	v_pk_fma_f32 v[32:33], v[126:127], v[80:81], v[178:179] op_sel_hi:[0,1,1]
	global_store_dwordx4 v[134:135], v[30:33], off offset:128 nt
	s_waitcnt vmcnt(15)
	v_mul_f32_e32 v176, v27, v67
	v_fmac_f32_e32 v176, v26, v66
	v_mul_f32_e32 v30, v27, v75
	v_fmac_f32_e32 v30, v26, v74
	v_fmac_f32_e32 v30, v28, v76
	v_fmac_f32_e32 v176, v28, v68
	v_fmac_f32_e32 v30, v29, v77
	v_pk_mul_f32 v[32:33], v[124:125], v[70:71] op_sel_hi:[0,1]
	v_fmac_f32_e32 v176, v29, v69
	v_add_f32_e32 v173, v173, v30
	v_pk_mul_f32 v[30:31], v[124:125], v[72:73] op_sel_hi:[0,1]
	v_pk_fma_f32 v[32:33], v[100:101], v[26:27], v[32:33] op_sel_hi:[0,1,1]
	v_add_f32_e32 v172, v172, v176
	v_mul_f32_e32 v176, v27, v63
	v_mul_f32_e32 v27, v27, v55
	v_pk_fma_f32 v[30:31], v[100:101], v[28:29], v[30:31] op_sel_hi:[0,1,1]
	v_fmac_f32_e32 v27, v26, v54
	v_pk_fma_f32 v[30:31], v[122:123], v[60:61], v[30:31] op_sel_hi:[0,1,1]
	v_pk_fma_f32 v[32:33], v[122:123], v[58:59], v[32:33] op_sel_hi:[0,1,1]
	v_fmac_f32_e32 v176, v26, v62
	v_fmac_f32_e32 v27, v28, v56
	v_fmac_f32_e32 v176, v28, v64
	v_pk_fma_f32 v[30:31], v[120:121], v[52:53], v[30:31] op_sel_hi:[0,1,1]
	v_pk_fma_f32 v[32:33], v[120:121], v[50:51], v[32:33] op_sel_hi:[0,1,1]
	v_fmac_f32_e32 v27, v29, v57
	v_fmac_f32_e32 v176, v29, v65
	v_add_f32_e32 v170, v170, v27
	v_pk_fma_f32 v[28:29], v[118:119], v[80:81], v[30:31] op_sel_hi:[0,1,1]
	v_pk_fma_f32 v[26:27], v[118:119], v[78:79], v[32:33] op_sel_hi:[0,1,1]
	global_store_dwordx4 v[140:141], v[26:29], off offset:128 nt
	s_waitcnt vmcnt(15)
	v_mul_f32_e32 v30, v23, v67
	v_fmac_f32_e32 v30, v22, v66
	v_mul_f32_e32 v26, v23, v75
	v_fmac_f32_e32 v26, v22, v74
	v_fmac_f32_e32 v26, v24, v76
	v_fmac_f32_e32 v30, v24, v68
	v_fmac_f32_e32 v26, v25, v77
	v_pk_mul_f32 v[28:29], v[116:117], v[70:71] op_sel_hi:[0,1]
	v_fmac_f32_e32 v30, v25, v69
	v_add_f32_e32 v169, v169, v26
	v_pk_mul_f32 v[26:27], v[116:117], v[72:73] op_sel_hi:[0,1]
	v_pk_fma_f32 v[28:29], v[100:101], v[22:23], v[28:29] op_sel_hi:[0,1,1]
	v_add_f32_e32 v168, v168, v30
	v_mul_f32_e32 v30, v23, v63
	v_mul_f32_e32 v23, v23, v55
	v_pk_fma_f32 v[26:27], v[100:101], v[24:25], v[26:27] op_sel_hi:[0,1,1]
	v_fmac_f32_e32 v23, v22, v54
	v_pk_fma_f32 v[26:27], v[114:115], v[60:61], v[26:27] op_sel_hi:[0,1,1]
	v_pk_fma_f32 v[28:29], v[114:115], v[58:59], v[28:29] op_sel_hi:[0,1,1]
	v_fmac_f32_e32 v30, v22, v62
	v_fmac_f32_e32 v23, v24, v56
	v_fmac_f32_e32 v30, v24, v64
	v_pk_fma_f32 v[26:27], v[112:113], v[52:53], v[26:27] op_sel_hi:[0,1,1]
	v_pk_fma_f32 v[28:29], v[112:113], v[50:51], v[28:29] op_sel_hi:[0,1,1]
	v_fmac_f32_e32 v23, v25, v57
	v_fmac_f32_e32 v30, v25, v65
	v_add_f32_e32 v166, v166, v23
	v_pk_fma_f32 v[24:25], v[110:111], v[80:81], v[26:27] op_sel_hi:[0,1,1]
	v_pk_fma_f32 v[22:23], v[110:111], v[78:79], v[28:29] op_sel_hi:[0,1,1]
	global_store_dwordx4 v[138:139], v[22:25], off offset:128 nt
	s_waitcnt vmcnt(15)
	v_mul_f32_e32 v26, v19, v67
	v_fmac_f32_e32 v26, v18, v66
	v_mul_f32_e32 v22, v19, v75
	v_fmac_f32_e32 v22, v18, v74
	v_fmac_f32_e32 v22, v20, v76
	v_fmac_f32_e32 v26, v20, v68
	v_fmac_f32_e32 v22, v21, v77
	v_pk_mul_f32 v[24:25], v[108:109], v[70:71] op_sel_hi:[0,1]
	v_fmac_f32_e32 v26, v21, v69
	v_add_f32_e32 v196, v165, v22
	v_pk_mul_f32 v[22:23], v[108:109], v[72:73] op_sel_hi:[0,1]
	v_pk_fma_f32 v[24:25], v[100:101], v[18:19], v[24:25] op_sel_hi:[0,1,1]
	v_add_f32_e32 v197, v164, v26
	v_mul_f32_e32 v26, v19, v63
	v_mul_f32_e32 v19, v19, v55
	v_pk_fma_f32 v[22:23], v[100:101], v[20:21], v[22:23] op_sel_hi:[0,1,1]
	v_fmac_f32_e32 v19, v18, v54
	v_pk_fma_f32 v[22:23], v[106:107], v[60:61], v[22:23] op_sel_hi:[0,1,1]
	v_pk_fma_f32 v[24:25], v[106:107], v[58:59], v[24:25] op_sel_hi:[0,1,1]
	v_fmac_f32_e32 v26, v18, v62
	v_fmac_f32_e32 v19, v20, v56
	v_fmac_f32_e32 v26, v20, v64
	v_pk_fma_f32 v[22:23], v[104:105], v[52:53], v[22:23] op_sel_hi:[0,1,1]
	v_pk_fma_f32 v[24:25], v[104:105], v[50:51], v[24:25] op_sel_hi:[0,1,1]
	v_fmac_f32_e32 v19, v21, v57
	v_fmac_f32_e32 v26, v21, v65
	v_add_f32_e32 v199, v162, v19
	v_pk_fma_f32 v[20:21], v[0:1], v[80:81], v[22:23] op_sel_hi:[0,1,1]
	v_pk_fma_f32 v[18:19], v[0:1], v[78:79], v[24:25] op_sel_hi:[0,1,1]
	global_store_dwordx4 v[136:137], v[18:21], off offset:128 nt
	v_add_f32_e32 v175, v175, v180
	v_add_f32_e32 v167, v167, v30
	v_add_f32_e32 v198, v163, v26
	global_load_dwordx4 v[62:65], v[142:143], off offset:512 nt
	global_load_dwordx4 v[58:61], v[148:149], off offset:512 nt
	global_load_dwordx4 v[54:57], v[150:151], off offset:512 nt
	global_load_dwordx4 v[50:53], v[152:153], off offset:512 nt
	global_load_dwordx4 v[30:33], v[142:143], off offset:640 nt
	global_load_dwordx4 v[26:29], v[148:149], off offset:640 nt
	global_load_dwordx4 v[22:25], v[150:151], off offset:640 nt
	global_load_dwordx4 v[18:21], v[152:153], off offset:640 nt
	ds_read_b128 v[66:69], v123 offset:256
	ds_read_b128 v[70:73], v123 offset:4352
	ds_read_b128 v[74:77], v123 offset:1280
	ds_read_b128 v[78:81], v123 offset:5376
	ds_read_b128 v[178:181], v123 offset:2304
	ds_read_b128 v[182:185], v123 offset:6400
	ds_read_b128 v[186:189], v123 offset:3328
	ds_read_b128 v[190:193], v123 offset:7424
	s_waitcnt vmcnt(23) lgkmcnt(7)
; #define LAS __attribute__((address_space(3)))
; __device__ __forceinline__ void mlstm_sample_unit(const Frame& F, int b, int h) {
;     ...
;     for (int hh = 0; hh < 4; ++hh) {
;         if (hh < 3) {
; #pragma unroll
;             for (int i2 = 0; i2 < 2; ++i2)
; #pragma unroll
;                 for (int rg = 0; rg < 4; ++rg) c[(hh + 1) & 1][i2][rg] = __builtin_nontemporal_load((const f32x4*)(c0b + rg * 2048 + ((hh + 1) * 2 + i2) * 32)); }
; #pragma unroll
;         for (int i2 = 0; i2 < 2; ++i2) { const int it = hh * 2 + i2; const int d = it * 32 + seg * 4;
;             f32x4 q[4], k[4];
; #pragma unroll
;             for (int t = 0; t < 4; ++t) { q[t] = *(const LAS f32x4*)(sq + t * 256 + d); k[t] = *(const LAS f32x4*)(sk + t * 256 + d); }
; #pragma unroll
;             for (int rg = 0; rg < 4; ++rg) { const f32x4 cv = c[hh & 1][i2][rg]; f32x4 nv = cv * decay;
; #pragma unroll
;                 for (int t = 0; t < 4; ++t) { acc[rg][t] += cv[0] * q[t][0] + cv[1] * q[t][1] + cv[2] * q[t][2] + cv[3] * q[t][3]; nv += k[t] * gv[rg][t]; }
;                 __builtin_nontemporal_store(nv, (f32x4*)(c1b + rg * 2048 + it * 32)); } }
;     }
	v_mul_f32_e32 v162, v47, v67
	v_fmac_f32_e32 v162, v46, v66
	v_fmac_f32_e32 v162, v48, v68
	v_fmac_f32_e32 v162, v49, v69
	s_waitcnt lgkmcnt(6)
	v_pk_mul_f32 v[164:165], v[132:133], v[70:71] op_sel_hi:[0,1]
	v_add_f32_e32 v171, v171, v176
	v_add_f32_e32 v177, v194, v162
	v_pk_mul_f32 v[162:163], v[132:133], v[72:73] op_sel_hi:[0,1]
	v_pk_fma_f32 v[164:165], v[100:101], v[46:47], v[164:165] op_sel_hi:[0,1,1]
	s_waitcnt lgkmcnt(5)
	v_mul_f32_e32 v176, v47, v75
	s_waitcnt lgkmcnt(3)
	v_mul_f32_e32 v194, v47, v179
	s_waitcnt lgkmcnt(1)
	v_mul_f32_e32 v47, v47, v187
	v_pk_fma_f32 v[162:163], v[100:101], v[48:49], v[162:163] op_sel_hi:[0,1,1]
	v_fmac_f32_e32 v47, v46, v186
	v_fmac_f32_e32 v176, v46, v74
	v_pk_fma_f32 v[164:165], v[130:131], v[78:79], v[164:165] op_sel_hi:[0,1,1]
	v_pk_fma_f32 v[162:163], v[130:131], v[80:81], v[162:163] op_sel_hi:[0,1,1]
	v_fmac_f32_e32 v194, v46, v178
	v_fmac_f32_e32 v47, v48, v188
	v_fmac_f32_e32 v176, v48, v76
	v_fmac_f32_e32 v194, v48, v180
	v_pk_fma_f32 v[162:163], v[128:129], v[184:185], v[162:163] op_sel_hi:[0,1,1]
	v_pk_fma_f32 v[164:165], v[128:129], v[182:183], v[164:165] op_sel_hi:[0,1,1]
	v_fmac_f32_e32 v47, v49, v189
	v_fmac_f32_e32 v176, v49, v77
	v_fmac_f32_e32 v194, v49, v181
	v_add_f32_e32 v174, v174, v47
	s_waitcnt lgkmcnt(0)
	v_pk_fma_f32 v[46:47], v[126:127], v[190:191], v[164:165] op_sel_hi:[0,1,1]
	v_pk_fma_f32 v[48:49], v[126:127], v[192:193], v[162:163] op_sel_hi:[0,1,1]
	global_store_dwordx4 v[134:135], v[46:49], off offset:256 nt
	s_waitcnt vmcnt(23)
	v_mul_f32_e32 v162, v43, v75
	v_fmac_f32_e32 v162, v42, v74
	v_mul_f32_e32 v46, v43, v67
	v_fmac_f32_e32 v46, v42, v66
	v_fmac_f32_e32 v46, v44, v68
	v_fmac_f32_e32 v162, v44, v76
	v_fmac_f32_e32 v46, v45, v69
	v_pk_mul_f32 v[48:49], v[124:125], v[70:71] op_sel_hi:[0,1]
	v_fmac_f32_e32 v162, v45, v77
	v_add_f32_e32 v173, v173, v46
	v_pk_mul_f32 v[46:47], v[124:125], v[72:73] op_sel_hi:[0,1]
	v_pk_fma_f32 v[48:49], v[100:101], v[42:43], v[48:49] op_sel_hi:[0,1,1]
	v_add_f32_e32 v172, v172, v162
	v_mul_f32_e32 v162, v43, v179
	v_mul_f32_e32 v43, v43, v187
	v_pk_fma_f32 v[46:47], v[100:101], v[44:45], v[46:47] op_sel_hi:[0,1,1]
	v_fmac_f32_e32 v43, v42, v186
	v_pk_fma_f32 v[46:47], v[122:123], v[80:81], v[46:47] op_sel_hi:[0,1,1]
	v_pk_fma_f32 v[48:49], v[122:123], v[78:79], v[48:49] op_sel_hi:[0,1,1]
	v_fmac_f32_e32 v162, v42, v178
	v_fmac_f32_e32 v43, v44, v188
	v_fmac_f32_e32 v162, v44, v180
	v_pk_fma_f32 v[46:47], v[120:121], v[184:185], v[46:47] op_sel_hi:[0,1,1]
	v_pk_fma_f32 v[48:49], v[120:121], v[182:183], v[48:49] op_sel_hi:[0,1,1]
	v_fmac_f32_e32 v43, v45, v189
	v_fmac_f32_e32 v162, v45, v181
	v_add_f32_e32 v170, v170, v43
	v_pk_fma_f32 v[44:45], v[118:119], v[192:193], v[46:47] op_sel_hi:[0,1,1]
	v_pk_fma_f32 v[42:43], v[118:119], v[190:191], v[48:49] op_sel_hi:[0,1,1]
	global_store_dwordx4 v[140:141], v[42:45], off offset:256 nt
	s_waitcnt vmcnt(23)
	v_mul_f32_e32 v46, v39, v75
	v_fmac_f32_e32 v46, v38, v74
	v_mul_f32_e32 v42, v39, v67
	v_fmac_f32_e32 v42, v38, v66
	v_fmac_f32_e32 v42, v40, v68
	v_fmac_f32_e32 v46, v40, v76
	v_fmac_f32_e32 v42, v41, v69
	v_pk_mul_f32 v[44:45], v[116:117], v[70:71] op_sel_hi:[0,1]
	v_fmac_f32_e32 v46, v41, v77
	v_add_f32_e32 v169, v169, v42
	v_pk_mul_f32 v[42:43], v[116:117], v[72:73] op_sel_hi:[0,1]
	v_pk_fma_f32 v[44:45], v[100:101], v[38:39], v[44:45] op_sel_hi:[0,1,1]
	v_add_f32_e32 v168, v168, v46
	v_mul_f32_e32 v46, v39, v179
	v_mul_f32_e32 v39, v39, v187
	v_pk_fma_f32 v[42:43], v[100:101], v[40:41], v[42:43] op_sel_hi:[0,1,1]
	v_fmac_f32_e32 v39, v38, v186
	v_pk_fma_f32 v[42:43], v[114:115], v[80:81], v[42:43] op_sel_hi:[0,1,1]
	v_pk_fma_f32 v[44:45], v[114:115], v[78:79], v[44:45] op_sel_hi:[0,1,1]
	v_fmac_f32_e32 v46, v38, v178
	v_fmac_f32_e32 v39, v40, v188
	v_fmac_f32_e32 v46, v40, v180
	v_pk_fma_f32 v[42:43], v[112:113], v[184:185], v[42:43] op_sel_hi:[0,1,1]
	v_pk_fma_f32 v[44:45], v[112:113], v[182:183], v[44:45] op_sel_hi:[0,1,1]
	v_fmac_f32_e32 v39, v41, v189
	v_fmac_f32_e32 v46, v41, v181
	v_add_f32_e32 v166, v166, v39
	v_pk_fma_f32 v[40:41], v[110:111], v[192:193], v[42:43] op_sel_hi:[0,1,1]
	v_pk_fma_f32 v[38:39], v[110:111], v[190:191], v[44:45] op_sel_hi:[0,1,1]
	global_store_dwordx4 v[138:139], v[38:41], off offset:256 nt
	s_waitcnt vmcnt(23)
	v_mul_f32_e32 v42, v35, v75
	v_fmac_f32_e32 v42, v34, v74
	v_mul_f32_e32 v38, v35, v67
	v_fmac_f32_e32 v38, v34, v66
	v_fmac_f32_e32 v38, v36, v68
	v_fmac_f32_e32 v42, v36, v76
	v_fmac_f32_e32 v38, v37, v69
	v_pk_mul_f32 v[40:41], v[108:109], v[70:71] op_sel_hi:[0,1]
	v_fmac_f32_e32 v42, v37, v77
	v_add_f32_e32 v165, v196, v38
	v_pk_mul_f32 v[38:39], v[108:109], v[72:73] op_sel_hi:[0,1]
	v_pk_fma_f32 v[40:41], v[100:101], v[34:35], v[40:41] op_sel_hi:[0,1,1]
	v_add_f32_e32 v164, v197, v42
	v_mul_f32_e32 v42, v35, v179
	v_mul_f32_e32 v35, v35, v187
	v_pk_fma_f32 v[38:39], v[100:101], v[36:37], v[38:39] op_sel_hi:[0,1,1]
	v_fmac_f32_e32 v35, v34, v186
	v_pk_fma_f32 v[38:39], v[106:107], v[80:81], v[38:39] op_sel_hi:[0,1,1]
	v_pk_fma_f32 v[40:41], v[106:107], v[78:79], v[40:41] op_sel_hi:[0,1,1]
	v_fmac_f32_e32 v42, v34, v178
	v_fmac_f32_e32 v35, v36, v188
	v_fmac_f32_e32 v42, v36, v180
	v_pk_fma_f32 v[38:39], v[104:105], v[184:185], v[38:39] op_sel_hi:[0,1,1]
	v_pk_fma_f32 v[40:41], v[104:105], v[182:183], v[40:41] op_sel_hi:[0,1,1]
	v_fmac_f32_e32 v35, v37, v189
	v_add_f32_e32 v171, v171, v162
	v_fmac_f32_e32 v42, v37, v181
	v_add_f32_e32 v162, v199, v35
	v_pk_fma_f32 v[36:37], v[0:1], v[192:193], v[38:39] op_sel_hi:[0,1,1]
	v_pk_fma_f32 v[34:35], v[0:1], v[190:191], v[40:41] op_sel_hi:[0,1,1]
	global_store_dwordx4 v[136:137], v[34:37], off offset:256 nt
	v_add_f32_e32 v167, v167, v46
	v_add_f32_e32 v163, v198, v42
	ds_read_b128 v[34:37], v123 offset:384
	ds_read_b128 v[46:49], v123 offset:4480
	ds_read_b128 v[42:45], v123 offset:1408
	ds_read_b128 v[38:41], v123 offset:5504
	ds_read_b128 v[70:73], v123 offset:2432
	ds_read_b128 v[66:69], v123 offset:6528
	ds_read_b128 v[74:77], v123 offset:3456
	ds_read_b128 v[78:81], v123 offset:7552
	s_waitcnt vmcnt(23) lgkmcnt(7)
; #define LAS __attribute__((address_space(3)))
; __device__ __forceinline__ void mlstm_sample_unit(const Frame& F, int b, int h) {
;     ...
;     for (int hh = 0; hh < 4; ++hh) {
;         if (hh < 3) {
; #pragma unroll
;             for (int i2 = 0; i2 < 2; ++i2)
; #pragma unroll
;                 for (int rg = 0; rg < 4; ++rg) c[(hh + 1) & 1][i2][rg] = __builtin_nontemporal_load((const f32x4*)(c0b + rg * 2048 + ((hh + 1) * 2 + i2) * 32)); }
; #pragma unroll
;         for (int i2 = 0; i2 < 2; ++i2) { const int it = hh * 2 + i2; const int d = it * 32 + seg * 4;
;             f32x4 q[4], k[4];
; #pragma unroll
;             for (int t = 0; t < 4; ++t) { q[t] = *(const LAS f32x4*)(sq + t * 256 + d); k[t] = *(const LAS f32x4*)(sk + t * 256 + d); }
; #pragma unroll
;             for (int rg = 0; rg < 4; ++rg) { const f32x4 cv = c[hh & 1][i2][rg]; f32x4 nv = cv * decay;
; #pragma unroll
;                 for (int t = 0; t < 4; ++t) { acc[rg][t] += cv[0] * q[t][0] + cv[1] * q[t][1] + cv[2] * q[t][2] + cv[3] * q[t][3]; nv += k[t] * gv[rg][t]; }
;                 __builtin_nontemporal_store(nv, (f32x4*)(c1b + rg * 2048 + it * 32)); } }
;     }
	v_mul_f32_e32 v178, v15, v35
	v_fmac_f32_e32 v178, v14, v34
	v_fmac_f32_e32 v178, v16, v36
	v_fmac_f32_e32 v178, v17, v37
	v_add_f32_e32 v186, v177, v178
	s_waitcnt lgkmcnt(5)
	v_mul_f32_e32 v177, v15, v43
	v_fmac_f32_e32 v177, v14, v42
	v_pk_mul_f32 v[180:181], v[132:133], v[46:47] op_sel_hi:[0,1]
	v_fmac_f32_e32 v177, v16, v44
	v_add_f32_e32 v176, v195, v176
	v_pk_fma_f32 v[180:181], v[100:101], v[14:15], v[180:181] op_sel_hi:[0,1,1]
	v_fmac_f32_e32 v177, v17, v45
	v_pk_mul_f32 v[178:179], v[132:133], v[48:49] op_sel_hi:[0,1]
	v_add_f32_e32 v187, v176, v177
	s_waitcnt lgkmcnt(4)
	v_pk_fma_f32 v[176:177], v[130:131], v[38:39], v[180:181] op_sel_hi:[0,1,1]
	s_waitcnt lgkmcnt(3)
	v_mul_f32_e32 v180, v15, v71
	s_waitcnt lgkmcnt(1)
	v_mul_f32_e32 v15, v15, v75
	v_pk_fma_f32 v[178:179], v[100:101], v[16:17], v[178:179] op_sel_hi:[0,1,1]
	v_fmac_f32_e32 v15, v14, v74
	v_pk_fma_f32 v[178:179], v[130:131], v[40:41], v[178:179] op_sel_hi:[0,1,1]
	v_fmac_f32_e32 v180, v14, v70
	v_fmac_f32_e32 v15, v16, v76
	v_fmac_f32_e32 v180, v16, v72
	v_pk_fma_f32 v[178:179], v[128:129], v[68:69], v[178:179] op_sel_hi:[0,1,1]
	v_pk_fma_f32 v[176:177], v[128:129], v[66:67], v[176:177] op_sel_hi:[0,1,1]
	v_fmac_f32_e32 v15, v17, v77
	v_fmac_f32_e32 v180, v17, v73
	v_add_f32_e32 v189, v174, v15
	s_waitcnt lgkmcnt(0)
	v_pk_fma_f32 v[14:15], v[126:127], v[78:79], v[176:177] op_sel_hi:[0,1,1]
	v_pk_fma_f32 v[16:17], v[126:127], v[80:81], v[178:179] op_sel_hi:[0,1,1]
	global_store_dwordx4 v[134:135], v[14:17], off offset:384 nt
	v_add_f32_e32 v175, v175, v194
	v_add_f32_e32 v188, v175, v180
	s_waitcnt vmcnt(23)
	v_mul_f32_e32 v14, v11, v35
	v_fmac_f32_e32 v14, v10, v34
	v_fmac_f32_e32 v14, v12, v36
	v_fmac_f32_e32 v14, v13, v37
	v_add_f32_e32 v190, v173, v14
	v_mul_f32_e32 v173, v11, v43
	v_fmac_f32_e32 v173, v10, v42
	v_fmac_f32_e32 v173, v12, v44
	v_pk_mul_f32 v[16:17], v[124:125], v[46:47] op_sel_hi:[0,1]
	v_fmac_f32_e32 v173, v13, v45
	v_pk_mul_f32 v[14:15], v[124:125], v[48:49] op_sel_hi:[0,1]
	v_pk_fma_f32 v[16:17], v[100:101], v[10:11], v[16:17] op_sel_hi:[0,1,1]
	v_add_f32_e32 v191, v172, v173
	v_mul_f32_e32 v172, v11, v71
	v_mul_f32_e32 v11, v11, v75
	v_pk_fma_f32 v[14:15], v[100:101], v[12:13], v[14:15] op_sel_hi:[0,1,1]
	v_fmac_f32_e32 v11, v10, v74
	v_pk_fma_f32 v[14:15], v[122:123], v[40:41], v[14:15] op_sel_hi:[0,1,1]
	v_pk_fma_f32 v[16:17], v[122:123], v[38:39], v[16:17] op_sel_hi:[0,1,1]
	v_fmac_f32_e32 v172, v10, v70
	v_fmac_f32_e32 v11, v12, v76
	v_fmac_f32_e32 v172, v12, v72
	v_pk_fma_f32 v[14:15], v[120:121], v[68:69], v[14:15] op_sel_hi:[0,1,1]
	v_pk_fma_f32 v[16:17], v[120:121], v[66:67], v[16:17] op_sel_hi:[0,1,1]
	v_fmac_f32_e32 v11, v13, v77
	v_fmac_f32_e32 v172, v13, v73
	v_add_f32_e32 v193, v170, v11
	v_pk_fma_f32 v[12:13], v[118:119], v[80:81], v[14:15] op_sel_hi:[0,1,1]
	v_pk_fma_f32 v[10:11], v[118:119], v[78:79], v[16:17] op_sel_hi:[0,1,1]
	global_store_dwordx4 v[140:141], v[10:13], off offset:384 nt
	s_waitcnt vmcnt(23)
	v_mul_f32_e32 v14, v7, v43
	v_fmac_f32_e32 v14, v6, v42
	v_mul_f32_e32 v10, v7, v35
	v_fmac_f32_e32 v10, v6, v34
	v_fmac_f32_e32 v10, v8, v36
	v_fmac_f32_e32 v14, v8, v44
	v_fmac_f32_e32 v10, v9, v37
	v_pk_mul_f32 v[12:13], v[116:117], v[46:47] op_sel_hi:[0,1]
	v_fmac_f32_e32 v14, v9, v45
	v_add_f32_e32 v194, v169, v10
	v_pk_mul_f32 v[10:11], v[116:117], v[48:49] op_sel_hi:[0,1]
	v_pk_fma_f32 v[12:13], v[100:101], v[6:7], v[12:13] op_sel_hi:[0,1,1]
	v_add_f32_e32 v195, v168, v14
	v_mul_f32_e32 v14, v7, v71
	v_mul_f32_e32 v7, v7, v75
	v_pk_fma_f32 v[10:11], v[100:101], v[8:9], v[10:11] op_sel_hi:[0,1,1]
	v_fmac_f32_e32 v7, v6, v74
	v_pk_fma_f32 v[10:11], v[114:115], v[40:41], v[10:11] op_sel_hi:[0,1,1]
	v_pk_fma_f32 v[12:13], v[114:115], v[38:39], v[12:13] op_sel_hi:[0,1,1]
	v_fmac_f32_e32 v14, v6, v70
	v_fmac_f32_e32 v7, v8, v76
	v_fmac_f32_e32 v14, v8, v72
	v_pk_fma_f32 v[10:11], v[112:113], v[68:69], v[10:11] op_sel_hi:[0,1,1]
	v_pk_fma_f32 v[12:13], v[112:113], v[66:67], v[12:13] op_sel_hi:[0,1,1]
	v_fmac_f32_e32 v7, v9, v77
	v_fmac_f32_e32 v14, v9, v73
	v_add_f32_e32 v197, v166, v7
	v_pk_fma_f32 v[8:9], v[110:111], v[80:81], v[10:11] op_sel_hi:[0,1,1]
	v_pk_fma_f32 v[6:7], v[110:111], v[78:79], v[12:13] op_sel_hi:[0,1,1]
	global_store_dwordx4 v[138:139], v[6:9], off offset:384 nt
	s_waitcnt vmcnt(23)
	v_mul_f32_e32 v10, v3, v43
	v_fmac_f32_e32 v10, v2, v42
	v_mul_f32_e32 v6, v3, v35
	v_fmac_f32_e32 v6, v2, v34
	v_fmac_f32_e32 v6, v4, v36
	v_fmac_f32_e32 v10, v4, v44
	v_fmac_f32_e32 v6, v5, v37
	v_pk_mul_f32 v[8:9], v[108:109], v[46:47] op_sel_hi:[0,1]
	v_fmac_f32_e32 v10, v5, v45
	v_add_f32_e32 v198, v165, v6
	v_pk_mul_f32 v[6:7], v[108:109], v[48:49] op_sel_hi:[0,1]
	v_pk_fma_f32 v[8:9], v[100:101], v[2:3], v[8:9] op_sel_hi:[0,1,1]
	v_add_f32_e32 v199, v164, v10
	v_mul_f32_e32 v10, v3, v71
	v_mul_f32_e32 v3, v3, v75
	v_pk_fma_f32 v[6:7], v[100:101], v[4:5], v[6:7] op_sel_hi:[0,1,1]
	v_fmac_f32_e32 v3, v2, v74
	v_pk_fma_f32 v[6:7], v[106:107], v[40:41], v[6:7] op_sel_hi:[0,1,1]
	v_pk_fma_f32 v[8:9], v[106:107], v[38:39], v[8:9] op_sel_hi:[0,1,1]
	v_fmac_f32_e32 v10, v2, v70
	v_fmac_f32_e32 v3, v4, v76
	v_fmac_f32_e32 v10, v4, v72
	v_pk_fma_f32 v[6:7], v[104:105], v[68:69], v[6:7] op_sel_hi:[0,1,1]
	v_pk_fma_f32 v[8:9], v[104:105], v[66:67], v[8:9] op_sel_hi:[0,1,1]
	v_fmac_f32_e32 v3, v5, v77
	v_fmac_f32_e32 v10, v5, v73
	v_add_f32_e32 v201, v162, v3
	v_pk_fma_f32 v[4:5], v[0:1], v[80:81], v[6:7] op_sel_hi:[0,1,1]
	v_pk_fma_f32 v[2:3], v[0:1], v[78:79], v[8:9] op_sel_hi:[0,1,1]
	global_store_dwordx4 v[136:137], v[2:5], off offset:384 nt
	v_add_f32_e32 v192, v171, v172
	v_add_f32_e32 v196, v167, v14
	v_add_f32_e32 v200, v163, v10
	global_load_dwordx4 v[46:49], v[142:143], off offset:768 nt
	global_load_dwordx4 v[42:45], v[148:149], off offset:768 nt
	global_load_dwordx4 v[38:41], v[150:151], off offset:768 nt
	global_load_dwordx4 v[34:37], v[152:153], off offset:768 nt
	global_load_dwordx4 v[14:17], v[142:143], off offset:896 nt
	global_load_dwordx4 v[10:13], v[148:149], off offset:896 nt
	global_load_dwordx4 v[6:9], v[150:151], off offset:896 nt
	global_load_dwordx4 v[2:5], v[152:153], off offset:896 nt
	ds_read_b128 v[66:69], v123 offset:512
	ds_read_b128 v[70:73], v123 offset:4608
	ds_read_b128 v[74:77], v123 offset:1536
	ds_read_b128 v[78:81], v123 offset:5632
	ds_read_b128 v[170:173], v123 offset:2560
	ds_read_b128 v[174:177], v123 offset:6656
	ds_read_b128 v[178:181], v123 offset:3584
	ds_read_b128 v[182:185], v123 offset:7680
	s_waitcnt vmcnt(23) lgkmcnt(7)
; #define LAS __attribute__((address_space(3)))
; __device__ __forceinline__ void mlstm_sample_unit(const Frame& F, int b, int h) {
;     ...
;     for (int hh = 0; hh < 4; ++hh) {
;         if (hh < 3) {
; #pragma unroll
;             for (int i2 = 0; i2 < 2; ++i2)
; #pragma unroll
;                 for (int rg = 0; rg < 4; ++rg) c[(hh + 1) & 1][i2][rg] = __builtin_nontemporal_load((const f32x4*)(c0b + rg * 2048 + ((hh + 1) * 2 + i2) * 32)); }
; #pragma unroll
;         for (int i2 = 0; i2 < 2; ++i2) { const int it = hh * 2 + i2; const int d = it * 32 + seg * 4;
;             f32x4 q[4], k[4];
; #pragma unroll
;             for (int t = 0; t < 4; ++t) { q[t] = *(const LAS f32x4*)(sq + t * 256 + d); k[t] = *(const LAS f32x4*)(sk + t * 256 + d); }
; #pragma unroll
;             for (int rg = 0; rg < 4; ++rg) { const f32x4 cv = c[hh & 1][i2][rg]; f32x4 nv = cv * decay;
; #pragma unroll
;                 for (int t = 0; t < 4; ++t) { acc[rg][t] += cv[0] * q[t][0] + cv[1] * q[t][1] + cv[2] * q[t][2] + cv[3] * q[t][3]; nv += k[t] * gv[rg][t]; }
;                 __builtin_nontemporal_store(nv, (f32x4*)(c1b + rg * 2048 + it * 32)); } }
;     }
	v_mul_f32_e32 v142, v63, v67
	s_waitcnt lgkmcnt(5)
	v_mul_f32_e32 v150, v63, v75
	v_fmac_f32_e32 v142, v62, v66
	v_fmac_f32_e32 v150, v62, v74
	v_fmac_f32_e32 v142, v64, v68
	v_fmac_f32_e32 v150, v64, v76
	v_fmac_f32_e32 v142, v65, v69
	v_pk_mul_f32 v[148:149], v[132:133], v[70:71] op_sel_hi:[0,1]
	v_fmac_f32_e32 v150, v65, v77
	v_add_f32_e32 v169, v186, v142
	v_pk_mul_f32 v[142:143], v[132:133], v[72:73] op_sel_hi:[0,1]
	v_pk_fma_f32 v[148:149], v[100:101], v[62:63], v[148:149] op_sel_hi:[0,1,1]
	v_add_f32_e32 v168, v187, v150
	s_waitcnt lgkmcnt(3)
	v_mul_f32_e32 v150, v63, v171
	s_waitcnt lgkmcnt(1)
	v_mul_f32_e32 v63, v63, v179
	v_pk_fma_f32 v[142:143], v[100:101], v[64:65], v[142:143] op_sel_hi:[0,1,1]
	v_fmac_f32_e32 v63, v62, v178
	v_pk_fma_f32 v[148:149], v[130:131], v[78:79], v[148:149] op_sel_hi:[0,1,1]
	v_pk_fma_f32 v[142:143], v[130:131], v[80:81], v[142:143] op_sel_hi:[0,1,1]
	v_fmac_f32_e32 v150, v62, v170
	v_fmac_f32_e32 v63, v64, v180
	v_fmac_f32_e32 v150, v64, v172
	v_pk_fma_f32 v[142:143], v[128:129], v[176:177], v[142:143] op_sel_hi:[0,1,1]
	v_pk_fma_f32 v[148:149], v[128:129], v[174:175], v[148:149] op_sel_hi:[0,1,1]
	v_fmac_f32_e32 v63, v65, v181
	v_fmac_f32_e32 v150, v65, v173
	v_add_f32_e32 v166, v189, v63
	s_waitcnt lgkmcnt(0)
	v_pk_fma_f32 v[62:63], v[126:127], v[182:183], v[148:149] op_sel_hi:[0,1,1]
	v_pk_fma_f32 v[64:65], v[126:127], v[184:185], v[142:143] op_sel_hi:[0,1,1]
	global_store_dwordx4 v[134:135], v[62:65], off offset:512 nt
	s_waitcnt vmcnt(23)
	v_mul_f32_e32 v142, v59, v75
	v_fmac_f32_e32 v142, v58, v74
	v_mul_f32_e32 v62, v59, v67
	v_fmac_f32_e32 v62, v58, v66
	v_fmac_f32_e32 v62, v60, v68
	v_fmac_f32_e32 v142, v60, v76
	v_fmac_f32_e32 v62, v61, v69
	v_pk_mul_f32 v[64:65], v[124:125], v[70:71] op_sel_hi:[0,1]
	v_fmac_f32_e32 v142, v61, v77
	v_add_f32_e32 v165, v190, v62
	v_pk_mul_f32 v[62:63], v[124:125], v[72:73] op_sel_hi:[0,1]
	v_pk_fma_f32 v[64:65], v[100:101], v[58:59], v[64:65] op_sel_hi:[0,1,1]
	v_add_f32_e32 v164, v191, v142
	v_mul_f32_e32 v142, v59, v171
	v_mul_f32_e32 v59, v59, v179
	v_pk_fma_f32 v[62:63], v[100:101], v[60:61], v[62:63] op_sel_hi:[0,1,1]
	v_fmac_f32_e32 v59, v58, v178
	v_pk_fma_f32 v[62:63], v[122:123], v[80:81], v[62:63] op_sel_hi:[0,1,1]
	v_pk_fma_f32 v[64:65], v[122:123], v[78:79], v[64:65] op_sel_hi:[0,1,1]
	v_fmac_f32_e32 v142, v58, v170
	v_fmac_f32_e32 v59, v60, v180
	v_fmac_f32_e32 v142, v60, v172
	v_pk_fma_f32 v[62:63], v[120:121], v[176:177], v[62:63] op_sel_hi:[0,1,1]
	v_pk_fma_f32 v[64:65], v[120:121], v[174:175], v[64:65] op_sel_hi:[0,1,1]
	v_fmac_f32_e32 v59, v61, v181
	v_fmac_f32_e32 v142, v61, v173
	v_add_f32_e32 v162, v193, v59
	v_pk_fma_f32 v[60:61], v[118:119], v[184:185], v[62:63] op_sel_hi:[0,1,1]
	v_pk_fma_f32 v[58:59], v[118:119], v[182:183], v[64:65] op_sel_hi:[0,1,1]
	global_store_dwordx4 v[140:141], v[58:61], off offset:512 nt
	s_waitcnt vmcnt(23)
	v_mul_f32_e32 v62, v55, v75
	v_fmac_f32_e32 v62, v54, v74
	v_mul_f32_e32 v58, v55, v67
	v_fmac_f32_e32 v58, v54, v66
	v_fmac_f32_e32 v58, v56, v68
	v_fmac_f32_e32 v62, v56, v76
	v_fmac_f32_e32 v58, v57, v69
	v_pk_mul_f32 v[60:61], v[116:117], v[70:71] op_sel_hi:[0,1]
	v_fmac_f32_e32 v62, v57, v77
	v_add_f32_e32 v153, v194, v58
	v_pk_mul_f32 v[58:59], v[116:117], v[72:73] op_sel_hi:[0,1]
	v_pk_fma_f32 v[60:61], v[100:101], v[54:55], v[60:61] op_sel_hi:[0,1,1]
	v_add_f32_e32 v152, v195, v62
	v_mul_f32_e32 v62, v55, v171
	v_mul_f32_e32 v55, v55, v179
	v_pk_fma_f32 v[58:59], v[100:101], v[56:57], v[58:59] op_sel_hi:[0,1,1]
	v_fmac_f32_e32 v55, v54, v178
	v_pk_fma_f32 v[58:59], v[114:115], v[80:81], v[58:59] op_sel_hi:[0,1,1]
	v_pk_fma_f32 v[60:61], v[114:115], v[78:79], v[60:61] op_sel_hi:[0,1,1]
	v_fmac_f32_e32 v62, v54, v170
	v_fmac_f32_e32 v55, v56, v180
	v_fmac_f32_e32 v62, v56, v172
	v_pk_fma_f32 v[58:59], v[112:113], v[176:177], v[58:59] op_sel_hi:[0,1,1]
	v_pk_fma_f32 v[60:61], v[112:113], v[174:175], v[60:61] op_sel_hi:[0,1,1]
	v_fmac_f32_e32 v55, v57, v181
	v_add_f32_e32 v167, v188, v150
	v_fmac_f32_e32 v62, v57, v173
	v_add_f32_e32 v150, v197, v55
	v_pk_fma_f32 v[56:57], v[110:111], v[184:185], v[58:59] op_sel_hi:[0,1,1]
	v_pk_fma_f32 v[54:55], v[110:111], v[182:183], v[60:61] op_sel_hi:[0,1,1]
	global_store_dwordx4 v[138:139], v[54:57], off offset:512 nt
	s_waitcnt vmcnt(23)
	v_mul_f32_e32 v58, v51, v75
	v_fmac_f32_e32 v58, v50, v74
	v_mul_f32_e32 v54, v51, v67
	v_fmac_f32_e32 v54, v50, v66
	v_fmac_f32_e32 v54, v52, v68
	v_fmac_f32_e32 v58, v52, v76
	v_fmac_f32_e32 v54, v53, v69
	v_pk_mul_f32 v[56:57], v[108:109], v[70:71] op_sel_hi:[0,1]
	v_fmac_f32_e32 v58, v53, v77
	v_add_f32_e32 v149, v198, v54
	v_pk_mul_f32 v[54:55], v[108:109], v[72:73] op_sel_hi:[0,1]
	v_pk_fma_f32 v[56:57], v[100:101], v[50:51], v[56:57] op_sel_hi:[0,1,1]
	v_add_f32_e32 v148, v199, v58
	v_mul_f32_e32 v58, v51, v171
	v_mul_f32_e32 v51, v51, v179
	v_pk_fma_f32 v[54:55], v[100:101], v[52:53], v[54:55] op_sel_hi:[0,1,1]
	v_fmac_f32_e32 v51, v50, v178
	v_pk_fma_f32 v[54:55], v[106:107], v[80:81], v[54:55] op_sel_hi:[0,1,1]
	v_pk_fma_f32 v[56:57], v[106:107], v[78:79], v[56:57] op_sel_hi:[0,1,1]
	v_fmac_f32_e32 v58, v50, v170
	v_fmac_f32_e32 v51, v52, v180
	v_fmac_f32_e32 v58, v52, v172
	v_pk_fma_f32 v[54:55], v[104:105], v[176:177], v[54:55] op_sel_hi:[0,1,1]
	v_pk_fma_f32 v[56:57], v[104:105], v[174:175], v[56:57] op_sel_hi:[0,1,1]
	v_fmac_f32_e32 v51, v53, v181
	v_add_f32_e32 v163, v192, v142
	v_fmac_f32_e32 v58, v53, v173
	v_add_f32_e32 v142, v201, v51
	v_pk_fma_f32 v[52:53], v[0:1], v[184:185], v[54:55] op_sel_hi:[0,1,1]
	v_pk_fma_f32 v[50:51], v[0:1], v[182:183], v[56:57] op_sel_hi:[0,1,1]
	global_store_dwordx4 v[136:137], v[50:53], off offset:512 nt
	v_add_f32_e32 v151, v196, v62
	v_add_f32_e32 v143, v200, v58
	ds_read_b128 v[50:53], v123 offset:640
	ds_read_b128 v[62:65], v123 offset:4736
	ds_read_b128 v[58:61], v123 offset:1664
	ds_read_b128 v[54:57], v123 offset:5760
	ds_read_b128 v[70:73], v123 offset:2688
	ds_read_b128 v[66:69], v123 offset:6784
	ds_read_b128 v[74:77], v123 offset:3712
	ds_read_b128 v[78:81], v123 offset:7808
	s_waitcnt vmcnt(23) lgkmcnt(7)
; #define LAS __attribute__((address_space(3)))
; __device__ __forceinline__ void mlstm_sample_unit(const Frame& F, int b, int h) {
;     ...
;     for (int hh = 0; hh < 4; ++hh) {
;         if (hh < 3) {
; #pragma unroll
;             for (int i2 = 0; i2 < 2; ++i2)
; #pragma unroll
;                 for (int rg = 0; rg < 4; ++rg) c[(hh + 1) & 1][i2][rg] = __builtin_nontemporal_load((const f32x4*)(c0b + rg * 2048 + ((hh + 1) * 2 + i2) * 32)); }
; #pragma unroll
;         for (int i2 = 0; i2 < 2; ++i2) { const int it = hh * 2 + i2; const int d = it * 32 + seg * 4;
;             f32x4 q[4], k[4];
; #pragma unroll
;             for (int t = 0; t < 4; ++t) { q[t] = *(const LAS f32x4*)(sq + t * 256 + d); k[t] = *(const LAS f32x4*)(sk + t * 256 + d); }
; #pragma unroll
;             for (int rg = 0; rg < 4; ++rg) { const f32x4 cv = c[hh & 1][i2][rg]; f32x4 nv = cv * decay;
; #pragma unroll
;                 for (int t = 0; t < 4; ++t) { acc[rg][t] += cv[0] * q[t][0] + cv[1] * q[t][1] + cv[2] * q[t][2] + cv[3] * q[t][3]; nv += k[t] * gv[rg][t]; }
;                 __builtin_nontemporal_store(nv, (f32x4*)(c1b + rg * 2048 + it * 32)); } }
;     }
	v_mul_f32_e32 v170, v31, v51
	v_fmac_f32_e32 v170, v30, v50
	v_fmac_f32_e32 v170, v32, v52
	v_fmac_f32_e32 v170, v33, v53
	v_add_f32_e32 v174, v169, v170
	s_waitcnt lgkmcnt(5)
	v_mul_f32_e32 v169, v31, v59
	v_fmac_f32_e32 v169, v30, v58
	v_pk_mul_f32 v[172:173], v[132:133], v[62:63] op_sel_hi:[0,1]
	v_fmac_f32_e32 v169, v32, v60
	v_pk_fma_f32 v[172:173], v[100:101], v[30:31], v[172:173] op_sel_hi:[0,1,1]
	v_fmac_f32_e32 v169, v33, v61
	v_pk_mul_f32 v[170:171], v[132:133], v[64:65] op_sel_hi:[0,1]
	v_add_f32_e32 v175, v168, v169
	s_waitcnt lgkmcnt(4)
	v_pk_fma_f32 v[168:169], v[130:131], v[54:55], v[172:173] op_sel_hi:[0,1,1]
	s_waitcnt lgkmcnt(3)
	v_mul_f32_e32 v172, v31, v71
	s_waitcnt lgkmcnt(1)
	v_mul_f32_e32 v31, v31, v75
	v_pk_fma_f32 v[170:171], v[100:101], v[32:33], v[170:171] op_sel_hi:[0,1,1]
	v_fmac_f32_e32 v31, v30, v74
	v_pk_fma_f32 v[170:171], v[130:131], v[56:57], v[170:171] op_sel_hi:[0,1,1]
	v_fmac_f32_e32 v172, v30, v70
	v_fmac_f32_e32 v31, v32, v76
	v_fmac_f32_e32 v172, v32, v72
	v_pk_fma_f32 v[170:171], v[128:129], v[68:69], v[170:171] op_sel_hi:[0,1,1]
	v_pk_fma_f32 v[168:169], v[128:129], v[66:67], v[168:169] op_sel_hi:[0,1,1]
	v_fmac_f32_e32 v31, v33, v77
	v_fmac_f32_e32 v172, v33, v73
	v_add_f32_e32 v166, v166, v31
	s_waitcnt lgkmcnt(0)
	v_pk_fma_f32 v[30:31], v[126:127], v[78:79], v[168:169] op_sel_hi:[0,1,1]
	v_pk_fma_f32 v[32:33], v[126:127], v[80:81], v[170:171] op_sel_hi:[0,1,1]
	global_store_dwordx4 v[134:135], v[30:33], off offset:640 nt
	s_waitcnt vmcnt(23)
	v_mul_f32_e32 v168, v27, v59
	v_fmac_f32_e32 v168, v26, v58
	v_mul_f32_e32 v30, v27, v51
	v_fmac_f32_e32 v30, v26, v50
	v_fmac_f32_e32 v30, v28, v52
	v_fmac_f32_e32 v168, v28, v60
	v_fmac_f32_e32 v30, v29, v53
	v_pk_mul_f32 v[32:33], v[124:125], v[62:63] op_sel_hi:[0,1]
	v_fmac_f32_e32 v168, v29, v61
	v_add_f32_e32 v165, v165, v30
	v_pk_mul_f32 v[30:31], v[124:125], v[64:65] op_sel_hi:[0,1]
	v_pk_fma_f32 v[32:33], v[100:101], v[26:27], v[32:33] op_sel_hi:[0,1,1]
	v_add_f32_e32 v164, v164, v168
	v_mul_f32_e32 v168, v27, v71
	v_mul_f32_e32 v27, v27, v75
	v_pk_fma_f32 v[30:31], v[100:101], v[28:29], v[30:31] op_sel_hi:[0,1,1]
	v_fmac_f32_e32 v27, v26, v74
	v_pk_fma_f32 v[30:31], v[122:123], v[56:57], v[30:31] op_sel_hi:[0,1,1]
	v_pk_fma_f32 v[32:33], v[122:123], v[54:55], v[32:33] op_sel_hi:[0,1,1]
	v_fmac_f32_e32 v168, v26, v70
	v_fmac_f32_e32 v27, v28, v76
	v_fmac_f32_e32 v168, v28, v72
	v_pk_fma_f32 v[30:31], v[120:121], v[68:69], v[30:31] op_sel_hi:[0,1,1]
	v_pk_fma_f32 v[32:33], v[120:121], v[66:67], v[32:33] op_sel_hi:[0,1,1]
	v_fmac_f32_e32 v27, v29, v77
	v_fmac_f32_e32 v168, v29, v73
	v_add_f32_e32 v162, v162, v27
	v_pk_fma_f32 v[28:29], v[118:119], v[80:81], v[30:31] op_sel_hi:[0,1,1]
	v_pk_fma_f32 v[26:27], v[118:119], v[78:79], v[32:33] op_sel_hi:[0,1,1]
	global_store_dwordx4 v[140:141], v[26:29], off offset:640 nt
	s_waitcnt vmcnt(23)
	v_mul_f32_e32 v30, v23, v59
	v_fmac_f32_e32 v30, v22, v58
	v_mul_f32_e32 v26, v23, v51
	v_fmac_f32_e32 v26, v22, v50
	v_fmac_f32_e32 v26, v24, v52
	v_fmac_f32_e32 v30, v24, v60
	v_fmac_f32_e32 v26, v25, v53
	v_pk_mul_f32 v[28:29], v[116:117], v[62:63] op_sel_hi:[0,1]
	v_fmac_f32_e32 v30, v25, v61
	v_add_f32_e32 v153, v153, v26
	v_pk_mul_f32 v[26:27], v[116:117], v[64:65] op_sel_hi:[0,1]
	v_pk_fma_f32 v[28:29], v[100:101], v[22:23], v[28:29] op_sel_hi:[0,1,1]
	v_add_f32_e32 v152, v152, v30
	v_mul_f32_e32 v30, v23, v71
	v_mul_f32_e32 v23, v23, v75
	v_pk_fma_f32 v[26:27], v[100:101], v[24:25], v[26:27] op_sel_hi:[0,1,1]
	v_fmac_f32_e32 v23, v22, v74
	v_pk_fma_f32 v[26:27], v[114:115], v[56:57], v[26:27] op_sel_hi:[0,1,1]
	v_pk_fma_f32 v[28:29], v[114:115], v[54:55], v[28:29] op_sel_hi:[0,1,1]
	v_fmac_f32_e32 v30, v22, v70
	v_fmac_f32_e32 v23, v24, v76
	v_fmac_f32_e32 v30, v24, v72
	v_pk_fma_f32 v[26:27], v[112:113], v[68:69], v[26:27] op_sel_hi:[0,1,1]
	v_pk_fma_f32 v[28:29], v[112:113], v[66:67], v[28:29] op_sel_hi:[0,1,1]
	v_fmac_f32_e32 v23, v25, v77
	v_fmac_f32_e32 v30, v25, v73
	v_add_f32_e32 v150, v150, v23
	v_pk_fma_f32 v[24:25], v[110:111], v[80:81], v[26:27] op_sel_hi:[0,1,1]
	v_pk_fma_f32 v[22:23], v[110:111], v[78:79], v[28:29] op_sel_hi:[0,1,1]
	global_store_dwordx4 v[138:139], v[22:25], off offset:640 nt
	s_waitcnt vmcnt(23)
	v_mul_f32_e32 v26, v19, v59
	v_fmac_f32_e32 v26, v18, v58
	v_mul_f32_e32 v22, v19, v51
	v_fmac_f32_e32 v22, v18, v50
	v_fmac_f32_e32 v22, v20, v52
	v_fmac_f32_e32 v26, v20, v60
	v_fmac_f32_e32 v22, v21, v53
	v_pk_mul_f32 v[24:25], v[108:109], v[62:63] op_sel_hi:[0,1]
	v_fmac_f32_e32 v26, v21, v61
	v_add_f32_e32 v149, v149, v22
	v_pk_mul_f32 v[22:23], v[108:109], v[64:65] op_sel_hi:[0,1]
	v_pk_fma_f32 v[24:25], v[100:101], v[18:19], v[24:25] op_sel_hi:[0,1,1]
	v_add_f32_e32 v58, v148, v26
	v_mul_f32_e32 v26, v19, v71
	v_mul_f32_e32 v19, v19, v75
	v_pk_fma_f32 v[22:23], v[100:101], v[20:21], v[22:23] op_sel_hi:[0,1,1]
	v_fmac_f32_e32 v19, v18, v74
	v_pk_fma_f32 v[22:23], v[106:107], v[56:57], v[22:23] op_sel_hi:[0,1,1]
	v_pk_fma_f32 v[24:25], v[106:107], v[54:55], v[24:25] op_sel_hi:[0,1,1]
	v_fmac_f32_e32 v26, v18, v70
	v_fmac_f32_e32 v19, v20, v76
	v_fmac_f32_e32 v26, v20, v72
	v_pk_fma_f32 v[22:23], v[104:105], v[68:69], v[22:23] op_sel_hi:[0,1,1]
	v_pk_fma_f32 v[24:25], v[104:105], v[66:67], v[24:25] op_sel_hi:[0,1,1]
	v_fmac_f32_e32 v19, v21, v77
	v_fmac_f32_e32 v26, v21, v73
	v_add_f32_e32 v142, v142, v19
	v_pk_fma_f32 v[20:21], v[0:1], v[80:81], v[22:23] op_sel_hi:[0,1,1]
	v_pk_fma_f32 v[18:19], v[0:1], v[78:79], v[24:25] op_sel_hi:[0,1,1]
	global_store_dwordx4 v[136:137], v[18:21], off offset:640 nt
	v_add_f32_e32 v151, v151, v30
	v_add_f32_e32 v143, v143, v26
	ds_read_b128 v[18:21], v123 offset:768
	ds_read_b128 v[22:25], v123 offset:4864
	ds_read_b128 v[26:29], v123 offset:1792
	ds_read_b128 v[30:33], v123 offset:5888
	ds_read_b128 v[66:69], v123 offset:2816
	ds_read_b128 v[70:73], v123 offset:6912
	ds_read_b128 v[74:77], v123 offset:3840
	ds_read_b128 v[78:81], v123 offset:7936
	s_waitcnt vmcnt(15) lgkmcnt(7)
; #define LAS __attribute__((address_space(3)))
; __device__ __forceinline__ void mlstm_sample_unit(const Frame& F, int b, int h) {
;     ...
;     for (int hh = 0; hh < 4; ++hh) {
;         if (hh < 3) {
; #pragma unroll
;             for (int i2 = 0; i2 < 2; ++i2)
; #pragma unroll
;                 for (int rg = 0; rg < 4; ++rg) c[(hh + 1) & 1][i2][rg] = __builtin_nontemporal_load((const f32x4*)(c0b + rg * 2048 + ((hh + 1) * 2 + i2) * 32)); }
; #pragma unroll
;         for (int i2 = 0; i2 < 2; ++i2) { const int it = hh * 2 + i2; const int d = it * 32 + seg * 4;
;             f32x4 q[4], k[4];
; #pragma unroll
;             for (int t = 0; t < 4; ++t) { q[t] = *(const LAS f32x4*)(sq + t * 256 + d); k[t] = *(const LAS f32x4*)(sk + t * 256 + d); }
; #pragma unroll
;             for (int rg = 0; rg < 4; ++rg) { const f32x4 cv = c[hh & 1][i2][rg]; f32x4 nv = cv * decay;
; #pragma unroll
;                 for (int t = 0; t < 4; ++t) { acc[rg][t] += cv[0] * q[t][0] + cv[1] * q[t][1] + cv[2] * q[t][2] + cv[3] * q[t][3]; nv += k[t] * gv[rg][t]; }
;                 __builtin_nontemporal_store(nv, (f32x4*)(c1b + rg * 2048 + it * 32)); } }
;     }
	v_mul_f32_e32 v50, v47, v19
	s_waitcnt lgkmcnt(5)
	v_mul_f32_e32 v54, v47, v27
	v_fmac_f32_e32 v50, v46, v18
	v_fmac_f32_e32 v54, v46, v26
	v_fmac_f32_e32 v50, v48, v20
	v_fmac_f32_e32 v54, v48, v28
	v_fmac_f32_e32 v50, v49, v21
	v_pk_mul_f32 v[52:53], v[132:133], v[22:23] op_sel_hi:[0,1]
	v_fmac_f32_e32 v54, v49, v29
	v_add_f32_e32 v65, v174, v50
	v_pk_mul_f32 v[50:51], v[132:133], v[24:25] op_sel_hi:[0,1]
	v_pk_fma_f32 v[52:53], v[100:101], v[46:47], v[52:53] op_sel_hi:[0,1,1]
	v_add_f32_e32 v64, v175, v54
	s_waitcnt lgkmcnt(3)
	v_mul_f32_e32 v54, v47, v67
	s_waitcnt lgkmcnt(1)
	v_mul_f32_e32 v47, v47, v75
	v_pk_fma_f32 v[50:51], v[100:101], v[48:49], v[50:51] op_sel_hi:[0,1,1]
	v_fmac_f32_e32 v47, v46, v74
	v_pk_fma_f32 v[52:53], v[130:131], v[30:31], v[52:53] op_sel_hi:[0,1,1]
	v_pk_fma_f32 v[50:51], v[130:131], v[32:33], v[50:51] op_sel_hi:[0,1,1]
	v_fmac_f32_e32 v54, v46, v66
	v_fmac_f32_e32 v47, v48, v76
	v_fmac_f32_e32 v54, v48, v68
	v_pk_fma_f32 v[50:51], v[128:129], v[72:73], v[50:51] op_sel_hi:[0,1,1]
	v_pk_fma_f32 v[52:53], v[128:129], v[70:71], v[52:53] op_sel_hi:[0,1,1]
	v_fmac_f32_e32 v47, v49, v77
	v_fmac_f32_e32 v54, v49, v69
	v_add_f32_e32 v62, v166, v47
	s_waitcnt lgkmcnt(0)
	v_pk_fma_f32 v[46:47], v[126:127], v[78:79], v[52:53] op_sel_hi:[0,1,1]
	v_pk_fma_f32 v[48:49], v[126:127], v[80:81], v[50:51] op_sel_hi:[0,1,1]
	global_store_dwordx4 v[134:135], v[46:49], off offset:768 nt
	s_waitcnt vmcnt(15)
	v_mul_f32_e32 v50, v43, v27
	v_fmac_f32_e32 v50, v42, v26
	v_mul_f32_e32 v46, v43, v19
	v_fmac_f32_e32 v46, v42, v18
	v_fmac_f32_e32 v46, v44, v20
	v_fmac_f32_e32 v50, v44, v28
	v_fmac_f32_e32 v46, v45, v21
	v_pk_mul_f32 v[48:49], v[124:125], v[22:23] op_sel_hi:[0,1]
	v_fmac_f32_e32 v50, v45, v29
	v_add_f32_e32 v61, v165, v46
	v_pk_mul_f32 v[46:47], v[124:125], v[24:25] op_sel_hi:[0,1]
	v_pk_fma_f32 v[48:49], v[100:101], v[42:43], v[48:49] op_sel_hi:[0,1,1]
	v_add_f32_e32 v60, v164, v50
	v_mul_f32_e32 v50, v43, v67
	v_mul_f32_e32 v43, v43, v75
	v_pk_fma_f32 v[46:47], v[100:101], v[44:45], v[46:47] op_sel_hi:[0,1,1]
	v_fmac_f32_e32 v43, v42, v74
	v_pk_fma_f32 v[46:47], v[122:123], v[32:33], v[46:47] op_sel_hi:[0,1,1]
	v_pk_fma_f32 v[48:49], v[122:123], v[30:31], v[48:49] op_sel_hi:[0,1,1]
	v_fmac_f32_e32 v50, v42, v66
	v_fmac_f32_e32 v43, v44, v76
	v_fmac_f32_e32 v50, v44, v68
	v_pk_fma_f32 v[46:47], v[120:121], v[72:73], v[46:47] op_sel_hi:[0,1,1]
	v_pk_fma_f32 v[48:49], v[120:121], v[70:71], v[48:49] op_sel_hi:[0,1,1]
	v_fmac_f32_e32 v43, v45, v77
	v_fmac_f32_e32 v50, v45, v69
	v_add_f32_e32 v57, v162, v43
	v_pk_fma_f32 v[44:45], v[118:119], v[80:81], v[46:47] op_sel_hi:[0,1,1]
	v_pk_fma_f32 v[42:43], v[118:119], v[78:79], v[48:49] op_sel_hi:[0,1,1]
	global_store_dwordx4 v[140:141], v[42:45], off offset:768 nt
	s_waitcnt vmcnt(15)
	v_mul_f32_e32 v46, v39, v27
	v_fmac_f32_e32 v46, v38, v26
	v_mul_f32_e32 v42, v39, v19
	s_waitcnt vmcnt(14)
	v_mul_f32_e32 v19, v35, v19
	v_fmac_f32_e32 v42, v38, v18
	v_fmac_f32_e32 v19, v34, v18
	v_fmac_f32_e32 v42, v40, v20
	v_fmac_f32_e32 v19, v36, v20
	v_fmac_f32_e32 v42, v41, v21
	v_pk_mul_f32 v[44:45], v[116:117], v[22:23] op_sel_hi:[0,1]
	v_fmac_f32_e32 v19, v37, v21
	v_pk_mul_f32 v[20:21], v[108:109], v[22:23] op_sel_hi:[0,1]
	v_mul_f32_e32 v22, v35, v27
	v_fmac_f32_e32 v22, v34, v26
	v_fmac_f32_e32 v22, v36, v28
	v_fmac_f32_e32 v22, v37, v29
	v_add_f32_e32 v51, v58, v22
	v_mul_f32_e32 v22, v35, v67
	v_fmac_f32_e32 v22, v34, v66
	v_fmac_f32_e32 v46, v40, v28
	v_pk_fma_f32 v[20:21], v[100:101], v[34:35], v[20:21] op_sel_hi:[0,1,1]
	v_fmac_f32_e32 v22, v36, v68
	v_add_f32_e32 v163, v163, v168
	v_fmac_f32_e32 v46, v41, v29
	v_pk_fma_f32 v[20:21], v[106:107], v[30:31], v[20:21] op_sel_hi:[0,1,1]
	v_fmac_f32_e32 v22, v37, v69
	v_add_f32_e32 v59, v163, v50
	v_add_f32_e32 v56, v153, v42
	v_pk_mul_f32 v[42:43], v[116:117], v[24:25] op_sel_hi:[0,1]
	v_pk_fma_f32 v[44:45], v[100:101], v[38:39], v[44:45] op_sel_hi:[0,1,1]
	v_add_f32_e32 v55, v152, v46
	v_mul_f32_e32 v46, v39, v67
	v_mul_f32_e32 v39, v39, v75
	v_add_f32_e32 v52, v149, v19
	v_pk_mul_f32 v[18:19], v[108:109], v[24:25] op_sel_hi:[0,1]
	v_add_f32_e32 v50, v143, v22
	v_pk_fma_f32 v[22:23], v[104:105], v[70:71], v[20:21] op_sel_hi:[0,1,1]
	v_mul_f32_e32 v20, v35, v75
	v_pk_fma_f32 v[42:43], v[100:101], v[40:41], v[42:43] op_sel_hi:[0,1,1]
	v_fmac_f32_e32 v39, v38, v74
	v_pk_fma_f32 v[18:19], v[100:101], v[36:37], v[18:19] op_sel_hi:[0,1,1]
	v_fmac_f32_e32 v20, v34, v74
	v_pk_fma_f32 v[42:43], v[114:115], v[32:33], v[42:43] op_sel_hi:[0,1,1]
	v_pk_fma_f32 v[44:45], v[114:115], v[30:31], v[44:45] op_sel_hi:[0,1,1]
	v_fmac_f32_e32 v46, v38, v66
	v_fmac_f32_e32 v39, v40, v76
	v_pk_fma_f32 v[18:19], v[106:107], v[32:33], v[18:19] op_sel_hi:[0,1,1]
	v_fmac_f32_e32 v20, v36, v76
	v_fmac_f32_e32 v46, v40, v68
	v_pk_fma_f32 v[42:43], v[112:113], v[72:73], v[42:43] op_sel_hi:[0,1,1]
	v_pk_fma_f32 v[44:45], v[112:113], v[70:71], v[44:45] op_sel_hi:[0,1,1]
	v_fmac_f32_e32 v39, v41, v77
	v_pk_fma_f32 v[18:19], v[104:105], v[72:73], v[18:19] op_sel_hi:[0,1,1]
	v_fmac_f32_e32 v20, v37, v77
	v_fmac_f32_e32 v46, v41, v69
	v_add_f32_e32 v53, v150, v39
	v_pk_fma_f32 v[40:41], v[110:111], v[80:81], v[42:43] op_sel_hi:[0,1,1]
	v_pk_fma_f32 v[38:39], v[110:111], v[78:79], v[44:45] op_sel_hi:[0,1,1]
	v_add_f32_e32 v58, v142, v20
	v_pk_fma_f32 v[20:21], v[0:1], v[80:81], v[18:19] op_sel_hi:[0,1,1]
	v_pk_fma_f32 v[18:19], v[0:1], v[78:79], v[22:23] op_sel_hi:[0,1,1]
	v_add_f32_e32 v167, v167, v172
	global_store_dwordx4 v[138:139], v[38:41], off offset:768 nt
	global_store_dwordx4 v[136:137], v[18:21], off offset:768 nt
	v_add_f32_e32 v63, v167, v54
	v_add_f32_e32 v54, v151, v46
	ds_read_b128 v[18:21], v123 offset:896
	ds_read_b128 v[22:25], v123 offset:4992
	ds_read_b128 v[30:33], v123 offset:1920
	ds_read_b128 v[26:29], v123 offset:6016
	ds_read_b128 v[38:41], v123 offset:2944
	ds_read_b128 v[34:37], v123 offset:7040
	ds_read_b128 v[42:45], v123 offset:3968
	ds_read_b128 v[46:49], v123 offset:8064
	s_waitcnt vmcnt(15) lgkmcnt(7)
; __device__ __forceinline__ float bf2f(bf16_t h) { return __uint_as_float((unsigned)h << 16); }
; __device__ __forceinline__ float sigmoidf_(float x) { return 1.f / (1.f + __expf(-x)); }
; __device__ __forceinline__ void mlstm_sample_unit(const Frame& F, int b, int h) {
;     ...
;             for (int rg = 0; rg < 4; ++rg) { const f32x4 cv = c[hh & 1][i2][rg]; f32x4 nv = cv * decay;
; #pragma unroll
;                 for (int t = 0; t < 4; ++t) { acc[rg][t] += cv[0] * q[t][0] + cv[1] * q[t][1] + cv[2] * q[t][2] + cv[3] * q[t][3]; nv += k[t] * gv[rg][t]; }
;                 __builtin_nontemporal_store(nv, (f32x4*)(c1b + rg * 2048 + it * 32)); } }
;     }
;     __syncthreads();
;     float hv[4][4], ssq[4] = {0.f, 0.f, 0.f, 0.f};
; #pragma unroll
;     for (int rg = 0; rg < 4; ++rg)
; #pragma unroll
;         for (int t = 0; t < 4; ++t) { float a = acc[rg][t]; a += __shfl_xor(a, 1); a += __shfl_xor(a, 2); a += __shfl_xor(a, 4);
;     ...
;             const float rms = rsqrtf(sS[32 + t] * (1.f / 256.f) + EPS); const float og = sigmoidf_(bf2f(P[row * NIN + C_MO + h * 256 + vr]));
	v_mul_f32_e32 v66, v15, v19
	v_fmac_f32_e32 v66, v14, v18
	v_fmac_f32_e32 v66, v16, v20
	v_fmac_f32_e32 v66, v17, v21
	v_add_f32_e32 v70, v65, v66
	s_waitcnt lgkmcnt(5)
	v_mul_f32_e32 v65, v15, v31
	v_fmac_f32_e32 v65, v14, v30
	v_pk_mul_f32 v[68:69], v[132:133], v[22:23] op_sel_hi:[0,1]
	v_fmac_f32_e32 v65, v16, v32
	v_pk_fma_f32 v[68:69], v[100:101], v[14:15], v[68:69] op_sel_hi:[0,1,1]
	v_fmac_f32_e32 v65, v17, v33
	v_pk_mul_f32 v[66:67], v[132:133], v[24:25] op_sel_hi:[0,1]
	v_add_f32_e32 v71, v64, v65
	s_waitcnt lgkmcnt(4)
	v_pk_fma_f32 v[64:65], v[130:131], v[26:27], v[68:69] op_sel_hi:[0,1,1]
	s_waitcnt lgkmcnt(3)
	v_mul_f32_e32 v68, v15, v39
	s_waitcnt lgkmcnt(1)
	v_mul_f32_e32 v15, v15, v43
	v_pk_fma_f32 v[66:67], v[100:101], v[16:17], v[66:67] op_sel_hi:[0,1,1]
	v_fmac_f32_e32 v15, v14, v42
	v_pk_fma_f32 v[66:67], v[130:131], v[28:29], v[66:67] op_sel_hi:[0,1,1]
	v_fmac_f32_e32 v68, v14, v38
	v_fmac_f32_e32 v15, v16, v44
	v_fmac_f32_e32 v68, v16, v40
	v_pk_fma_f32 v[66:67], v[128:129], v[36:37], v[66:67] op_sel_hi:[0,1,1]
	v_pk_fma_f32 v[64:65], v[128:129], v[34:35], v[64:65] op_sel_hi:[0,1,1]
	v_fmac_f32_e32 v15, v17, v45
	v_fmac_f32_e32 v68, v17, v41
	v_add_f32_e32 v62, v62, v15
	s_waitcnt lgkmcnt(0)
	v_pk_fma_f32 v[14:15], v[126:127], v[46:47], v[64:65] op_sel_hi:[0,1,1]
	v_pk_fma_f32 v[16:17], v[126:127], v[48:49], v[66:67] op_sel_hi:[0,1,1]
	global_store_dwordx4 v[134:135], v[14:17], off offset:896 nt
	s_waitcnt vmcnt(15)
	v_mul_f32_e32 v64, v11, v31
	v_fmac_f32_e32 v64, v10, v30
	v_mul_f32_e32 v14, v11, v19
	v_fmac_f32_e32 v14, v10, v18
	v_fmac_f32_e32 v14, v12, v20
	v_fmac_f32_e32 v64, v12, v32
	v_fmac_f32_e32 v14, v13, v21
	v_pk_mul_f32 v[16:17], v[124:125], v[22:23] op_sel_hi:[0,1]
	v_fmac_f32_e32 v64, v13, v33
	v_add_f32_e32 v61, v61, v14
	v_pk_mul_f32 v[14:15], v[124:125], v[24:25] op_sel_hi:[0,1]
	v_pk_fma_f32 v[16:17], v[100:101], v[10:11], v[16:17] op_sel_hi:[0,1,1]
	v_add_f32_e32 v60, v60, v64
	v_mul_f32_e32 v64, v11, v39
	v_mul_f32_e32 v11, v11, v43
	v_pk_fma_f32 v[14:15], v[100:101], v[12:13], v[14:15] op_sel_hi:[0,1,1]
	v_fmac_f32_e32 v11, v10, v42
	v_pk_fma_f32 v[14:15], v[122:123], v[28:29], v[14:15] op_sel_hi:[0,1,1]
	v_pk_fma_f32 v[16:17], v[122:123], v[26:27], v[16:17] op_sel_hi:[0,1,1]
	v_fmac_f32_e32 v64, v10, v38
	v_fmac_f32_e32 v11, v12, v44
	v_fmac_f32_e32 v64, v12, v40
	v_pk_fma_f32 v[14:15], v[120:121], v[36:37], v[14:15] op_sel_hi:[0,1,1]
	v_pk_fma_f32 v[16:17], v[120:121], v[34:35], v[16:17] op_sel_hi:[0,1,1]
	v_fmac_f32_e32 v11, v13, v45
	v_fmac_f32_e32 v64, v13, v41
	v_add_f32_e32 v57, v57, v11
	v_pk_fma_f32 v[12:13], v[118:119], v[48:49], v[14:15] op_sel_hi:[0,1,1]
	v_pk_fma_f32 v[10:11], v[118:119], v[46:47], v[16:17] op_sel_hi:[0,1,1]
	global_store_dwordx4 v[140:141], v[10:13], off offset:896 nt
	s_waitcnt vmcnt(15)
	v_mul_f32_e32 v14, v7, v31
	v_fmac_f32_e32 v14, v6, v30
	v_mul_f32_e32 v10, v7, v19
	v_fmac_f32_e32 v10, v6, v18
	v_fmac_f32_e32 v10, v8, v20
	v_fmac_f32_e32 v14, v8, v32
	v_fmac_f32_e32 v10, v9, v21
	v_pk_mul_f32 v[12:13], v[116:117], v[22:23] op_sel_hi:[0,1]
	v_fmac_f32_e32 v14, v9, v33
	v_add_f32_e32 v56, v56, v10
	v_pk_mul_f32 v[10:11], v[116:117], v[24:25] op_sel_hi:[0,1]
	v_pk_fma_f32 v[12:13], v[100:101], v[6:7], v[12:13] op_sel_hi:[0,1,1]
	v_add_f32_e32 v55, v55, v14
	v_mul_f32_e32 v14, v7, v39
	v_mul_f32_e32 v7, v7, v43
	v_pk_fma_f32 v[10:11], v[100:101], v[8:9], v[10:11] op_sel_hi:[0,1,1]
	v_fmac_f32_e32 v7, v6, v42
	v_pk_fma_f32 v[10:11], v[114:115], v[28:29], v[10:11] op_sel_hi:[0,1,1]
	v_pk_fma_f32 v[12:13], v[114:115], v[26:27], v[12:13] op_sel_hi:[0,1,1]
	v_fmac_f32_e32 v14, v6, v38
	v_fmac_f32_e32 v7, v8, v44
	v_fmac_f32_e32 v14, v8, v40
	v_pk_fma_f32 v[10:11], v[112:113], v[36:37], v[10:11] op_sel_hi:[0,1,1]
	v_pk_fma_f32 v[12:13], v[112:113], v[34:35], v[12:13] op_sel_hi:[0,1,1]
	v_fmac_f32_e32 v7, v9, v45
	v_fmac_f32_e32 v14, v9, v41
	v_add_f32_e32 v53, v53, v7
	v_pk_fma_f32 v[8:9], v[110:111], v[48:49], v[10:11] op_sel_hi:[0,1,1]
	v_pk_fma_f32 v[6:7], v[110:111], v[46:47], v[12:13] op_sel_hi:[0,1,1]
	global_store_dwordx4 v[138:139], v[6:9], off offset:896 nt
	s_waitcnt vmcnt(15)
	v_mul_f32_e32 v10, v3, v31
	v_fmac_f32_e32 v10, v2, v30
	v_mul_f32_e32 v6, v3, v19
	v_fmac_f32_e32 v6, v2, v18
	v_fmac_f32_e32 v6, v4, v20
	v_fmac_f32_e32 v10, v4, v32
	v_fmac_f32_e32 v6, v5, v21
	v_pk_mul_f32 v[8:9], v[108:109], v[22:23] op_sel_hi:[0,1]
	v_fmac_f32_e32 v10, v5, v33
	v_add_f32_e32 v52, v52, v6
	v_pk_mul_f32 v[6:7], v[108:109], v[24:25] op_sel_hi:[0,1]
	v_pk_fma_f32 v[8:9], v[100:101], v[2:3], v[8:9] op_sel_hi:[0,1,1]
	v_add_f32_e32 v51, v51, v10
	v_mul_f32_e32 v10, v3, v39
	v_mul_f32_e32 v3, v3, v43
	v_pk_fma_f32 v[6:7], v[100:101], v[4:5], v[6:7] op_sel_hi:[0,1,1]
	v_fmac_f32_e32 v3, v2, v42
	v_pk_fma_f32 v[6:7], v[106:107], v[28:29], v[6:7] op_sel_hi:[0,1,1]
	v_pk_fma_f32 v[8:9], v[106:107], v[26:27], v[8:9] op_sel_hi:[0,1,1]
	v_fmac_f32_e32 v10, v2, v38
	v_fmac_f32_e32 v3, v4, v44
	v_fmac_f32_e32 v10, v4, v40
	v_pk_fma_f32 v[6:7], v[104:105], v[36:37], v[6:7] op_sel_hi:[0,1,1]
	v_pk_fma_f32 v[8:9], v[104:105], v[34:35], v[8:9] op_sel_hi:[0,1,1]
	v_fmac_f32_e32 v3, v5, v45
	v_fmac_f32_e32 v10, v5, v41
	v_add_f32_e32 v45, v58, v3
	v_pk_fma_f32 v[4:5], v[0:1], v[48:49], v[6:7] op_sel_hi:[0,1,1]
	v_pk_fma_f32 v[2:3], v[0:1], v[46:47], v[8:9] op_sel_hi:[0,1,1]
	ds_bpermute_b32 v0, v109, v70
	global_store_dwordx4 v[136:137], v[2:5], off offset:896 nt
	v_add_f32_e32 v54, v54, v14
	v_add_f32_e32 v50, v50, v10
	s_waitcnt lgkmcnt(0)
	v_add_f32_e32 v0, v70, v0
	ds_bpermute_b32 v2, v107, v0
	s_mul_hi_i32 s28, s62, 0x2c00
	s_mul_i32 s29, s62, 0x2c00
	s_add_u32 s46, s44, s29
	s_addc_u32 s47, s45, s28
	s_lshl_b32 s29, s0, 1
	s_add_u32 s46, s46, s29
	s_addc_u32 s47, s47, 0
	v_readlane_b32 s42, v245, 25
	v_readlane_b32 s43, v245, 26
	v_and_b32_e32 v207, 3, v144
	v_bfe_u32 v208, v144, 2, 1
	v_mul_u32_u24_e32 v209, 0x2c00, v207
	v_lshl_add_u32 v209, v208, 4, v209
	v_lshlrev_b32_e32 v210, 1, v84
	v_add3_u32 v212, v210, v209, s97
	v_mov_b32_e32 v213, 0
	v_lshl_add_u64 v[212:213], s[46:47], 0, v[212:213]
	global_load_ushort v203, v[212:213], off offset:1024
	global_load_ushort v204, v[212:213], off offset:1056
	v_add_u32_e32 v210, s0, v84
	v_mov_b32_e32 v211, 0
	v_lshl_add_u64 v[210:211], v[210:211], 2, s[42:43]
	v_lshlrev_b32_e32 v214, 5, v208
	v_mov_b32_e32 v215, 0
	v_lshl_add_u64 v[210:211], v[210:211], 0, v[214:215]
	global_load_dword v205, v[210:211], off
	global_load_dword v206, v[210:211], off offset:64
	s_barrier
; __device__ __forceinline__ void mlstm_sample_unit(const Frame& F, int b, int h) {
;     ...
;         for (int t = 0; t < 4; ++t) { float a = acc[rg][t]; a += __shfl_xor(a, 1); a += __shfl_xor(a, 2); a += __shfl_xor(a, 4);
;             float num = sS[40 + t] * a;
; #pragma unroll
;             for (int s2 = 0; s2 < 4; ++s2) num += sS[48 + t * 4 + s2] * sv[s2 * 256 + w * 32 + rg * 8 + r8];
;             hv[rg][t] = num / sS[44 + t]; if (seg == 0) ssq[t] += hv[rg][t] * hv[rg][t]; }
	s_waitcnt lgkmcnt(0)
	v_add_f32_e32 v63, v63, v68
	v_add_f32_e32 v59, v59, v64
	v_add_f32_e32 v0, v0, v2
	ds_bpermute_b32 v2, v105, v0
	s_waitcnt lgkmcnt(0)
	v_add_f32_e32 v0, v0, v2
	ds_read_b128 v[6:9], v1 offset:12448
	ds_read_b128 v[2:5], v1 offset:12464
	ds_read_b128 v[14:17], v1 offset:12480
	ds_read_b128 v[10:13], v1 offset:12496
	ds_read2_b32 v[26:27], v161 offset1:8
	ds_read2_b32 v[28:29], v159 offset1:8
	ds_read2_b32 v[30:31], v158 offset1:8
	ds_read2_b32 v[32:33], v95 offset1:8
	s_waitcnt lgkmcnt(3)
	v_mul_f32_e32 v18, v14, v26
	v_fmac_f32_e32 v18, v6, v0
	s_waitcnt lgkmcnt(2)
	v_fmac_f32_e32 v18, v15, v28
	s_waitcnt lgkmcnt(1)
	v_fmac_f32_e32 v18, v16, v30
	s_waitcnt lgkmcnt(0)
	v_fmac_f32_e32 v18, v17, v32
	v_div_scale_f32 v0, s[28:29], v2, v2, v18
	v_rcp_f32_e32 v19, v0
	s_nop 0
	v_fma_f32 v20, -v0, v19, 1.0
	v_fmac_f32_e32 v19, v20, v19
	v_div_scale_f32 v20, vcc, v18, v2, v18
	v_mul_f32_e32 v21, v20, v19
	v_fma_f32 v22, -v0, v21, v20
	v_fmac_f32_e32 v21, v22, v19
	v_fma_f32 v0, -v0, v21, v20
	v_div_fmas_f32 v0, v0, v19, v21
	v_div_fixup_f32 v39, v0, v2, v18
	ds_bpermute_b32 v0, v109, v71
	s_waitcnt lgkmcnt(0)
	v_add_f32_e32 v0, v71, v0
	ds_bpermute_b32 v18, v107, v0
	s_waitcnt lgkmcnt(0)
	v_add_f32_e32 v0, v0, v18
	ds_bpermute_b32 v18, v105, v0
	s_waitcnt lgkmcnt(0)
	v_add_f32_e32 v0, v0, v18
	v_mul_f32_e32 v18, v26, v10
	v_fmac_f32_e32 v18, v7, v0
	v_fmac_f32_e32 v18, v28, v11
	v_fmac_f32_e32 v18, v30, v12
	v_fmac_f32_e32 v18, v32, v13
	v_div_scale_f32 v0, s[28:29], v3, v3, v18
	v_rcp_f32_e32 v19, v0
	s_nop 0
	v_fma_f32 v20, -v0, v19, 1.0
	v_fmac_f32_e32 v19, v20, v19
	v_div_scale_f32 v20, vcc, v18, v3, v18
	v_mul_f32_e32 v21, v20, v19
	v_fma_f32 v22, -v0, v21, v20
	v_fmac_f32_e32 v21, v22, v19
	v_fma_f32 v0, -v0, v21, v20
	v_div_fmas_f32 v0, v0, v19, v21
	v_div_fixup_f32 v40, v0, v3, v18
	ds_bpermute_b32 v0, v109, v63
	s_waitcnt lgkmcnt(0)
	v_add_f32_e32 v0, v63, v0
	ds_bpermute_b32 v18, v107, v0
	s_waitcnt lgkmcnt(0)
	v_add_f32_e32 v0, v0, v18
	ds_bpermute_b32 v18, v105, v0
	s_waitcnt lgkmcnt(0)
	v_add_f32_e32 v0, v0, v18
	ds_read_b128 v[18:21], v1 offset:12512
	s_waitcnt lgkmcnt(0)
	v_mul_f32_e32 v22, v26, v18
	v_fmac_f32_e32 v22, v8, v0
	v_fmac_f32_e32 v22, v28, v19
	v_fmac_f32_e32 v22, v30, v20
	v_fmac_f32_e32 v22, v32, v21
	v_div_scale_f32 v0, s[28:29], v4, v4, v22
	v_rcp_f32_e32 v23, v0
	s_nop 0
	v_fma_f32 v24, -v0, v23, 1.0
	v_fmac_f32_e32 v23, v24, v23
	v_div_scale_f32 v24, vcc, v22, v4, v22
	v_mul_f32_e32 v25, v24, v23
	v_fma_f32 v34, -v0, v25, v24
	v_fmac_f32_e32 v25, v34, v23
	v_fma_f32 v0, -v0, v25, v24
	v_div_fmas_f32 v0, v0, v23, v25
	v_div_fixup_f32 v42, v0, v4, v22
	ds_bpermute_b32 v0, v109, v62
	s_waitcnt lgkmcnt(0)
	v_add_f32_e32 v0, v62, v0
	ds_bpermute_b32 v22, v107, v0
	s_waitcnt lgkmcnt(0)
	v_add_f32_e32 v0, v0, v22
	ds_bpermute_b32 v22, v105, v0
	s_waitcnt lgkmcnt(0)
	v_add_f32_e32 v0, v0, v22
	ds_read_b128 v[22:25], v1 offset:12528
	s_waitcnt lgkmcnt(0)
	v_mul_f32_e32 v26, v26, v22
	v_fmac_f32_e32 v26, v9, v0
	v_fmac_f32_e32 v26, v28, v23
	v_fmac_f32_e32 v26, v30, v24
	v_fmac_f32_e32 v26, v32, v25
	v_div_scale_f32 v0, s[28:29], v5, v5, v26
	v_rcp_f32_e32 v28, v0
	s_nop 0
	v_fma_f32 v30, -v0, v28, 1.0
	v_fmac_f32_e32 v28, v30, v28
	v_div_scale_f32 v30, vcc, v26, v5, v26
	v_mul_f32_e32 v32, v30, v28
	v_fma_f32 v34, -v0, v32, v30
	v_fmac_f32_e32 v32, v34, v28
	v_fma_f32 v0, -v0, v32, v30
	v_div_fmas_f32 v0, v0, v28, v32
	v_div_fixup_f32 v43, v0, v5, v26
	ds_bpermute_b32 v0, v109, v61
	s_waitcnt lgkmcnt(0)
	v_add_f32_e32 v0, v61, v0
	ds_bpermute_b32 v26, v107, v0
	s_waitcnt lgkmcnt(0)
	v_add_f32_e32 v0, v0, v26
	ds_bpermute_b32 v26, v105, v0
	s_waitcnt lgkmcnt(0)
	v_add_f32_e32 v0, v0, v26
	v_mul_f32_e32 v0, v6, v0
	v_fmac_f32_e32 v0, v14, v27
	v_fmac_f32_e32 v0, v15, v29
	v_fmac_f32_e32 v0, v16, v31
	v_fmac_f32_e32 v0, v17, v33
	v_div_scale_f32 v26, s[28:29], v2, v2, v0
	v_rcp_f32_e32 v28, v26
	s_nop 0
	v_fma_f32 v30, -v26, v28, 1.0
	v_fmac_f32_e32 v28, v30, v28
	v_div_scale_f32 v30, vcc, v0, v2, v0
	v_mul_f32_e32 v32, v30, v28
	v_fma_f32 v34, -v26, v32, v30
	v_fmac_f32_e32 v32, v34, v28
	v_fma_f32 v26, -v26, v32, v30
	v_div_fmas_f32 v26, v26, v28, v32
	v_div_fixup_f32 v44, v26, v2, v0
	ds_bpermute_b32 v26, v109, v60
	v_mul_f32_e32 v0, v44, v44
	v_fmac_f32_e32 v0, v39, v39
	s_waitcnt lgkmcnt(0)
	v_add_f32_e32 v26, v60, v26
	ds_bpermute_b32 v28, v107, v26
	s_waitcnt lgkmcnt(0)
	v_add_f32_e32 v26, v26, v28
	ds_bpermute_b32 v28, v105, v26
	s_waitcnt lgkmcnt(0)
	v_add_f32_e32 v26, v26, v28
	v_mul_f32_e32 v26, v7, v26
	v_fmac_f32_e32 v26, v10, v27
	v_fmac_f32_e32 v26, v11, v29
	v_fmac_f32_e32 v26, v12, v31
	v_fmac_f32_e32 v26, v13, v33
	v_div_scale_f32 v28, s[28:29], v3, v3, v26
	v_rcp_f32_e32 v30, v28
	s_nop 0
	v_fma_f32 v32, -v28, v30, 1.0
	v_fmac_f32_e32 v30, v32, v30
	v_div_scale_f32 v32, vcc, v26, v3, v26
	v_mul_f32_e32 v34, v32, v30
	v_fma_f32 v35, -v28, v34, v32
	v_fmac_f32_e32 v34, v35, v30
	v_fma_f32 v28, -v28, v34, v32
	v_div_fmas_f32 v28, v28, v30, v34
	v_div_fixup_f32 v41, v28, v3, v26
	ds_bpermute_b32 v26, v109, v59
	v_mul_f32_e32 v46, v41, v41
	v_fmac_f32_e32 v46, v40, v40
	s_waitcnt lgkmcnt(0)
	v_add_f32_e32 v26, v59, v26
	ds_bpermute_b32 v28, v107, v26
	s_waitcnt lgkmcnt(0)
	v_add_f32_e32 v26, v26, v28
	ds_bpermute_b32 v28, v105, v26
	s_waitcnt lgkmcnt(0)
	v_add_f32_e32 v26, v26, v28
	v_mul_f32_e32 v26, v8, v26
	v_fmac_f32_e32 v26, v18, v27
	v_fmac_f32_e32 v26, v19, v29
	v_fmac_f32_e32 v26, v20, v31
	v_fmac_f32_e32 v26, v21, v33
	v_div_scale_f32 v28, s[28:29], v4, v4, v26
	v_rcp_f32_e32 v30, v28
	s_nop 0
	v_fma_f32 v32, -v28, v30, 1.0
	v_fmac_f32_e32 v30, v32, v30
	v_div_scale_f32 v32, vcc, v26, v4, v26
	v_mul_f32_e32 v34, v32, v30
	v_fma_f32 v35, -v28, v34, v32
	v_fmac_f32_e32 v34, v35, v30
	v_fma_f32 v28, -v28, v34, v32
	v_div_fmas_f32 v28, v28, v30, v34
	v_div_fixup_f32 v38, v28, v4, v26
	ds_bpermute_b32 v26, v109, v57
	v_mul_f32_e32 v47, v38, v38
	v_fmac_f32_e32 v47, v42, v42
	s_waitcnt lgkmcnt(0)
; __device__ __forceinline__ void mlstm_sample_unit(const Frame& F, int b, int h) {
;     ...
;         for (int t = 0; t < 4; ++t) { float a = acc[rg][t]; a += __shfl_xor(a, 1); a += __shfl_xor(a, 2); a += __shfl_xor(a, 4);
;             float num = sS[40 + t] * a;
; #pragma unroll
;             for (int s2 = 0; s2 < 4; ++s2) num += sS[48 + t * 4 + s2] * sv[s2 * 256 + w * 32 + rg * 8 + r8];
;             hv[rg][t] = num / sS[44 + t]; if (seg == 0) ssq[t] += hv[rg][t] * hv[rg][t]; }
	v_add_f32_e32 v26, v57, v26
	ds_bpermute_b32 v28, v107, v26
	s_waitcnt lgkmcnt(0)
	v_add_f32_e32 v26, v26, v28
	ds_bpermute_b32 v28, v105, v26
	s_waitcnt lgkmcnt(0)
	v_add_f32_e32 v26, v26, v28
	v_mul_f32_e32 v26, v9, v26
	v_fmac_f32_e32 v26, v22, v27
	v_fmac_f32_e32 v26, v23, v29
	v_fmac_f32_e32 v26, v24, v31
	v_fmac_f32_e32 v26, v25, v33
	v_div_scale_f32 v27, s[28:29], v5, v5, v26
	v_rcp_f32_e32 v28, v27
	ds_read2_b32 v[32:33], v95 offset0:16 offset1:24
	v_fma_f32 v29, -v27, v28, 1.0
	v_fmac_f32_e32 v28, v29, v28
	v_div_scale_f32 v29, vcc, v26, v5, v26
	v_mul_f32_e32 v30, v29, v28
	v_fma_f32 v31, -v27, v30, v29
	v_fmac_f32_e32 v30, v31, v28
	v_fma_f32 v27, -v27, v30, v29
	v_div_fmas_f32 v27, v27, v28, v30
	v_div_fixup_f32 v37, v27, v5, v26
	ds_bpermute_b32 v26, v109, v56
	ds_read2_b32 v[28:29], v159 offset0:16 offset1:24
	ds_read2_b32 v[30:31], v158 offset0:16 offset1:24
	v_mul_f32_e32 v48, v37, v37
	v_fmac_f32_e32 v48, v43, v43
	s_waitcnt lgkmcnt(2)
	v_add_f32_e32 v26, v56, v26
	ds_bpermute_b32 v27, v107, v26
	s_waitcnt lgkmcnt(0)
	v_add_f32_e32 v26, v26, v27
	ds_bpermute_b32 v27, v105, v26
	s_waitcnt lgkmcnt(0)
	v_add_f32_e32 v26, v26, v27
	v_mul_f32_e32 v34, v6, v26
	ds_read2_b32 v[26:27], v161 offset0:16 offset1:24
	s_waitcnt lgkmcnt(0)
	v_fmac_f32_e32 v34, v14, v26
	v_fmac_f32_e32 v34, v15, v28
	v_fmac_f32_e32 v34, v16, v30
	v_fmac_f32_e32 v34, v17, v32
	v_div_scale_f32 v35, s[28:29], v2, v2, v34
	v_rcp_f32_e32 v36, v35
	s_nop 0
	v_fma_f32 v49, -v35, v36, 1.0
	v_fmac_f32_e32 v36, v49, v36
	v_div_scale_f32 v49, vcc, v34, v2, v34
	v_mul_f32_e32 v56, v49, v36
	v_fma_f32 v57, -v35, v56, v49
	v_fmac_f32_e32 v56, v57, v36
	v_fma_f32 v35, -v35, v56, v49
	v_div_fmas_f32 v35, v35, v36, v56
	v_div_fixup_f32 v36, v35, v2, v34
	ds_bpermute_b32 v34, v109, v55
	v_fmac_f32_e32 v0, v36, v36
	s_waitcnt lgkmcnt(0)
	v_add_f32_e32 v34, v55, v34
	ds_bpermute_b32 v35, v107, v34
	s_waitcnt lgkmcnt(0)
	v_add_f32_e32 v34, v34, v35
	ds_bpermute_b32 v35, v105, v34
	s_waitcnt lgkmcnt(0)
	v_add_f32_e32 v34, v34, v35
	v_mul_f32_e32 v34, v7, v34
	v_fmac_f32_e32 v34, v10, v26
	v_fmac_f32_e32 v34, v11, v28
	v_fmac_f32_e32 v34, v12, v30
	v_fmac_f32_e32 v34, v13, v32
	v_div_scale_f32 v35, s[28:29], v3, v3, v34
	v_rcp_f32_e32 v49, v35
	s_nop 0
	v_fma_f32 v55, -v35, v49, 1.0
	v_fmac_f32_e32 v49, v55, v49
	v_div_scale_f32 v55, vcc, v34, v3, v34
	v_mul_f32_e32 v56, v55, v49
	v_fma_f32 v57, -v35, v56, v55
	v_fmac_f32_e32 v56, v57, v49
	v_fma_f32 v35, -v35, v56, v55
	v_div_fmas_f32 v35, v35, v49, v56
	v_div_fixup_f32 v35, v35, v3, v34
	ds_bpermute_b32 v34, v109, v54
	v_fmac_f32_e32 v46, v35, v35
	s_waitcnt lgkmcnt(0)
	v_add_f32_e32 v34, v54, v34
	ds_bpermute_b32 v49, v107, v34
	s_waitcnt lgkmcnt(0)
	v_add_f32_e32 v34, v34, v49
	ds_bpermute_b32 v49, v105, v34
	s_waitcnt lgkmcnt(0)
	v_add_f32_e32 v34, v34, v49
	v_mul_f32_e32 v34, v8, v34
	v_fmac_f32_e32 v34, v18, v26
	v_fmac_f32_e32 v34, v19, v28
	v_fmac_f32_e32 v34, v20, v30
	v_fmac_f32_e32 v34, v21, v32
	v_div_scale_f32 v49, s[28:29], v4, v4, v34
	v_rcp_f32_e32 v54, v49
	s_nop 0
	v_fma_f32 v55, -v49, v54, 1.0
	v_fmac_f32_e32 v54, v55, v54
	v_div_scale_f32 v55, vcc, v34, v4, v34
	v_mul_f32_e32 v56, v55, v54
	v_fma_f32 v57, -v49, v56, v55
	v_fmac_f32_e32 v56, v57, v54
	v_fma_f32 v49, -v49, v56, v55
	v_div_fmas_f32 v49, v49, v54, v56
	v_div_fixup_f32 v34, v49, v4, v34
	ds_bpermute_b32 v49, v109, v53
	v_fmac_f32_e32 v47, v34, v34
	s_waitcnt lgkmcnt(0)
	v_add_f32_e32 v49, v53, v49
	ds_bpermute_b32 v53, v107, v49
	s_waitcnt lgkmcnt(0)
	v_add_f32_e32 v49, v49, v53
	ds_bpermute_b32 v53, v105, v49
	s_waitcnt lgkmcnt(0)
	v_add_f32_e32 v49, v49, v53
	v_mul_f32_e32 v49, v9, v49
	v_fmac_f32_e32 v49, v22, v26
	v_fmac_f32_e32 v49, v23, v28
	v_fmac_f32_e32 v49, v24, v30
	v_fmac_f32_e32 v49, v25, v32
	v_div_scale_f32 v26, s[28:29], v5, v5, v49
	v_rcp_f32_e32 v28, v26
	s_nop 0
	v_fma_f32 v30, -v26, v28, 1.0
	v_fmac_f32_e32 v28, v30, v28
	v_div_scale_f32 v30, vcc, v49, v5, v49
	v_mul_f32_e32 v32, v30, v28
	v_fma_f32 v53, -v26, v32, v30
	v_fmac_f32_e32 v32, v53, v28
	v_fma_f32 v26, -v26, v32, v30
	v_div_fmas_f32 v26, v26, v28, v32
	ds_bpermute_b32 v28, v109, v52
	v_div_fixup_f32 v26, v26, v5, v49
	v_fmac_f32_e32 v48, v26, v26
	s_waitcnt lgkmcnt(0)
	v_add_f32_e32 v28, v52, v28
	ds_bpermute_b32 v30, v107, v28
	s_waitcnt lgkmcnt(0)
	v_add_f32_e32 v28, v28, v30
	ds_bpermute_b32 v30, v105, v28
	s_waitcnt lgkmcnt(0)
; __device__ __forceinline__ void lds_add(LAS float* p, float v) { __hip_atomic_fetch_add(p, v, __ATOMIC_RELAXED, __HIP_MEMORY_SCOPE_WORKGROUP); }
; __device__ __forceinline__ void mlstm_sample_unit(const Frame& F, int b, int h) {
;     ...
;         for (int t = 0; t < 4; ++t) { float a = acc[rg][t]; a += __shfl_xor(a, 1); a += __shfl_xor(a, 2); a += __shfl_xor(a, 4);
;             float num = sS[40 + t] * a;
; #pragma unroll
;             for (int s2 = 0; s2 < 4; ++s2) num += sS[48 + t * 4 + s2] * sv[s2 * 256 + w * 32 + rg * 8 + r8];
;             hv[rg][t] = num / sS[44 + t]; if (seg == 0) ssq[t] += hv[rg][t] * hv[rg][t]; }
; #pragma unroll
;     for (int t = 0; t < 4; ++t) { ssq[t] = wave_sum(ssq[t]); }
;     if (lane == 0) {
; #pragma unroll
;         for (int t = 0; t < 4; ++t) lds_add(&sS[32 + t], ssq[t]); }
	v_add_f32_e32 v28, v28, v30
	v_mul_f32_e32 v6, v6, v28
	v_fmac_f32_e32 v6, v14, v27
	v_fmac_f32_e32 v6, v15, v29
	v_fmac_f32_e32 v6, v16, v31
	v_fmac_f32_e32 v6, v17, v33
	v_div_scale_f32 v14, s[28:29], v2, v2, v6
	v_rcp_f32_e32 v15, v14
	s_nop 0
	v_fma_f32 v16, -v14, v15, 1.0
	v_fmac_f32_e32 v15, v16, v15
	v_div_scale_f32 v16, vcc, v6, v2, v6
	v_mul_f32_e32 v17, v16, v15
	v_fma_f32 v28, -v14, v17, v16
	v_fmac_f32_e32 v17, v28, v15
	v_fma_f32 v14, -v14, v17, v16
	v_div_fmas_f32 v14, v14, v15, v17
	v_div_fixup_f32 v14, v14, v2, v6
	ds_bpermute_b32 v2, v109, v51
	v_fmac_f32_e32 v0, v14, v14
	v_cndmask_b32_e64 v0, 0, v0, s[10:11]
	s_waitcnt lgkmcnt(0)
	v_add_f32_e32 v2, v51, v2
	ds_bpermute_b32 v6, v107, v2
	s_waitcnt lgkmcnt(0)
	v_add_f32_e32 v2, v2, v6
	ds_bpermute_b32 v6, v105, v2
	s_waitcnt lgkmcnt(0)
	v_add_f32_e32 v2, v2, v6
	v_mul_f32_e32 v2, v7, v2
	v_fmac_f32_e32 v2, v10, v27
	v_fmac_f32_e32 v2, v11, v29
	v_fmac_f32_e32 v2, v12, v31
	v_fmac_f32_e32 v2, v13, v33
	v_div_scale_f32 v6, s[28:29], v3, v3, v2
	v_rcp_f32_e32 v7, v6
	s_nop 0
	v_fma_f32 v10, -v6, v7, 1.0
	v_fmac_f32_e32 v7, v10, v7
	v_div_scale_f32 v10, vcc, v2, v3, v2
	v_mul_f32_e32 v11, v10, v7
	v_fma_f32 v12, -v6, v11, v10
	v_fmac_f32_e32 v11, v12, v7
	v_fma_f32 v6, -v6, v11, v10
	v_div_fmas_f32 v6, v6, v7, v11
	v_div_fixup_f32 v11, v6, v3, v2
	ds_bpermute_b32 v3, v109, v50
	v_fmac_f32_e32 v46, v11, v11
	v_cndmask_b32_e64 v2, 0, v46, s[10:11]
	s_waitcnt lgkmcnt(0)
	v_add_f32_e32 v3, v50, v3
	ds_bpermute_b32 v6, v107, v3
	s_waitcnt lgkmcnt(0)
	v_add_f32_e32 v3, v3, v6
	ds_bpermute_b32 v6, v105, v3
	s_waitcnt lgkmcnt(0)
	v_add_f32_e32 v3, v3, v6
	v_mul_f32_e32 v3, v8, v3
	v_fmac_f32_e32 v3, v18, v27
	v_fmac_f32_e32 v3, v19, v29
	v_fmac_f32_e32 v3, v20, v31
	v_fmac_f32_e32 v3, v21, v33
	v_div_scale_f32 v6, s[28:29], v4, v4, v3
	v_rcp_f32_e32 v7, v6
	s_nop 0
	v_fma_f32 v8, -v6, v7, 1.0
	v_fmac_f32_e32 v7, v8, v7
	v_div_scale_f32 v8, vcc, v3, v4, v3
	v_mul_f32_e32 v10, v8, v7
	v_fma_f32 v12, -v6, v10, v8
	v_fmac_f32_e32 v10, v12, v7
	v_fma_f32 v6, -v6, v10, v8
	v_div_fmas_f32 v6, v6, v7, v10
	v_div_fixup_f32 v10, v6, v4, v3
	ds_bpermute_b32 v3, v109, v45
	v_fmac_f32_e32 v47, v10, v10
	v_cndmask_b32_e64 v4, 0, v47, s[10:11]
	s_waitcnt lgkmcnt(0)
	v_add_f32_e32 v3, v45, v3
	ds_bpermute_b32 v6, v107, v3
	s_waitcnt lgkmcnt(0)
	v_add_f32_e32 v3, v3, v6
	ds_bpermute_b32 v6, v105, v3
	s_waitcnt lgkmcnt(0)
	v_add_f32_e32 v3, v3, v6
	v_mul_f32_e32 v3, v9, v3
	v_fmac_f32_e32 v3, v22, v27
	v_fmac_f32_e32 v3, v23, v29
	v_fmac_f32_e32 v3, v24, v31
	v_fmac_f32_e32 v3, v25, v33
	v_div_scale_f32 v6, s[28:29], v5, v5, v3
	v_rcp_f32_e32 v7, v6
	s_nop 0
	v_fma_f32 v8, -v6, v7, 1.0
	v_fmac_f32_e32 v7, v8, v7
	v_div_scale_f32 v8, vcc, v3, v5, v3
	v_mul_f32_e32 v9, v8, v7
	v_fma_f32 v12, -v6, v9, v8
	v_fmac_f32_e32 v9, v12, v7
	v_fma_f32 v6, -v6, v9, v8
	v_div_fmas_f32 v6, v6, v7, v9
	v_div_fixup_f32 v8, v6, v5, v3
	ds_bpermute_b32 v3, v111, v0
	v_fmac_f32_e32 v48, v8, v8
	v_cndmask_b32_e64 v7, 0, v48, s[10:11]
	ds_bpermute_b32 v6, v111, v4
	ds_bpermute_b32 v9, v111, v7
	s_waitcnt lgkmcnt(2)
	v_add_f32_e32 v0, v0, v3
	ds_bpermute_b32 v3, v83, v0
	s_waitcnt lgkmcnt(2)
	v_add_f32_e32 v4, v4, v6
	s_waitcnt lgkmcnt(1)
	v_add_f32_e32 v7, v7, v9
	ds_bpermute_b32 v6, v83, v4
	s_waitcnt lgkmcnt(1)
	v_add_f32_e32 v0, v0, v3
	ds_bpermute_b32 v3, v101, v0
	ds_bpermute_b32 v9, v83, v7
	s_waitcnt lgkmcnt(2)
	v_add_f32_e32 v4, v4, v6
	ds_bpermute_b32 v6, v101, v4
	s_waitcnt lgkmcnt(2)
	v_add_f32_e32 v0, v0, v3
	ds_bpermute_b32 v3, v105, v0
	s_waitcnt lgkmcnt(2)
	v_add_f32_e32 v7, v7, v9
	ds_bpermute_b32 v9, v101, v7
	s_waitcnt lgkmcnt(2)
	v_add_f32_e32 v4, v4, v6
	ds_bpermute_b32 v6, v105, v4
	s_waitcnt lgkmcnt(2)
	v_add_f32_e32 v0, v0, v3
	ds_bpermute_b32 v3, v107, v0
	s_waitcnt lgkmcnt(2)
	v_add_f32_e32 v7, v7, v9
	ds_bpermute_b32 v9, v105, v7
	s_waitcnt lgkmcnt(2)
	v_add_f32_e32 v4, v4, v6
	ds_bpermute_b32 v6, v107, v4
	s_waitcnt lgkmcnt(2)
	v_add_f32_e32 v3, v0, v3
	ds_bpermute_b32 v0, v111, v2
	s_waitcnt lgkmcnt(2)
	v_add_f32_e32 v7, v7, v9
	ds_bpermute_b32 v9, v107, v7
	s_waitcnt lgkmcnt(2)
	v_add_f32_e32 v4, v4, v6
	ds_bpermute_b32 v5, v109, v3
	s_waitcnt lgkmcnt(2)
	v_add_f32_e32 v0, v2, v0
	ds_bpermute_b32 v2, v83, v0
	s_waitcnt lgkmcnt(2)
	v_add_f32_e32 v7, v7, v9
	ds_bpermute_b32 v6, v109, v4
	ds_bpermute_b32 v9, v109, v7
	s_waitcnt lgkmcnt(2)
	v_add_f32_e32 v0, v0, v2
	ds_bpermute_b32 v2, v101, v0
	s_waitcnt lgkmcnt(0)
	v_add_f32_e32 v0, v0, v2
	ds_bpermute_b32 v2, v105, v0
	s_waitcnt lgkmcnt(0)
	v_add_f32_e32 v0, v0, v2
	ds_bpermute_b32 v2, v107, v0
	s_waitcnt lgkmcnt(0)
	v_add_f32_e32 v0, v0, v2
	ds_bpermute_b32 v2, v109, v0
	s_and_saveexec_b64 s[46:47], s[4:5]
	s_cbranch_execz .LBB0_392
	s_mov_b64 s[42:43], exec
	v_add_f32_e32 v5, v3, v5
	v_bfrev_b32_e32 v3, 1

; __device__ __forceinline__ void mlstm_sample_unit(const Frame& F, int b, int h) {
;     ...
;     if (tid < 256) { float nn = decay * F.in[5][(size_t)bh * 256 + tid];
; #pragma unroll
;         for (int s2 = 0; s2 < 4; ++s2) nn += gs[s2] * sk[s2 * 256 + tid];
;         F.out[O_NS + (size_t)bh * 256 + tid] = nn; }
.LBB0_392:
	s_or_b64 exec, exec, s[46:47]
	s_and_saveexec_b64 s[46:47], s[36:37]
	s_cbranch_execz .LBB0_394
	s_waitcnt lgkmcnt(0)
	ds_read2st64_b32 v[2:3], v113 offset0:16 offset1:20
	v_readlane_b32 s12, v245, 21
	v_readlane_b32 s26, v245, 35
	v_readlane_b32 s27, v245, 36
	s_add_u32 s28, s26, s64
	s_waitcnt lgkmcnt(0)
	v_pk_mul_f32 v[2:3], v[102:103], v[2:3]
	s_addc_u32 s29, s27, s65
	v_mov_b32_e32 v95, v1
	v_readlane_b32 s13, v245, 22
	v_readlane_b32 s14, v245, 23
	v_readlane_b32 s15, v245, 24
	v_readlane_b32 s16, v245, 25
	v_readlane_b32 s17, v245, 26
	v_readlane_b32 s18, v245, 27
	v_readlane_b32 s19, v245, 28
	v_readlane_b32 s20, v245, 29
	v_readlane_b32 s21, v245, 30
	v_readlane_b32 s22, v245, 31
	v_readlane_b32 s23, v245, 32
	v_readlane_b32 s24, v245, 33
	v_readlane_b32 s25, v245, 34
	v_fma_f32 v0, v100, v202, v2
	v_add_f32_e32 v0, v0, v3
	ds_read2st64_b32 v[2:3], v113 offset0:24 offset1:28
	s_waitcnt lgkmcnt(0)
	v_pk_mul_f32 v[2:3], v[98:99], v[2:3]
	s_nop 0
	v_add_f32_e32 v0, v0, v2
	v_add_f32_e32 v0, v0, v3
	v_lshl_add_u64 v[2:3], s[28:29], 0, v[94:95]
	v_add_co_u32_e32 v2, vcc, 0xe541000, v2
	s_nop 1
	v_addc_co_u32_e32 v3, vcc, 0, v3, vcc
	global_store_dword v[2:3], v0, off offset:16

; __device__ __forceinline__ unsigned cvt_pk_bf16(float lo, float hi) { unsigned r; asm volatile("v_cvt_pk_bf16_f32 %0, %1, %2" : "=v"(r) : "v"(lo), "v"(hi)); return r; }
; __device__ __forceinline__ float bf2f(bf16_t h) { return __uint_as_float((unsigned)h << 16); }
; __device__ __forceinline__ float sigmoidf_(float x) { return 1.f / (1.f + __expf(-x)); }
; __device__ __forceinline__ void mlstm_sample_unit(const Frame& F, int b, int h) {
;     ...
; #pragma unroll
;     for (int rg = 0; rg < 4; ++rg)
; #pragma unroll
;         for (int t = 0; t < 4; ++t) if (seg == ((rg * 4 + t) & 7)) { const int vr = w * 32 + rg * 8 + r8; const size_t row = (size_t)(SP + b * 4 + t);
;             const float rms = rsqrtf(sS[32 + t] * (1.f / 256.f) + EPS); const float og = sigmoidf_(bf2f(P[row * NIN + C_MO + h * 256 + vr]));
;             MIX[row * D + 1024 + h * 256 + vr] = (bf16_t)(cvt_pk_bf16(hv[rg][t] * rms * F.in[18][h * 256 + vr] * og, 0.f) & 0xffff); }
.LBB0_396:
	s_or_b64 exec, exec, s[42:43]
	v_readlane_b32 s12, v245, 21
	v_add_u32_e32 v0, s0, v84
	s_lshl_b32 s0, s0, 1
	v_readlane_b32 s16, v245, 25
	v_readlane_b32 s17, v245, 26
	s_waitcnt lgkmcnt(0)
	v_lshl_add_u64 v[2:3], v[92:93], 0, s[0:1]
	s_mul_hi_i32 s28, s62, 0x2c00
	s_mul_i32 s29, s62, 0x2c00
	v_lshlrev_b32_e32 v6, 1, v84
	v_lshl_add_u64 v[4:5], v[0:1], 2, s[16:17]
	s_barrier
	v_readlane_b32 s13, v245, 22
	v_readlane_b32 s14, v245, 23
	v_readlane_b32 s15, v245, 24
	v_readlane_b32 s18, v245, 27
	v_readlane_b32 s19, v245, 28
	v_readlane_b32 s20, v245, 29
	v_readlane_b32 s21, v245, 30
	v_readlane_b32 s22, v245, 31
	v_readlane_b32 s23, v245, 32
	v_readlane_b32 s24, v245, 33
	v_readlane_b32 s25, v245, 34
	v_readlane_b32 s26, v245, 35
	v_readlane_b32 s27, v245, 36
	s_lshl_b64 s[64:65], s[62:63], 12
	v_and_b32_e32 v45, 3, v144
	v_bfe_u32 v46, v144, 2, 1
	v_mul_u32_u24_e32 v47, 0x2c00, v45
	v_lshl_add_u32 v47, v46, 4, v47
	v_lshlrev_b32_e32 v48, 12, v45
	v_lshl_add_u32 v48, v46, 4, v48
	v_lshlrev_b32_e32 v50, 2, v45
	ds_read_b32 v51, v50 offset:12416
	v_mov_b32_e32 v49, 0
	v_lshl_add_u64 v[60:61], v[2:3], 0, v[48:49]
	v_lshl_add_u64 v[60:61], v[60:61], 0, s[64:65]
	v_mov_b32_e32 v62, v37
	v_cndmask_b32_e64 v62, v62, v38, s[6:7]
	v_cndmask_b32_e64 v62, v62, v41, s[66:67]
	v_cndmask_b32_e64 v62, v62, v44, s[58:59]
	v_cndmask_b32_e64 v62, v62, v43, s[50:51]
	v_cndmask_b32_e64 v62, v62, v42, s[40:41]
	v_cndmask_b32_e64 v62, v62, v40, s[38:39]
	v_cndmask_b32_e64 v62, v62, v39, s[10:11]
	v_mov_b32_e32 v63, v8
	v_cndmask_b32_e64 v63, v63, v10, s[6:7]
	v_cndmask_b32_e64 v63, v63, v11, s[66:67]
	v_cndmask_b32_e64 v63, v63, v14, s[58:59]
	v_cndmask_b32_e64 v63, v63, v26, s[50:51]
	v_cndmask_b32_e64 v63, v63, v34, s[40:41]
	v_cndmask_b32_e64 v63, v63, v35, s[38:39]
	v_cndmask_b32_e64 v63, v63, v36, s[10:11]
	s_waitcnt lgkmcnt(0)
	v_fmamk_f32 v51, v51, 0x3b800000, v131
	v_mul_f32_e32 v64, 0x4b800000, v51
	v_cmp_gt_f32_e32 vcc, s31, v51
	s_nop 1
	v_cndmask_b32_e32 v51, v51, v64, vcc
	v_rsq_f32_e32 v51, v51
	s_nop 0
	v_mul_f32_e32 v64, 0x45800000, v51
	v_cndmask_b32_e32 v51, v51, v64, vcc
	v_mul_f32_e32 v62, v62, v51
	v_mul_f32_e32 v63, v63, v51
	s_waitcnt vmcnt(0)
	v_mul_f32_e32 v62, v205, v62
	v_mul_f32_e32 v63, v206, v63
	v_lshlrev_b32_e32 v203, 16, v203
	v_mul_f32_e32 v203, 0xbfb8aa3b, v203
	v_exp_f32_e32 v203, v203
	s_nop 0
	v_add_f32_e32 v203, 1.0, v203
	v_div_scale_f32 v65, s[42:43], v203, v203, 1.0
	v_rcp_f32_e32 v66, v65
	s_nop 0
	v_fma_f32 v67, -v65, v66, 1.0
	v_fmac_f32_e32 v66, v67, v66
	v_div_scale_f32 v67, vcc, 1.0, v203, 1.0
	v_mul_f32_e32 v68, v67, v66
	v_fma_f32 v69, -v65, v68, v67
	v_fmac_f32_e32 v68, v69, v66
	v_fma_f32 v65, -v65, v68, v67
	v_div_fmas_f32 v65, v65, v66, v68
	v_div_fixup_f32 v203, v65, v203, 1.0
	v_mul_f32_e32 v62, v203, v62
	v_cvt_pk_bf16_f32 v62, v62, v1
	global_store_short v[60:61], v62, off
	v_lshlrev_b32_e32 v204, 16, v204
	v_mul_f32_e32 v204, 0xbfb8aa3b, v204
	v_exp_f32_e32 v204, v204
	s_nop 0
	v_add_f32_e32 v204, 1.0, v204
	v_div_scale_f32 v65, s[42:43], v204, v204, 1.0
	v_rcp_f32_e32 v66, v65
	s_nop 0
	v_fma_f32 v67, -v65, v66, 1.0
	v_fmac_f32_e32 v66, v67, v66
	v_div_scale_f32 v67, vcc, 1.0, v204, 1.0
	v_mul_f32_e32 v68, v67, v66
	v_fma_f32 v69, -v65, v68, v67
	v_fmac_f32_e32 v68, v69, v66
	v_fma_f32 v65, -v65, v68, v67
	v_div_fmas_f32 v65, v65, v66, v68
	v_div_fixup_f32 v204, v65, v204, 1.0
	v_mul_f32_e32 v63, v204, v63
	v_cvt_pk_bf16_f32 v63, v63, v1
	global_store_short v[60:61], v63, off offset:32
	s_branch .LBB0_349

; __device__ __forceinline__ float bf2f(bf16_t h) { return __uint_as_float((unsigned)h << 16); }
; __device__ __forceinline__ float logsigmoid_fast(float x) { return fminf(x, 0.f) - __logf(1.f + __expf(-fabsf(x))); }
; __device__ __forceinline__ void mlstm_sample_unit(const Frame& F, int b, int h) {
;     ...
;     for (int i = tid; i < 1024; i += 512) { const int t = i >> 8, d = i & 255; const bf16_t* row = P + (size_t)(SP + b * 4 + t) * NIN;
;         sq[i] = bf2f(row[C_MQ + h * 256 + d]) * 0.0625f; sk[i] = bf2f(row[C_MK + h * 256 + d]); sv[i] = bf2f(row[C_MV + h * 256 + d]); }
;     if (tid < 64) sS[tid] = 0.f;
;     __syncthreads();
;     {
;         const int pair = tid >> 5, sub = tid & 31, t = pair >> 2, s = pair & 3; float a = 0.f, c = 0.f;
; #pragma unroll
;         for (int e = 0; e < 8; ++e) { const int d = sub * 8 + e; a += sq[t * 256 + d] * sk[s * 256 + d]; if (s == 0) c += sq[t * 256 + d] * F.in[5][(size_t)bh * 256 + d]; }
; #pragma unroll
;         for (int o = 16; o >= 1; o >>= 1) { a += __shfl_xor(a, o); c += __shfl_xor(c, o); }
;         if (sub == 0) { sS[pair] = a; if (s == 0) sS[16 + t] = c; } }
;     __syncthreads();
;     ...
;     const float m0 = F.in[6][bh];
;     { float acc = 0.f;
; #pragma unroll
;       for (int t = 0; t < 4; ++t) { const float* gp = gates + (size_t)(SP + b * 4 + t) * 8; li[t] = gp[h] + F.in[15][h]; acc += logsigmoid_fast(gp[4 + h] + F.in[16][h]); bcum[t] = acc; } }
;     ...
;     if (tid < 256) { float nn = decay * F.in[5][(size_t)bh * 256 + tid];
.LBB0_539:
	s_movk_i32 s35, 0x2c00
	v_mad_i64_i32 v[10:11], s[38:39], v6, s35, v[96:97]
	v_lshl_add_u64 v[12:13], v[10:11], 0, v[0:1]
	v_lshl_add_u64 v[14:15], v[10:11], 0, v[2:3]
	v_lshl_add_u64 v[10:11], v[10:11], 0, v[4:5]
	global_load_ushort v9, v[12:13], off offset:3072
	global_load_ushort v12, v[14:15], off
	global_load_ushort v10, v[10:11], off
	v_add_u32_e32 v6, 2, v6
	v_mad_i64_i32 v[16:17], s[38:39], v6, s35, v[96:97]
	v_lshl_add_u64 v[18:19], v[16:17], 0, v[0:1]
	v_lshl_add_u64 v[20:21], v[16:17], 0, v[2:3]
	v_lshl_add_u64 v[16:17], v[16:17], 0, v[4:5]
	global_load_ushort v22, v[18:19], off offset:3072
	global_load_ushort v23, v[20:21], off
	global_load_ushort v24, v[16:17], off
	s_ashr_i32 s35, s34, 31
	v_readlane_b32 s60, v245, 47
	v_readlane_b32 s61, v245, 48
	v_readlane_b32 s46, v245, 49
	v_readlane_b32 s47, v245, 50
	v_readlane_b32 vcc_lo, v245, 17
	v_readlane_b32 vcc_hi, v245, 18
	s_lshl_b64 s[54:55], s[34:35], 10
	s_add_u32 s60, s60, s54
	s_addc_u32 s61, s61, s55
	s_lshl_b64 s[54:55], s[34:35], 2
	s_add_u32 s46, s46, s54
	s_addc_u32 s47, s47, s55
	s_lshl_b32 s54, s29, 2
	v_mov_b32_e32 v56, s54
	s_add_u32 s38, s91, s54
	s_addc_u32 s39, s92, 0
	s_add_i32 s54, s28, 0x2000
	s_ashr_i32 s55, s54, 31
	s_lshl_b64 s[54:55], s[54:55], 5
	s_add_u32 s38, s38, s54
	s_addc_u32 s39, s39, s55
	v_readlane_b32 s54, v245, 21
	v_readlane_b32 s55, v245, 22
	v_lshlrev_b32_e32 v57, 2, v82
	global_load_dwordx4 v[58:61], v57, s[60:61]
	global_load_dwordx4 v[62:65], v57, s[60:61] offset:16
	global_load_dword v55, v1, s[38:39] offset:16
	global_load_dword v49, v1, s[38:39]
	global_load_dword v70, v1, s[38:39] offset:32
	global_load_dword v71, v1, s[38:39] offset:48
	global_load_dword v72, v1, s[38:39] offset:64
	global_load_dword v73, v1, s[38:39] offset:80
	global_load_dword v74, v1, s[38:39] offset:96
	global_load_dword v75, v1, s[38:39] offset:112
	global_load_dword v54, v1, s[46:47]
	global_load_dword v48, v56, vcc
	global_load_dword v66, v56, s[54:55]
	s_and_saveexec_b64 s[54:55], s[36:37]
	global_load_dword v202, v94, s[60:61]
	s_or_b64 exec, exec, s[54:55]
	v_add_u32_e32 v6, 2, v6
	s_waitcnt vmcnt(17)
	v_lshlrev_b32_e32 v9, 16, v9
	v_lshlrev_b32_e32 v11, 16, v12
	v_lshlrev_b32_e32 v10, 16, v10
	v_mul_f32_e32 v9, 0x3d800000, v9
	ds_write_b32 v7, v10 offset:8192
	ds_write2st64_b32 v7, v9, v11 offset1:16
	v_add_u32_e32 v7, 0x800, v7
	s_waitcnt vmcnt(14)
	v_lshlrev_b32_e32 v22, 16, v22
	v_lshlrev_b32_e32 v23, 16, v23
	v_lshlrev_b32_e32 v24, 16, v24
	v_mul_f32_e32 v22, 0x3d800000, v22
	ds_write_b32 v7, v24 offset:8192
	ds_write2st64_b32 v7, v22, v23 offset1:16
	v_add_u32_e32 v7, 0x800, v7
	s_or_b64 exec, exec, s[0:1]
	s_and_saveexec_b64 s[0:1], s[68:69]
	ds_write_b32 v113, v1 offset:12288
	s_or_b64 exec, exec, s[0:1]
	s_waitcnt lgkmcnt(0)
	s_barrier
	ds_read_b32 v0, v115
	ds_read_b32 v2, v117 offset:4096
	s_ashr_i32 s35, s34, 31
	v_readlane_b32 s12, v245, 37
	s_lshl_b64 s[62:63], s[34:35], 10
	v_readlane_b32 s22, v245, 47
	v_readlane_b32 s23, v245, 48
	s_add_u32 s0, s22, s62
	s_addc_u32 s1, s23, s63
	v_mov_b32_e32 v3, 0
	v_lshlrev_b32_e32 v4, 2, v82
	v_readlane_b32 s13, v245, 38
	v_readlane_b32 s14, v245, 39
	v_readlane_b32 s15, v245, 40
	v_readlane_b32 s16, v245, 41
	v_readlane_b32 s17, v245, 42
	v_readlane_b32 s18, v245, 43
	v_readlane_b32 s19, v245, 44
	v_readlane_b32 s20, v245, 45
	v_readlane_b32 s21, v245, 46
	v_readlane_b32 s24, v245, 49
	v_readlane_b32 s25, v245, 50
	v_readlane_b32 s26, v245, 51
	v_readlane_b32 s27, v245, 52
	ds_read_b32 v5, v115 offset:4
	ds_read_b32 v6, v117 offset:4100
	ds_read_b32 v7, v115 offset:8
	ds_read_b32 v8, v117 offset:4104
	ds_read_b32 v9, v115 offset:12
	ds_read_b32 v10, v117 offset:4108
	ds_read_b32 v11, v115 offset:16
	ds_read_b32 v12, v117 offset:4112
	ds_read_b32 v13, v115 offset:20
	ds_read_b32 v14, v117 offset:4116
	ds_read_b32 v15, v115 offset:24
	ds_read_b32 v16, v117 offset:4120
	ds_read_b32 v17, v115 offset:28
	ds_read_b32 v18, v117 offset:4124
	s_waitcnt lgkmcnt(0)
	s_and_saveexec_b64 s[38:39], s[4:5]
	s_waitcnt vmcnt(12)
	v_fma_f32 v3, v0, v58, 0
	v_fmac_f32_e32 v3, v5, v59
	v_fmac_f32_e32 v3, v7, v60
	v_fmac_f32_e32 v3, v9, v61
	v_fmac_f32_e32 v3, v11, v62
	v_fmac_f32_e32 v3, v13, v63
	v_fmac_f32_e32 v3, v15, v64
	v_fmac_f32_e32 v3, v17, v65
	s_or_b64 exec, exec, s[38:39]
	v_fma_f32 v0, v0, v2, 0
	v_fmac_f32_e32 v0, v5, v6
	v_fmac_f32_e32 v0, v7, v8
	v_fmac_f32_e32 v0, v9, v10
	v_fmac_f32_e32 v0, v11, v12
	v_fmac_f32_e32 v0, v13, v14
	v_fmac_f32_e32 v0, v15, v16
	v_fmac_f32_e32 v0, v17, v18
	ds_bpermute_b32 v2, v83, v3
	ds_bpermute_b32 v4, v83, v0
	s_waitcnt lgkmcnt(1)
	v_add_f32_e32 v2, v3, v2
	s_waitcnt lgkmcnt(0)
	v_add_f32_e32 v0, v0, v4
	ds_bpermute_b32 v3, v99, v2
	ds_bpermute_b32 v4, v99, v0
	s_waitcnt lgkmcnt(1)
	v_add_f32_e32 v2, v2, v3
	s_waitcnt lgkmcnt(0)
	v_add_f32_e32 v0, v0, v4
	ds_bpermute_b32 v3, v105, v2
	ds_bpermute_b32 v4, v105, v0
	s_waitcnt lgkmcnt(1)
	v_add_f32_e32 v2, v2, v3
	s_waitcnt lgkmcnt(0)
	v_add_f32_e32 v4, v0, v4
	ds_bpermute_b32 v3, v107, v2
	ds_bpermute_b32 v5, v107, v4
	s_waitcnt lgkmcnt(1)
	v_add_f32_e32 v0, v2, v3
	s_waitcnt lgkmcnt(0)
	v_add_f32_e32 v3, v4, v5
	ds_bpermute_b32 v4, v109, v3
	ds_bpermute_b32 v2, v109, v0
	s_and_saveexec_b64 s[0:1], s[6:7]
	s_cbranch_execz .LBB0_561
	s_waitcnt lgkmcnt(1)
	v_add_f32_e32 v3, v3, v4
	ds_write_b32 v119, v3 offset:12288
	s_and_b64 exec, exec, s[4:5]
	s_cbranch_execz .LBB0_561
	s_waitcnt lgkmcnt(1)
	v_add_f32_e32 v0, v0, v2
	ds_write_b32 v121, v0 offset:12352
; __device__ __forceinline__ float logsigmoid_fast(float x) { return fminf(x, 0.f) - __logf(1.f + __expf(-fabsf(x))); }
; __device__ __forceinline__ void mlstm_sample_unit(const Frame& F, int b, int h) {
;     ...
;     float li[4], bcum[4], mt[4], at[4], gs[4], sm[4][4], den[4];
;     const float m0 = F.in[6][bh];
;     { float acc = 0.f;
; #pragma unroll
;       for (int t = 0; t < 4; ++t) { const float* gp = gates + (size_t)(SP + b * 4 + t) * 8; li[t] = gp[h] + F.in[15][h]; acc += logsigmoid_fast(gp[4 + h] + F.in[16][h]); bcum[t] = acc; } }
; #pragma unroll
;     for (int t = 0; t < 4; ++t) { const float mi = bcum[t] + m0; float m = mi;
; #pragma unroll
;         for (int s = 0; s < 4; ++s) if (s <= t) m = fmaxf(m, bcum[t] - bcum[s] + li[s]);
;         mt[t] = m; at[t] = __expf(mi - m); float dsum = at[t] * sS[16 + t];
; #pragma unroll
;         for (int s = 0; s < 4; ++s) { sm[t][s] = (s <= t) ? sS[t * 4 + s] * __expf(bcum[t] - bcum[s] + li[s] - m) : 0.f; dsum += sm[t][s]; }
;         den[t] = fmaxf(fabsf(dsum), __expf(-m)); }
;     const float mnew = mt[3], decay = __expf(bcum[3] + m0 - mnew);
.LBB0_561:
	s_or_b64 exec, exec, s[0:1]
	v_readlane_b32 s12, v245, 37
	s_add_i32 s54, s28, 0x2000
	s_lshl_b64 s[64:65], s[34:35], 2
	v_readlane_b32 s24, v245, 49
	v_readlane_b32 s25, v245, 50
	s_add_u32 s0, s24, s64
	s_addc_u32 s1, s25, s65
	s_waitcnt lgkmcnt(0)
	s_barrier
	s_lshl_b32 s0, s29, 2
	v_readlane_b32 s13, v245, 38
	v_readlane_b32 s14, v245, 39
	v_readlane_b32 s15, v245, 40
	v_readlane_b32 s16, v245, 41
	v_readlane_b32 s17, v245, 42
	v_readlane_b32 s18, v245, 43
	v_readlane_b32 s19, v245, 44
	v_readlane_b32 s20, v245, 45
	v_readlane_b32 s21, v245, 46
	v_readlane_b32 s22, v245, 47
	v_readlane_b32 s23, v245, 48
	v_readlane_b32 s26, v245, 51
	v_readlane_b32 s27, v245, 52
	s_add_u32 s29, s91, s0
	s_addc_u32 s42, s92, 0
	v_readlane_b32 s12, v245, 3
	s_ashr_i32 s55, s54, 31
	v_mov_b32_e32 v2, s0
	v_readlane_b32 s13, v245, 4
	v_readlane_b32 s14, v245, 5
	v_readlane_b32 s15, v245, 6
	v_readlane_b32 s16, v245, 7
	v_readlane_b32 s17, v245, 8
	v_readlane_b32 s18, v245, 9
	v_readlane_b32 s19, v245, 10
	v_readlane_b32 s20, v245, 11
	v_readlane_b32 s21, v245, 12
	v_readlane_b32 s22, v245, 13
	v_readlane_b32 s23, v245, 14
	v_readlane_b32 s24, v245, 15
	v_readlane_b32 s25, v245, 16
	v_readlane_b32 s26, v245, 17
	v_readlane_b32 s27, v245, 18
	s_lshl_b64 s[0:1], s[54:55], 5
	s_add_u32 s0, s29, s0
	s_addc_u32 s1, s42, s1
	v_add_u32_e32 v155, 0x2000, v85
	v_readlane_b32 s12, v245, 21
	v_readlane_b32 s13, v245, 22
	v_add_u32_e32 v154, 0x2400, v85
	v_add_u32_e32 v147, 0x2800, v85
	v_add_u32_e32 v95, 0x2c00, v85
	v_readlane_b32 s14, v245, 23
	v_readlane_b32 s15, v245, 24
	v_readlane_b32 s12, v245, 1
	v_readlane_b32 s13, v245, 2
	v_readlane_b32 s16, v245, 25
	v_readlane_b32 s17, v245, 26
	v_readlane_b32 s18, v245, 27
	v_readlane_b32 s19, v245, 28
	v_readlane_b32 s20, v245, 29
	v_readlane_b32 s21, v245, 30
	v_readlane_b32 s22, v245, 31
	v_readlane_b32 s23, v245, 32
	v_readlane_b32 s24, v245, 33
	v_readlane_b32 s25, v245, 34
	v_readlane_b32 s26, v245, 35
	v_readlane_b32 s27, v245, 36
	s_waitcnt vmcnt(0)
	v_mov_b32_e32 v0, v54
	v_mov_b32_e32 v3, v55
	v_mov_b32_e32 v4, v48
	v_mov_b32_e32 v5, v66
	v_mov_b32_e32 v2, v49
	v_add_f32_e32 v3, v5, v3
	v_min_f32_e32 v6, 0, v3
	v_mul_f32_e64 v3, |v3|, s77
	v_exp_f32_e32 v3, v3
	s_waitcnt vmcnt(0)
	v_add_f32_e32 v2, v4, v2
	v_add_f32_e32 v3, 1.0, v3
	v_cmp_gt_f32_e32 vcc, s82, v3
	s_and_b64 s[0:1], vcc, exec
	s_cselect_b32 s0, 32, 0
	v_ldexp_f32 v3, v3, s0
	v_log_f32_e32 v3, v3
	s_add_i32 s38, s28, 0x2001
	s_ashr_i32 s39, s38, 31
	v_mul_f32_e32 v7, 0x3f317217, v3
	v_fma_f32 v7, v3, s83, -v7
	v_fmac_f32_e32 v7, 0x3377d1cf, v3
	v_fmac_f32_e32 v7, 0x3f317217, v3
	v_cmp_lt_f32_e64 s[0:1], |v3|, s90
	s_nop 1
	v_cndmask_b32_e64 v3, v3, v7, s[0:1]
	s_lshl_b64 s[0:1], s[38:39], 5
	v_cndmask_b32_e32 v7, 0, v133, vcc
	s_add_u32 s0, s29, s0
	v_sub_f32_e32 v3, v3, v7
	s_addc_u32 s1, s42, s1
	v_sub_f32_e32 v3, v6, v3
	v_mov_b32_e32 v6, v70
	v_add_f32_e32 v3, 0, v3
	s_waitcnt vmcnt(0)
	v_add_f32_e32 v20, v4, v6
	v_mov_b32_e32 v6, v71
	s_waitcnt vmcnt(0)
	v_add_f32_e32 v6, v5, v6
	v_min_f32_e32 v7, 0, v6
	v_mul_f32_e64 v6, |v6|, s77
	v_exp_f32_e32 v6, v6
	s_nop 0
	v_add_f32_e32 v6, 1.0, v6
	v_cmp_gt_f32_e32 vcc, s82, v6
	s_and_b64 s[0:1], vcc, exec
	s_cselect_b32 s0, 32, 0
	v_ldexp_f32 v6, v6, s0
	v_log_f32_e32 v6, v6
	s_add_i32 s46, s28, 0x2002
	s_ashr_i32 s47, s46, 31
	v_mul_f32_e32 v8, 0x3f317217, v6
	v_fma_f32 v8, v6, s83, -v8
	v_fmac_f32_e32 v8, 0x3377d1cf, v6
	v_fmac_f32_e32 v8, 0x3f317217, v6
	v_cmp_lt_f32_e64 s[0:1], |v6|, s90
	s_nop 1
	v_cndmask_b32_e64 v6, v6, v8, s[0:1]
	v_cndmask_b32_e32 v8, 0, v133, vcc
	s_lshl_b64 s[0:1], s[46:47], 5
	v_sub_f32_e32 v6, v6, v8
	s_add_u32 s0, s29, s0
	v_sub_f32_e32 v6, v7, v6
	s_addc_u32 s1, s42, s1
	v_add_f32_e32 v21, v3, v6
	v_mov_b32_e32 v6, v72
	s_waitcnt vmcnt(0)
	v_add_f32_e32 v22, v4, v6
	v_mov_b32_e32 v6, v73
	s_waitcnt vmcnt(0)
	v_add_f32_e32 v6, v5, v6
	v_min_f32_e32 v7, 0, v6
	v_mul_f32_e64 v6, |v6|, s77
	v_exp_f32_e32 v6, v6
	s_nop 0
	v_add_f32_e32 v6, 1.0, v6
	v_cmp_gt_f32_e32 vcc, s82, v6
	s_and_b64 s[0:1], vcc, exec
	s_cselect_b32 s0, 32, 0
	v_ldexp_f32 v6, v6, s0
	v_log_f32_e32 v6, v6
	s_add_i32 s60, s28, 0x2003
	s_ashr_i32 s61, s60, 31
	v_mul_f32_e32 v8, 0x3f317217, v6
	v_fma_f32 v8, v6, s83, -v8
	v_fmac_f32_e32 v8, 0x3377d1cf, v6
	v_fmac_f32_e32 v8, 0x3f317217, v6
	v_cmp_lt_f32_e64 s[0:1], |v6|, s90
	s_nop 1
	v_cndmask_b32_e64 v6, v6, v8, s[0:1]
	v_cndmask_b32_e32 v8, 0, v133, vcc
	s_lshl_b64 s[0:1], s[60:61], 5
	v_sub_f32_e32 v6, v6, v8
	s_add_u32 s0, s29, s0
	v_sub_f32_e32 v6, v7, v6
	s_addc_u32 s1, s42, s1
	v_add_f32_e32 v23, v21, v6
	v_mov_b32_e32 v6, v74
	s_waitcnt vmcnt(0)
	v_add_f32_e32 v4, v4, v6
	v_mov_b32_e32 v6, v75
	s_waitcnt vmcnt(0)
	v_add_f32_e32 v5, v5, v6
	v_min_f32_e32 v6, 0, v5
	v_mul_f32_e64 v5, |v5|, s77
	v_exp_f32_e32 v5, v5
	s_nop 0
	v_add_f32_e32 v5, 1.0, v5
	v_cmp_gt_f32_e32 vcc, s82, v5
	s_and_b64 s[0:1], vcc, exec
	s_cselect_b32 s0, 32, 0
	v_ldexp_f32 v5, v5, s0
	v_log_f32_e32 v5, v5
	s_nop 0
	v_mul_f32_e32 v7, 0x3f317217, v5
	v_fma_f32 v7, v5, s83, -v7
	v_fmac_f32_e32 v7, 0x3377d1cf, v5
	v_fmac_f32_e32 v7, 0x3f317217, v5
	v_cmp_lt_f32_e64 s[0:1], |v5|, s90
	s_nop 1
	v_cndmask_b32_e64 v5, v5, v7, s[0:1]
	v_cndmask_b32_e32 v7, 0, v133, vcc
	v_sub_f32_e32 v5, v5, v7
	v_sub_f32_e32 v5, v6, v5
	v_add_f32_e32 v5, v23, v5
	v_sub_f32_e32 v7, v5, v3
	v_sub_f32_e32 v8, v5, v21
	v_add_f32_e32 v6, v0, v5
	v_add_f32_e32 v7, v2, v7
	v_add_f32_e32 v8, v20, v8
	v_sub_f32_e32 v10, v5, v23
	v_sub_f32_e32 v5, v5, v5
	v_max3_f32 v9, v6, v7, v8
	v_add_f32_e32 v10, v22, v10
	v_add_f32_e32 v4, v4, v5
	v_max3_f32 v145, v9, v10, v4
	v_sub_f32_e32 v4, v4, v145
	v_mul_f32_e32 v4, 0x3fb8aa3b, v4
	v_exp_f32_e32 v101, v4
	v_sub_f32_e32 v4, v7, v145
	v_mul_f32_e32 v4, 0x3fb8aa3b, v4
	v_exp_f32_e32 v102, v4
	v_sub_f32_e32 v4, v8, v145
	v_mul_f32_e32 v4, 0x3fb8aa3b, v4
	v_sub_f32_e32 v5, v6, v145
	v_exp_f32_e32 v103, v4
	v_sub_f32_e32 v4, v10, v145
	v_mul_f32_e32 v5, 0x3fb8aa3b, v5
	v_mul_f32_e32 v4, 0x3fb8aa3b, v4
	v_exp_f32_e32 v98, v5
	v_exp_f32_e32 v100, v4
	ds_read2_b32 v[4:5], v155 offset1:8
	ds_read2_b32 v[6:7], v154 offset1:8
	ds_read2_b32 v[8:9], v147 offset1:8
	ds_read2_b32 v[16:17], v95 offset1:8
	ds_read2_b32 v[10:11], v155 offset0:16 offset1:24
	ds_read2_b32 v[12:13], v154 offset0:16 offset1:24
	ds_read2_b32 v[14:15], v147 offset0:16 offset1:24
	ds_read2_b32 v[18:19], v95 offset0:16 offset1:24
	s_and_saveexec_b64 s[0:1], s[12:13]
	s_cbranch_execz .LBB0_563
; __device__ __forceinline__ void mlstm_sample_unit(const Frame& F, int b, int h) {
;     ...
;     for (int t = 0; t < 4; ++t) { const float mi = bcum[t] + m0; float m = mi;
; #pragma unroll
;         for (int s = 0; s < 4; ++s) if (s <= t) m = fmaxf(m, bcum[t] - bcum[s] + li[s]);
;         mt[t] = m; at[t] = __expf(mi - m); float dsum = at[t] * sS[16 + t];
; #pragma unroll
;         for (int s = 0; s < 4; ++s) { sm[t][s] = (s <= t) ? sS[t * 4 + s] * __expf(bcum[t] - bcum[s] + li[s] - m) : 0.f; dsum += sm[t][s]; }
;         den[t] = fmaxf(fabsf(dsum), __expf(-m)); }
;     const float mnew = mt[3], decay = __expf(bcum[3] + m0 - mnew);
; #pragma unroll
;     for (int s = 0; s < 4; ++s) gs[s] = __expf(bcum[3] - bcum[s] + li[s] - mnew);
;     const int r8 = lane >> 3, seg = lane & 7, w = F.wave;
;     const float* c0b = F.in[4] + (size_t)bh * 65536 + (size_t)(w * 32 + r8) * 256 + seg * 4;
;     float* c1b = F.out + O_CS + (size_t)bh * 65536 + (size_t)(w * 32 + r8) * 256 + seg * 4;
;     float acc[4][4], gv[4][4];
; #pragma unroll
;     for (int rg = 0; rg < 4; ++rg)
; #pragma unroll
;         for (int t = 0; t < 4; ++t) { acc[rg][t] = 0.f; gv[rg][t] = gs[t] * sv[t * 256 + w * 32 + rg * 8 + r8]; }
;     if (tid == 0) {
; #pragma unroll
;         for (int t = 0; t < 4; ++t) { sS[40 + t] = at[t]; sS[44 + t] = den[t];
; #pragma unroll
;             for (int s2 = 0; s2 < 4; ++s2) sS[48 + t * 4 + s2] = sm[t][s2]; } }
;     f32x4 c[2][2][4];
; #pragma unroll
;     for (int i2 = 0; i2 < 2; ++i2)
; #pragma unroll
;         for (int rg = 0; rg < 4; ++rg) c[0][i2][rg] = __builtin_nontemporal_load((const f32x4*)(c0b + rg * 2048 + i2 * 32));
	v_add_f32_e32 v24, v0, v23
	v_sub_f32_e32 v25, v23, v3
	v_sub_f32_e32 v27, v23, v21
	v_add_f32_e32 v38, v0, v21
	v_sub_f32_e32 v39, v21, v3
	v_sub_f32_e32 v21, v21, v21
	v_add_f32_e32 v0, v0, v3
	v_sub_f32_e32 v3, v3, v3
	v_add_f32_e32 v25, v2, v25
	v_add_f32_e32 v27, v20, v27
	v_sub_f32_e32 v23, v23, v23
	v_add_f32_e32 v39, v2, v39
	v_add_f32_e32 v20, v20, v21
	v_add_f32_e32 v2, v2, v3
	v_max_f32_e32 v26, v24, v25
	v_add_f32_e32 v23, v22, v23
	v_max3_f32 v44, v38, v39, v20
	v_max_f32_e32 v3, v0, v2
	v_max3_f32 v35, v26, v27, v23
	v_sub_f32_e32 v20, v20, v44
	v_sub_f32_e32 v0, v0, v3
	v_sub_f32_e32 v22, v24, v35
	v_sub_f32_e32 v24, v25, v35
	v_mul_f32_e32 v20, 0x3fb8aa3b, v20
	v_mul_f32_e32 v0, 0x3fb8aa3b, v0
	v_mul_f32_e32 v24, 0x3fb8aa3b, v24
	v_sub_f32_e32 v21, v38, v44
	v_sub_f32_e32 v38, v39, v44
	v_exp_f32_e32 v39, v20
	v_exp_f32_e32 v20, v0
	v_sub_f32_e32 v0, v2, v3
	v_exp_f32_e32 v32, v24
	v_sub_f32_e32 v24, v27, v35
	v_mul_f32_e32 v0, 0x3fb8aa3b, v0
	v_mul_f32_e32 v24, 0x3fb8aa3b, v24
	v_exp_f32_e32 v0, v0
	ds_read_b32 v43, v1 offset:12288
	ds_read_b64 v[36:37], v1 offset:12304
	ds_read_b96 v[40:42], v1 offset:12320
	v_exp_f32_e32 v33, v24
	ds_read_b128 v[24:27], v1 offset:12352
	ds_read_b128 v[28:31], v1 offset:12336
	v_mul_f32_e32 v2, 0xbfb8aa3b, v3
	v_mul_f32_e32 v38, 0x3fb8aa3b, v38
	v_exp_f32_e32 v2, v2
	v_mul_f32_e32 v21, 0x3fb8aa3b, v21
	v_exp_f32_e32 v38, v38
	v_exp_f32_e32 v21, v21
	s_waitcnt lgkmcnt(4)
	v_mul_f32_e32 v0, v0, v43
	v_mul_f32_e32 v22, 0x3fb8aa3b, v22
	v_mul_f32_e32 v44, 0xbfb8aa3b, v44
	s_waitcnt lgkmcnt(1)
	v_fma_f32 v3, v20, v24, v0
	v_exp_f32_e32 v22, v22
	v_sub_f32_e32 v23, v23, v35
	v_exp_f32_e32 v44, v44
	v_max_f32_e64 v24, |v3|, v2
	v_mul_f32_e32 v2, 0xbfb8aa3b, v145
	v_mul_f32_e32 v23, 0x3fb8aa3b, v23
	v_exp_f32_e32 v43, v2
	v_mov_b32_e32 v2, v1
	v_mov_b32_e32 v3, v1
	v_pk_mul_f32 v[36:37], v[38:39], v[36:37]
	v_exp_f32_e32 v23, v23
	ds_write_b128 v1, v[0:3] offset:12480
	v_fma_f32 v0, v21, v25, v36
	v_mul_f32_e32 v35, 0xbfb8aa3b, v35
	v_add_f32_e32 v0, v0, v37
	v_pk_mul_f32 v[32:33], v[32:33], v[40:41]
	v_exp_f32_e32 v35, v35
	v_max_f32_e64 v25, |v0|, v44
	v_fma_f32 v0, v22, v26, v32
	v_add_f32_e32 v0, v0, v33
	v_mul_f32_e32 v34, v23, v42
	v_fmac_f32_e32 v0, v23, v42
	v_mov_b32_e32 v23, v98
	ds_write_b128 v1, v[20:23] offset:12448
	s_waitcnt lgkmcnt(2)
	v_pk_mul_f32 v[20:21], v[102:103], v[28:29]
	v_max_f32_e64 v26, |v0|, v35
	v_fma_f32 v0, v98, v27, v20
	v_add_f32_e32 v0, v0, v21
	v_pk_mul_f32 v[22:23], v[100:101], v[30:31]
	v_mov_b32_e32 v38, v1
	v_add_f32_e32 v0, v0, v22
	v_add_f32_e32 v0, v23, v0
	v_mov_b32_e32 v39, v1
	v_mov_b32_e32 v35, v1
	v_max_f32_e64 v27, |v0|, v43
	ds_write_b128 v1, v[36:39] offset:12496
	ds_write_b128 v1, v[32:35] offset:12512
	ds_write_b128 v1, v[24:27] offset:12464
	ds_write_b128 v1, v[20:23] offset:12528
.LBB0_563:
	s_or_b64 exec, exec, s[0:1]
	s_lshl_b64 s[0:1], s[34:35], 18
	v_lshl_add_u64 v[142:143], v[86:87], 0, s[0:1]
	global_load_dwordx4 v[78:81], v[142:143], off nt
	v_add_co_u32_e32 v148, vcc, s76, v142
	s_waitcnt lgkmcnt(7)
	v_mul_f32_e32 v132, v4, v102
	v_addc_co_u32_e32 v149, vcc, 0, v143, vcc
	global_load_dwordx4 v[136:139], v[148:149], off nt
	v_add_co_u32_e32 v152, vcc, s70, v142
	s_waitcnt lgkmcnt(6)
	v_mul_f32_e32 v130, v6, v103
	v_addc_co_u32_e32 v153, vcc, 0, v143, vcc
	global_load_dwordx4 v[74:77], v[152:153], off nt
	v_add_co_u32_e32 v150, vcc, s71, v142
	s_waitcnt lgkmcnt(5)
	v_mul_f32_e32 v128, v8, v100
	v_addc_co_u32_e32 v151, vcc, 0, v143, vcc
	s_waitcnt lgkmcnt(4)
	v_mul_f32_e32 v126, v16, v101
	v_mul_f32_e32 v124, v5, v102
	v_mul_f32_e32 v122, v7, v103
	v_mul_f32_e32 v120, v9, v100
	v_mul_f32_e32 v118, v17, v101
	s_waitcnt lgkmcnt(3)
	v_mul_f32_e32 v116, v10, v102
	s_waitcnt lgkmcnt(2)
	v_mul_f32_e32 v114, v12, v103
	s_waitcnt lgkmcnt(1)
	v_mul_f32_e32 v112, v14, v100
	s_waitcnt lgkmcnt(0)
	v_mul_f32_e32 v110, v18, v101
	v_mul_f32_e32 v108, v11, v102
	v_mul_f32_e32 v106, v103, v13
	v_mul_f32_e32 v104, v100, v15
	v_mul_f32_e32 v0, v101, v19
	global_load_dwordx4 v[50:53], v[150:151], off nt
	global_load_dwordx4 v[30:33], v[142:143], off offset:128 nt
	global_load_dwordx4 v[26:29], v[148:149], off offset:128 nt
	global_load_dwordx4 v[22:25], v[152:153], off offset:128 nt
	global_load_dwordx4 v[18:21], v[150:151], off offset:128 nt
	global_load_dwordx4 v[46:49], v[142:143], off offset:256 nt
	global_load_dwordx4 v[42:45], v[148:149], off offset:256 nt
	global_load_dwordx4 v[38:41], v[152:153], off offset:256 nt
	global_load_dwordx4 v[34:37], v[150:151], off offset:256 nt
	global_load_dwordx4 v[14:17], v[142:143], off offset:384 nt
	global_load_dwordx4 v[10:13], v[148:149], off offset:384 nt
	global_load_dwordx4 v[6:9], v[152:153], off offset:384 nt
	global_load_dwordx4 v[2:5], v[150:151], off offset:384 nt
	ds_read_b128 v[156:159], v123
	ds_read_b128 v[174:177], v123 offset:4096
	ds_read_b128 v[70:73], v123 offset:1024
	ds_read_b128 v[66:69], v123 offset:5120
	ds_read_b128 v[62:65], v123 offset:2048
	ds_read_b128 v[58:61], v123 offset:6144
	ds_read_b128 v[54:57], v123 offset:3072
	ds_read_b128 v[178:181], v123 offset:7168
	s_waitcnt lgkmcnt(6)
	v_pk_mul_f32 v[162:163], v[132:133], v[174:175] op_sel_hi:[0,1]
	v_lshl_add_u64 v[134:135], v[88:89], 0, s[0:1]
	s_waitcnt vmcnt(15)
	v_mul_f32_e32 v140, v79, v157
	v_fmac_f32_e32 v140, v78, v156
	s_waitcnt lgkmcnt(5)
	v_mul_f32_e32 v161, v79, v71
	v_fmac_f32_e32 v140, v80, v158
	v_fmac_f32_e32 v161, v78, v70
	v_fmac_f32_e32 v140, v81, v159
	v_fmac_f32_e32 v161, v80, v72
	v_add_f32_e32 v172, 0, v140
	v_pk_mul_f32 v[140:141], v[132:133], v[176:177] op_sel_hi:[0,1]
	v_fmac_f32_e32 v161, v81, v73
	v_pk_fma_f32 v[140:141], v[98:99], v[80:81], v[140:141] op_sel_hi:[0,1,1]
	v_pk_fma_f32 v[162:163], v[98:99], v[78:79], v[162:163] op_sel_hi:[0,1,1]
	v_add_f32_e32 v171, 0, v161
	s_waitcnt lgkmcnt(3)
; #define LAS __attribute__((address_space(3)))
; __device__ __forceinline__ void mlstm_sample_unit(const Frame& F, int b, int h) {
;     ...
;     for (int hh = 0; hh < 4; ++hh) {
;         if (hh < 3) {
; #pragma unroll
;             for (int i2 = 0; i2 < 2; ++i2)
; #pragma unroll
;                 for (int rg = 0; rg < 4; ++rg) c[(hh + 1) & 1][i2][rg] = __builtin_nontemporal_load((const f32x4*)(c0b + rg * 2048 + ((hh + 1) * 2 + i2) * 32)); }
; #pragma unroll
;         for (int i2 = 0; i2 < 2; ++i2) { const int it = hh * 2 + i2; const int d = it * 32 + seg * 4;
;             f32x4 q[4], k[4];
; #pragma unroll
;             for (int t = 0; t < 4; ++t) { q[t] = *(const LAS f32x4*)(sq + t * 256 + d); k[t] = *(const LAS f32x4*)(sk + t * 256 + d); }
; #pragma unroll
;             for (int rg = 0; rg < 4; ++rg) { const f32x4 cv = c[hh & 1][i2][rg]; f32x4 nv = cv * decay;
; #pragma unroll
;                 for (int t = 0; t < 4; ++t) { acc[rg][t] += cv[0] * q[t][0] + cv[1] * q[t][1] + cv[2] * q[t][2] + cv[3] * q[t][3]; nv += k[t] * gv[rg][t]; }
;                 __builtin_nontemporal_store(nv, (f32x4*)(c1b + rg * 2048 + it * 32)); } }
;     }
	v_mul_f32_e32 v161, v79, v63
	s_waitcnt lgkmcnt(1)
	v_mul_f32_e32 v79, v79, v55
	v_pk_fma_f32 v[140:141], v[130:131], v[68:69], v[140:141] op_sel_hi:[0,1,1]
	v_fmac_f32_e32 v161, v78, v62
	v_fmac_f32_e32 v79, v78, v54
	v_fmac_f32_e32 v161, v80, v64
	v_pk_fma_f32 v[140:141], v[128:129], v[60:61], v[140:141] op_sel_hi:[0,1,1]
	v_fmac_f32_e32 v79, v80, v56
	v_fmac_f32_e32 v161, v81, v65
	v_fmac_f32_e32 v79, v81, v57
	s_waitcnt lgkmcnt(0)
	v_pk_fma_f32 v[80:81], v[126:127], v[180:181], v[140:141] op_sel_hi:[0,1,1]
	s_waitcnt vmcnt(14)
	v_mul_f32_e32 v140, v137, v71
	v_pk_fma_f32 v[162:163], v[130:131], v[66:67], v[162:163] op_sel_hi:[0,1,1]
	v_fmac_f32_e32 v140, v136, v70
	v_pk_fma_f32 v[162:163], v[128:129], v[58:59], v[162:163] op_sel_hi:[0,1,1]
	v_fmac_f32_e32 v140, v138, v72
	v_add_f32_e32 v169, 0, v79
	v_pk_fma_f32 v[78:79], v[126:127], v[178:179], v[162:163] op_sel_hi:[0,1,1]
	v_fmac_f32_e32 v140, v139, v73
	global_store_dwordx4 v[134:135], v[78:81], off nt
	v_add_f32_e32 v167, 0, v140
	v_mul_f32_e32 v140, v137, v63
	v_mul_f32_e32 v78, v137, v157
	v_fmac_f32_e32 v78, v136, v156
	v_pk_mul_f32 v[80:81], v[124:125], v[174:175] op_sel_hi:[0,1]
	v_fmac_f32_e32 v140, v136, v62
	v_fmac_f32_e32 v78, v138, v158
	v_pk_fma_f32 v[80:81], v[98:99], v[136:137], v[80:81] op_sel_hi:[0,1,1]
	v_fmac_f32_e32 v140, v138, v64
	v_fmac_f32_e32 v78, v139, v159
	v_pk_fma_f32 v[80:81], v[122:123], v[66:67], v[80:81] op_sel_hi:[0,1,1]
	v_fmac_f32_e32 v140, v139, v65
	v_add_f32_e32 v168, 0, v78
	v_pk_mul_f32 v[78:79], v[124:125], v[176:177] op_sel_hi:[0,1]
	v_add_f32_e32 v166, 0, v140
	v_pk_fma_f32 v[140:141], v[120:121], v[58:59], v[80:81] op_sel_hi:[0,1,1]
	v_mul_f32_e32 v80, v137, v55
	v_pk_fma_f32 v[78:79], v[98:99], v[138:139], v[78:79] op_sel_hi:[0,1,1]
	v_fmac_f32_e32 v80, v136, v54
	v_pk_fma_f32 v[78:79], v[122:123], v[68:69], v[78:79] op_sel_hi:[0,1,1]
	v_fmac_f32_e32 v80, v138, v56
	v_pk_fma_f32 v[78:79], v[120:121], v[60:61], v[78:79] op_sel_hi:[0,1,1]
	v_fmac_f32_e32 v80, v139, v57
	v_add_f32_e32 v165, 0, v80
	v_pk_fma_f32 v[80:81], v[118:119], v[180:181], v[78:79] op_sel_hi:[0,1,1]
	v_pk_fma_f32 v[78:79], v[118:119], v[178:179], v[140:141] op_sel_hi:[0,1,1]
	v_add_co_u32_e32 v140, vcc, s76, v134
	s_waitcnt vmcnt(14)
	v_mul_f32_e32 v136, v75, v71
	v_addc_co_u32_e32 v141, vcc, 0, v135, vcc
	global_store_dwordx4 v[140:141], v[78:81], off nt
	v_fmac_f32_e32 v136, v74, v70
	v_fmac_f32_e32 v136, v76, v72
	v_mul_f32_e32 v78, v75, v157
	v_fmac_f32_e32 v78, v74, v156
	v_fmac_f32_e32 v78, v76, v158
	v_fmac_f32_e32 v78, v77, v159
	v_pk_mul_f32 v[80:81], v[116:117], v[174:175] op_sel_hi:[0,1]
	v_fmac_f32_e32 v136, v77, v73
	v_add_f32_e32 v164, 0, v78
	v_pk_mul_f32 v[78:79], v[116:117], v[176:177] op_sel_hi:[0,1]
	v_pk_fma_f32 v[80:81], v[98:99], v[74:75], v[80:81] op_sel_hi:[0,1,1]
	v_add_f32_e32 v163, 0, v136
	v_mul_f32_e32 v136, v75, v63
	v_mul_f32_e32 v75, v75, v55
	v_pk_fma_f32 v[78:79], v[98:99], v[76:77], v[78:79] op_sel_hi:[0,1,1]
	v_fmac_f32_e32 v75, v74, v54
	v_pk_fma_f32 v[78:79], v[114:115], v[68:69], v[78:79] op_sel_hi:[0,1,1]
	v_pk_fma_f32 v[80:81], v[114:115], v[66:67], v[80:81] op_sel_hi:[0,1,1]
	v_fmac_f32_e32 v136, v74, v62
	v_fmac_f32_e32 v75, v76, v56
	v_fmac_f32_e32 v136, v76, v64
	v_pk_fma_f32 v[78:79], v[112:113], v[60:61], v[78:79] op_sel_hi:[0,1,1]
	v_pk_fma_f32 v[80:81], v[112:113], v[58:59], v[80:81] op_sel_hi:[0,1,1]
	v_fmac_f32_e32 v75, v77, v57
	v_add_co_u32_e32 v138, vcc, s70, v134
	v_add_f32_e32 v170, 0, v161
	v_fmac_f32_e32 v136, v77, v65
	v_add_f32_e32 v161, 0, v75
	v_pk_fma_f32 v[76:77], v[110:111], v[180:181], v[78:79] op_sel_hi:[0,1,1]
	v_pk_fma_f32 v[74:75], v[110:111], v[178:179], v[80:81] op_sel_hi:[0,1,1]
	v_addc_co_u32_e32 v139, vcc, 0, v135, vcc
	global_store_dwordx4 v[138:139], v[74:77], off nt
	s_waitcnt vmcnt(15)
	v_mul_f32_e32 v71, v51, v71
	v_mul_f32_e32 v63, v51, v63
	v_mul_f32_e32 v74, v51, v157
	v_fmac_f32_e32 v74, v50, v156
	v_fmac_f32_e32 v74, v52, v158
	v_fmac_f32_e32 v74, v53, v159
	v_pk_mul_f32 v[76:77], v[108:109], v[174:175] op_sel_hi:[0,1]
	v_add_f32_e32 v159, 0, v74
	v_pk_mul_f32 v[74:75], v[108:109], v[176:177] op_sel_hi:[0,1]
	v_pk_fma_f32 v[76:77], v[98:99], v[50:51], v[76:77] op_sel_hi:[0,1,1]
	v_mul_f32_e32 v51, v51, v55
	v_pk_fma_f32 v[74:75], v[98:99], v[52:53], v[74:75] op_sel_hi:[0,1,1]
	v_fmac_f32_e32 v51, v50, v54
	v_fmac_f32_e32 v71, v50, v70
	v_pk_fma_f32 v[68:69], v[106:107], v[68:69], v[74:75] op_sel_hi:[0,1,1]
	v_pk_fma_f32 v[66:67], v[106:107], v[66:67], v[76:77] op_sel_hi:[0,1,1]
	v_fmac_f32_e32 v63, v50, v62
	v_fmac_f32_e32 v51, v52, v56
	v_add_f32_e32 v162, 0, v136
	v_fmac_f32_e32 v71, v52, v72
	v_fmac_f32_e32 v63, v52, v64
	v_pk_fma_f32 v[60:61], v[104:105], v[60:61], v[68:69] op_sel_hi:[0,1,1]
	v_pk_fma_f32 v[58:59], v[104:105], v[58:59], v[66:67] op_sel_hi:[0,1,1]
	v_fmac_f32_e32 v51, v53, v57
	v_add_co_u32_e32 v136, vcc, s71, v134
	v_fmac_f32_e32 v71, v53, v73
	v_fmac_f32_e32 v63, v53, v65
	v_add_f32_e32 v156, 0, v51
	v_pk_fma_f32 v[52:53], v[0:1], v[180:181], v[60:61] op_sel_hi:[0,1,1]
	v_pk_fma_f32 v[50:51], v[0:1], v[178:179], v[58:59] op_sel_hi:[0,1,1]
	v_addc_co_u32_e32 v137, vcc, 0, v135, vcc
	global_store_dwordx4 v[136:137], v[50:53], off nt
	v_add_f32_e32 v158, 0, v71
	v_add_f32_e32 v157, 0, v63
	ds_read_b128 v[70:73], v123 offset:128
	ds_read_b128 v[74:77], v123 offset:4224
	ds_read_b128 v[62:65], v123 offset:1152
	ds_read_b128 v[66:69], v123 offset:5248
	ds_read_b128 v[54:57], v123 offset:2176
	ds_read_b128 v[58:61], v123 offset:6272
	ds_read_b128 v[50:53], v123 offset:3200
	ds_read_b128 v[78:81], v123 offset:7296
	s_waitcnt vmcnt(15) lgkmcnt(5)
; #define LAS __attribute__((address_space(3)))
; __device__ __forceinline__ void mlstm_sample_unit(const Frame& F, int b, int h) {
;     ...
;     for (int hh = 0; hh < 4; ++hh) {
;         if (hh < 3) {
; #pragma unroll
;             for (int i2 = 0; i2 < 2; ++i2)
; #pragma unroll
;                 for (int rg = 0; rg < 4; ++rg) c[(hh + 1) & 1][i2][rg] = __builtin_nontemporal_load((const f32x4*)(c0b + rg * 2048 + ((hh + 1) * 2 + i2) * 32)); }
; #pragma unroll
;         for (int i2 = 0; i2 < 2; ++i2) { const int it = hh * 2 + i2; const int d = it * 32 + seg * 4;
;             f32x4 q[4], k[4];
; #pragma unroll
;             for (int t = 0; t < 4; ++t) { q[t] = *(const LAS f32x4*)(sq + t * 256 + d); k[t] = *(const LAS f32x4*)(sk + t * 256 + d); }
; #pragma unroll
;             for (int rg = 0; rg < 4; ++rg) { const f32x4 cv = c[hh & 1][i2][rg]; f32x4 nv = cv * decay;
; #pragma unroll
;                 for (int t = 0; t < 4; ++t) { acc[rg][t] += cv[0] * q[t][0] + cv[1] * q[t][1] + cv[2] * q[t][2] + cv[3] * q[t][3]; nv += k[t] * gv[rg][t]; }
;                 __builtin_nontemporal_store(nv, (f32x4*)(c1b + rg * 2048 + it * 32)); } }
;     }
	v_mul_f32_e32 v176, v31, v63
	v_mul_f32_e32 v173, v31, v71
	v_fmac_f32_e32 v176, v30, v62
	v_fmac_f32_e32 v173, v30, v70
	v_fmac_f32_e32 v176, v32, v64
	v_fmac_f32_e32 v173, v32, v72
	v_fmac_f32_e32 v176, v33, v65
	v_fmac_f32_e32 v173, v33, v73
	v_pk_mul_f32 v[174:175], v[132:133], v[74:75] op_sel_hi:[0,1]
	v_add_f32_e32 v191, v171, v176
	s_waitcnt lgkmcnt(3)
	v_mul_f32_e32 v171, v31, v55
	v_add_f32_e32 v190, v172, v173
	v_pk_mul_f32 v[172:173], v[132:133], v[76:77] op_sel_hi:[0,1]
	v_pk_fma_f32 v[174:175], v[98:99], v[30:31], v[174:175] op_sel_hi:[0,1,1]
	v_fmac_f32_e32 v171, v30, v54
	s_waitcnt lgkmcnt(1)
	v_mul_f32_e32 v31, v31, v51
	v_pk_fma_f32 v[172:173], v[98:99], v[32:33], v[172:173] op_sel_hi:[0,1,1]
	v_fmac_f32_e32 v171, v32, v56
	v_fmac_f32_e32 v31, v30, v50
	v_pk_fma_f32 v[174:175], v[130:131], v[66:67], v[174:175] op_sel_hi:[0,1,1]
	v_pk_fma_f32 v[172:173], v[130:131], v[68:69], v[172:173] op_sel_hi:[0,1,1]
	v_fmac_f32_e32 v171, v33, v57
	v_fmac_f32_e32 v31, v32, v52
	v_add_f32_e32 v192, v170, v171
	v_pk_fma_f32 v[170:171], v[128:129], v[60:61], v[172:173] op_sel_hi:[0,1,1]
	v_pk_fma_f32 v[172:173], v[128:129], v[58:59], v[174:175] op_sel_hi:[0,1,1]
	v_fmac_f32_e32 v31, v33, v53
	v_add_f32_e32 v169, v169, v31
	s_waitcnt lgkmcnt(0)
	v_pk_fma_f32 v[30:31], v[126:127], v[78:79], v[172:173] op_sel_hi:[0,1,1]
	v_pk_fma_f32 v[32:33], v[126:127], v[80:81], v[170:171] op_sel_hi:[0,1,1]
	global_store_dwordx4 v[134:135], v[30:33], off offset:128 nt
	s_waitcnt vmcnt(15)
	v_mul_f32_e32 v170, v27, v63
	v_fmac_f32_e32 v170, v26, v62
	v_mul_f32_e32 v30, v27, v71
	v_fmac_f32_e32 v30, v26, v70
	v_fmac_f32_e32 v30, v28, v72
	v_fmac_f32_e32 v170, v28, v64
	v_fmac_f32_e32 v30, v29, v73
	v_pk_mul_f32 v[32:33], v[124:125], v[74:75] op_sel_hi:[0,1]
	v_fmac_f32_e32 v170, v29, v65
	v_add_f32_e32 v168, v168, v30
	v_pk_mul_f32 v[30:31], v[124:125], v[76:77] op_sel_hi:[0,1]
	v_pk_fma_f32 v[32:33], v[98:99], v[26:27], v[32:33] op_sel_hi:[0,1,1]
	v_add_f32_e32 v167, v167, v170
	v_mul_f32_e32 v170, v27, v55
	v_mul_f32_e32 v27, v27, v51
	v_pk_fma_f32 v[30:31], v[98:99], v[28:29], v[30:31] op_sel_hi:[0,1,1]
	v_fmac_f32_e32 v27, v26, v50
	v_pk_fma_f32 v[30:31], v[122:123], v[68:69], v[30:31] op_sel_hi:[0,1,1]
	v_pk_fma_f32 v[32:33], v[122:123], v[66:67], v[32:33] op_sel_hi:[0,1,1]
	v_fmac_f32_e32 v170, v26, v54
	v_fmac_f32_e32 v27, v28, v52
	v_fmac_f32_e32 v170, v28, v56
	v_pk_fma_f32 v[30:31], v[120:121], v[60:61], v[30:31] op_sel_hi:[0,1,1]
	v_pk_fma_f32 v[32:33], v[120:121], v[58:59], v[32:33] op_sel_hi:[0,1,1]
	v_fmac_f32_e32 v27, v29, v53
	v_fmac_f32_e32 v170, v29, v57
	v_add_f32_e32 v165, v165, v27
	v_pk_fma_f32 v[28:29], v[118:119], v[80:81], v[30:31] op_sel_hi:[0,1,1]
	v_pk_fma_f32 v[26:27], v[118:119], v[78:79], v[32:33] op_sel_hi:[0,1,1]
	global_store_dwordx4 v[140:141], v[26:29], off offset:128 nt
	s_waitcnt vmcnt(15)
	v_mul_f32_e32 v30, v23, v63
	v_fmac_f32_e32 v30, v22, v62
	v_mul_f32_e32 v26, v23, v71
	v_fmac_f32_e32 v26, v22, v70
	v_fmac_f32_e32 v26, v24, v72
	v_fmac_f32_e32 v30, v24, v64
	v_fmac_f32_e32 v26, v25, v73
	v_pk_mul_f32 v[28:29], v[116:117], v[74:75] op_sel_hi:[0,1]
	v_fmac_f32_e32 v30, v25, v65
	v_add_f32_e32 v164, v164, v26
	v_pk_mul_f32 v[26:27], v[116:117], v[76:77] op_sel_hi:[0,1]
	v_pk_fma_f32 v[28:29], v[98:99], v[22:23], v[28:29] op_sel_hi:[0,1,1]
	v_add_f32_e32 v163, v163, v30
	v_mul_f32_e32 v30, v23, v55
	v_mul_f32_e32 v23, v23, v51
	v_pk_fma_f32 v[26:27], v[98:99], v[24:25], v[26:27] op_sel_hi:[0,1,1]
	v_fmac_f32_e32 v23, v22, v50
	v_pk_fma_f32 v[26:27], v[114:115], v[68:69], v[26:27] op_sel_hi:[0,1,1]
	v_pk_fma_f32 v[28:29], v[114:115], v[66:67], v[28:29] op_sel_hi:[0,1,1]
	v_fmac_f32_e32 v30, v22, v54
	v_fmac_f32_e32 v23, v24, v52
	v_fmac_f32_e32 v30, v24, v56
	v_pk_fma_f32 v[26:27], v[112:113], v[60:61], v[26:27] op_sel_hi:[0,1,1]
	v_pk_fma_f32 v[28:29], v[112:113], v[58:59], v[28:29] op_sel_hi:[0,1,1]
	v_fmac_f32_e32 v23, v25, v53
	v_fmac_f32_e32 v30, v25, v57
	v_add_f32_e32 v161, v161, v23
	v_pk_fma_f32 v[24:25], v[110:111], v[80:81], v[26:27] op_sel_hi:[0,1,1]
	v_pk_fma_f32 v[22:23], v[110:111], v[78:79], v[28:29] op_sel_hi:[0,1,1]
	global_store_dwordx4 v[138:139], v[22:25], off offset:128 nt
	s_waitcnt vmcnt(15)
	v_mul_f32_e32 v26, v19, v63
	v_fmac_f32_e32 v26, v18, v62
	v_mul_f32_e32 v22, v19, v71
	v_fmac_f32_e32 v22, v18, v70
	v_fmac_f32_e32 v22, v20, v72
	v_fmac_f32_e32 v26, v20, v64
	v_fmac_f32_e32 v22, v21, v73
	v_pk_mul_f32 v[24:25], v[108:109], v[74:75] op_sel_hi:[0,1]
	v_fmac_f32_e32 v26, v21, v65
	v_add_f32_e32 v173, v159, v22
	v_pk_mul_f32 v[22:23], v[108:109], v[76:77] op_sel_hi:[0,1]
	v_pk_fma_f32 v[24:25], v[98:99], v[18:19], v[24:25] op_sel_hi:[0,1,1]
	v_add_f32_e32 v193, v158, v26
	v_mul_f32_e32 v26, v19, v55
	v_mul_f32_e32 v19, v19, v51
	v_pk_fma_f32 v[22:23], v[98:99], v[20:21], v[22:23] op_sel_hi:[0,1,1]
	v_fmac_f32_e32 v19, v18, v50
	v_pk_fma_f32 v[22:23], v[106:107], v[68:69], v[22:23] op_sel_hi:[0,1,1]
	v_pk_fma_f32 v[24:25], v[106:107], v[66:67], v[24:25] op_sel_hi:[0,1,1]
	v_fmac_f32_e32 v26, v18, v54
	v_fmac_f32_e32 v19, v20, v52
	v_fmac_f32_e32 v26, v20, v56
	v_pk_fma_f32 v[22:23], v[104:105], v[60:61], v[22:23] op_sel_hi:[0,1,1]
	v_pk_fma_f32 v[24:25], v[104:105], v[58:59], v[24:25] op_sel_hi:[0,1,1]
	v_fmac_f32_e32 v19, v21, v53
	v_fmac_f32_e32 v26, v21, v57
	v_add_f32_e32 v195, v156, v19
	v_pk_fma_f32 v[20:21], v[0:1], v[80:81], v[22:23] op_sel_hi:[0,1,1]
	v_pk_fma_f32 v[18:19], v[0:1], v[78:79], v[24:25] op_sel_hi:[0,1,1]
	global_store_dwordx4 v[136:137], v[18:21], off offset:128 nt
	v_add_f32_e32 v166, v166, v170
	v_add_f32_e32 v162, v162, v30
	v_add_f32_e32 v194, v157, v26
	global_load_dwordx4 v[62:65], v[142:143], off offset:512 nt
	global_load_dwordx4 v[58:61], v[148:149], off offset:512 nt
	global_load_dwordx4 v[54:57], v[152:153], off offset:512 nt
	global_load_dwordx4 v[50:53], v[150:151], off offset:512 nt
	global_load_dwordx4 v[30:33], v[142:143], off offset:640 nt
	global_load_dwordx4 v[26:29], v[148:149], off offset:640 nt
	global_load_dwordx4 v[22:25], v[152:153], off offset:640 nt
	global_load_dwordx4 v[18:21], v[150:151], off offset:640 nt
	ds_read_b128 v[66:69], v123 offset:256
	ds_read_b128 v[70:73], v123 offset:4352
	ds_read_b128 v[74:77], v123 offset:1280
	ds_read_b128 v[78:81], v123 offset:5376
	ds_read_b128 v[174:177], v123 offset:2304
	ds_read_b128 v[178:181], v123 offset:6400
	ds_read_b128 v[182:185], v123 offset:3328
	ds_read_b128 v[186:189], v123 offset:7424
	s_waitcnt vmcnt(23) lgkmcnt(7)
; #define LAS __attribute__((address_space(3)))
; __device__ __forceinline__ void mlstm_sample_unit(const Frame& F, int b, int h) {
;     ...
;     for (int hh = 0; hh < 4; ++hh) {
;         if (hh < 3) {
; #pragma unroll
;             for (int i2 = 0; i2 < 2; ++i2)
; #pragma unroll
;                 for (int rg = 0; rg < 4; ++rg) c[(hh + 1) & 1][i2][rg] = __builtin_nontemporal_load((const f32x4*)(c0b + rg * 2048 + ((hh + 1) * 2 + i2) * 32)); }
; #pragma unroll
;         for (int i2 = 0; i2 < 2; ++i2) { const int it = hh * 2 + i2; const int d = it * 32 + seg * 4;
;             f32x4 q[4], k[4];
; #pragma unroll
;             for (int t = 0; t < 4; ++t) { q[t] = *(const LAS f32x4*)(sq + t * 256 + d); k[t] = *(const LAS f32x4*)(sk + t * 256 + d); }
; #pragma unroll
;             for (int rg = 0; rg < 4; ++rg) { const f32x4 cv = c[hh & 1][i2][rg]; f32x4 nv = cv * decay;
; #pragma unroll
;                 for (int t = 0; t < 4; ++t) { acc[rg][t] += cv[0] * q[t][0] + cv[1] * q[t][1] + cv[2] * q[t][2] + cv[3] * q[t][3]; nv += k[t] * gv[rg][t]; }
;                 __builtin_nontemporal_store(nv, (f32x4*)(c1b + rg * 2048 + it * 32)); } }
;     }
	v_mul_f32_e32 v156, v47, v67
	s_waitcnt lgkmcnt(5)
	v_mul_f32_e32 v170, v47, v75
	v_fmac_f32_e32 v156, v46, v66
	v_fmac_f32_e32 v170, v46, v74
	v_fmac_f32_e32 v156, v48, v68
	v_fmac_f32_e32 v170, v48, v76
	v_fmac_f32_e32 v156, v49, v69
	v_pk_mul_f32 v[158:159], v[132:133], v[70:71] op_sel_hi:[0,1]
	v_fmac_f32_e32 v170, v49, v77
	v_add_f32_e32 v172, v190, v156
	v_pk_mul_f32 v[156:157], v[132:133], v[72:73] op_sel_hi:[0,1]
	v_pk_fma_f32 v[158:159], v[98:99], v[46:47], v[158:159] op_sel_hi:[0,1,1]
	v_add_f32_e32 v171, v191, v170
	s_waitcnt lgkmcnt(3)
	v_mul_f32_e32 v170, v47, v175
	s_waitcnt lgkmcnt(1)
	v_mul_f32_e32 v47, v47, v183
	v_pk_fma_f32 v[156:157], v[98:99], v[48:49], v[156:157] op_sel_hi:[0,1,1]
	v_fmac_f32_e32 v47, v46, v182
	v_pk_fma_f32 v[158:159], v[130:131], v[78:79], v[158:159] op_sel_hi:[0,1,1]
	v_pk_fma_f32 v[156:157], v[130:131], v[80:81], v[156:157] op_sel_hi:[0,1,1]
	v_fmac_f32_e32 v170, v46, v174
	v_fmac_f32_e32 v47, v48, v184
	v_fmac_f32_e32 v170, v48, v176
	v_pk_fma_f32 v[156:157], v[128:129], v[180:181], v[156:157] op_sel_hi:[0,1,1]
	v_pk_fma_f32 v[158:159], v[128:129], v[178:179], v[158:159] op_sel_hi:[0,1,1]
	v_fmac_f32_e32 v47, v49, v185
	v_fmac_f32_e32 v170, v49, v177
	v_add_f32_e32 v169, v169, v47
	s_waitcnt lgkmcnt(0)
	v_pk_fma_f32 v[46:47], v[126:127], v[186:187], v[158:159] op_sel_hi:[0,1,1]
	v_pk_fma_f32 v[48:49], v[126:127], v[188:189], v[156:157] op_sel_hi:[0,1,1]
	global_store_dwordx4 v[134:135], v[46:49], off offset:256 nt
	s_waitcnt vmcnt(23)
	v_mul_f32_e32 v156, v43, v75
	v_fmac_f32_e32 v156, v42, v74
	v_mul_f32_e32 v46, v43, v67
	v_fmac_f32_e32 v46, v42, v66
	v_fmac_f32_e32 v46, v44, v68
	v_fmac_f32_e32 v156, v44, v76
	v_fmac_f32_e32 v46, v45, v69
	v_pk_mul_f32 v[48:49], v[124:125], v[70:71] op_sel_hi:[0,1]
	v_fmac_f32_e32 v156, v45, v77
	v_add_f32_e32 v168, v168, v46
	v_pk_mul_f32 v[46:47], v[124:125], v[72:73] op_sel_hi:[0,1]
	v_pk_fma_f32 v[48:49], v[98:99], v[42:43], v[48:49] op_sel_hi:[0,1,1]
	v_add_f32_e32 v167, v167, v156
	v_mul_f32_e32 v156, v43, v175
	v_mul_f32_e32 v43, v43, v183
	v_pk_fma_f32 v[46:47], v[98:99], v[44:45], v[46:47] op_sel_hi:[0,1,1]
	v_fmac_f32_e32 v43, v42, v182
	v_pk_fma_f32 v[46:47], v[122:123], v[80:81], v[46:47] op_sel_hi:[0,1,1]
	v_pk_fma_f32 v[48:49], v[122:123], v[78:79], v[48:49] op_sel_hi:[0,1,1]
	v_fmac_f32_e32 v156, v42, v174
	v_fmac_f32_e32 v43, v44, v184
	v_fmac_f32_e32 v156, v44, v176
	v_pk_fma_f32 v[46:47], v[120:121], v[180:181], v[46:47] op_sel_hi:[0,1,1]
	v_pk_fma_f32 v[48:49], v[120:121], v[178:179], v[48:49] op_sel_hi:[0,1,1]
	v_fmac_f32_e32 v43, v45, v185
	v_fmac_f32_e32 v156, v45, v177
	v_add_f32_e32 v165, v165, v43
	v_pk_fma_f32 v[44:45], v[118:119], v[188:189], v[46:47] op_sel_hi:[0,1,1]
	v_pk_fma_f32 v[42:43], v[118:119], v[186:187], v[48:49] op_sel_hi:[0,1,1]
	global_store_dwordx4 v[140:141], v[42:45], off offset:256 nt
	s_waitcnt vmcnt(23)
	v_mul_f32_e32 v46, v39, v75
	v_fmac_f32_e32 v46, v38, v74
	v_mul_f32_e32 v42, v39, v67
	v_fmac_f32_e32 v42, v38, v66
	v_fmac_f32_e32 v42, v40, v68
	v_fmac_f32_e32 v46, v40, v76
	v_fmac_f32_e32 v42, v41, v69
	v_pk_mul_f32 v[44:45], v[116:117], v[70:71] op_sel_hi:[0,1]
	v_fmac_f32_e32 v46, v41, v77
	v_add_f32_e32 v164, v164, v42
	v_pk_mul_f32 v[42:43], v[116:117], v[72:73] op_sel_hi:[0,1]
	v_pk_fma_f32 v[44:45], v[98:99], v[38:39], v[44:45] op_sel_hi:[0,1,1]
	v_add_f32_e32 v163, v163, v46
	v_mul_f32_e32 v46, v39, v175
	v_mul_f32_e32 v39, v39, v183
	v_pk_fma_f32 v[42:43], v[98:99], v[40:41], v[42:43] op_sel_hi:[0,1,1]
	v_fmac_f32_e32 v39, v38, v182
	v_pk_fma_f32 v[42:43], v[114:115], v[80:81], v[42:43] op_sel_hi:[0,1,1]
	v_pk_fma_f32 v[44:45], v[114:115], v[78:79], v[44:45] op_sel_hi:[0,1,1]
	v_fmac_f32_e32 v46, v38, v174
	v_fmac_f32_e32 v39, v40, v184
	v_fmac_f32_e32 v46, v40, v176
	v_pk_fma_f32 v[42:43], v[112:113], v[180:181], v[42:43] op_sel_hi:[0,1,1]
	v_pk_fma_f32 v[44:45], v[112:113], v[178:179], v[44:45] op_sel_hi:[0,1,1]
	v_fmac_f32_e32 v39, v41, v185
	v_fmac_f32_e32 v46, v41, v177
	v_add_f32_e32 v161, v161, v39
	v_pk_fma_f32 v[40:41], v[110:111], v[188:189], v[42:43] op_sel_hi:[0,1,1]
	v_pk_fma_f32 v[38:39], v[110:111], v[186:187], v[44:45] op_sel_hi:[0,1,1]
	global_store_dwordx4 v[138:139], v[38:41], off offset:256 nt
	s_waitcnt vmcnt(23)
	v_mul_f32_e32 v42, v35, v75
	v_fmac_f32_e32 v42, v34, v74
	v_mul_f32_e32 v38, v35, v67
	v_fmac_f32_e32 v38, v34, v66
	v_fmac_f32_e32 v38, v36, v68
	v_fmac_f32_e32 v42, v36, v76
	v_fmac_f32_e32 v38, v37, v69
	v_pk_mul_f32 v[40:41], v[108:109], v[70:71] op_sel_hi:[0,1]
	v_fmac_f32_e32 v42, v37, v77
	v_add_f32_e32 v159, v173, v38
	v_pk_mul_f32 v[38:39], v[108:109], v[72:73] op_sel_hi:[0,1]
	v_pk_fma_f32 v[40:41], v[98:99], v[34:35], v[40:41] op_sel_hi:[0,1,1]
	v_add_f32_e32 v158, v193, v42
	v_mul_f32_e32 v42, v35, v175
	v_mul_f32_e32 v35, v35, v183
	v_pk_fma_f32 v[38:39], v[98:99], v[36:37], v[38:39] op_sel_hi:[0,1,1]
	v_fmac_f32_e32 v35, v34, v182
	v_pk_fma_f32 v[38:39], v[106:107], v[80:81], v[38:39] op_sel_hi:[0,1,1]
	v_pk_fma_f32 v[40:41], v[106:107], v[78:79], v[40:41] op_sel_hi:[0,1,1]
	v_fmac_f32_e32 v42, v34, v174
	v_fmac_f32_e32 v35, v36, v184
	v_fmac_f32_e32 v42, v36, v176
	v_pk_fma_f32 v[38:39], v[104:105], v[180:181], v[38:39] op_sel_hi:[0,1,1]
	v_pk_fma_f32 v[40:41], v[104:105], v[178:179], v[40:41] op_sel_hi:[0,1,1]
	v_fmac_f32_e32 v35, v37, v185
	v_add_f32_e32 v166, v166, v156
	v_fmac_f32_e32 v42, v37, v177
	v_add_f32_e32 v156, v195, v35
	v_pk_fma_f32 v[36:37], v[0:1], v[188:189], v[38:39] op_sel_hi:[0,1,1]
	v_pk_fma_f32 v[34:35], v[0:1], v[186:187], v[40:41] op_sel_hi:[0,1,1]
	global_store_dwordx4 v[136:137], v[34:37], off offset:256 nt
	v_add_f32_e32 v162, v162, v46
	v_add_f32_e32 v157, v194, v42
	ds_read_b128 v[34:37], v123 offset:384
	ds_read_b128 v[38:41], v123 offset:4480
	ds_read_b128 v[42:45], v123 offset:1408
	ds_read_b128 v[46:49], v123 offset:5504
	ds_read_b128 v[66:69], v123 offset:2432
	ds_read_b128 v[70:73], v123 offset:6528
	ds_read_b128 v[74:77], v123 offset:3456
	ds_read_b128 v[78:81], v123 offset:7552
	s_waitcnt vmcnt(23) lgkmcnt(5)
; #define LAS __attribute__((address_space(3)))
; __device__ __forceinline__ void mlstm_sample_unit(const Frame& F, int b, int h) {
;     ...
;     for (int hh = 0; hh < 4; ++hh) {
;         if (hh < 3) {
; #pragma unroll
;             for (int i2 = 0; i2 < 2; ++i2)
; #pragma unroll
;                 for (int rg = 0; rg < 4; ++rg) c[(hh + 1) & 1][i2][rg] = __builtin_nontemporal_load((const f32x4*)(c0b + rg * 2048 + ((hh + 1) * 2 + i2) * 32)); }
; #pragma unroll
;         for (int i2 = 0; i2 < 2; ++i2) { const int it = hh * 2 + i2; const int d = it * 32 + seg * 4;
;             f32x4 q[4], k[4];
; #pragma unroll
;             for (int t = 0; t < 4; ++t) { q[t] = *(const LAS f32x4*)(sq + t * 256 + d); k[t] = *(const LAS f32x4*)(sk + t * 256 + d); }
; #pragma unroll
;             for (int rg = 0; rg < 4; ++rg) { const f32x4 cv = c[hh & 1][i2][rg]; f32x4 nv = cv * decay;
; #pragma unroll
;                 for (int t = 0; t < 4; ++t) { acc[rg][t] += cv[0] * q[t][0] + cv[1] * q[t][1] + cv[2] * q[t][2] + cv[3] * q[t][3]; nv += k[t] * gv[rg][t]; }
;                 __builtin_nontemporal_store(nv, (f32x4*)(c1b + rg * 2048 + it * 32)); } }
;     }
	v_mul_f32_e32 v176, v15, v43
	v_mul_f32_e32 v173, v15, v35
	v_fmac_f32_e32 v176, v14, v42
	v_fmac_f32_e32 v173, v14, v34
	v_fmac_f32_e32 v176, v16, v44
	v_fmac_f32_e32 v173, v16, v36
	v_fmac_f32_e32 v176, v17, v45
	v_fmac_f32_e32 v173, v17, v37
	v_pk_mul_f32 v[174:175], v[132:133], v[38:39] op_sel_hi:[0,1]
	v_add_f32_e32 v183, v171, v176
	s_waitcnt lgkmcnt(3)
	v_mul_f32_e32 v171, v15, v67
	v_add_f32_e32 v182, v172, v173
	v_pk_mul_f32 v[172:173], v[132:133], v[40:41] op_sel_hi:[0,1]
	v_pk_fma_f32 v[174:175], v[98:99], v[14:15], v[174:175] op_sel_hi:[0,1,1]
	v_fmac_f32_e32 v171, v14, v66
	s_waitcnt lgkmcnt(1)
	v_mul_f32_e32 v15, v15, v75
	v_pk_fma_f32 v[172:173], v[98:99], v[16:17], v[172:173] op_sel_hi:[0,1,1]
	v_fmac_f32_e32 v171, v16, v68
	v_fmac_f32_e32 v15, v14, v74
	v_add_f32_e32 v170, v192, v170
	v_pk_fma_f32 v[174:175], v[130:131], v[46:47], v[174:175] op_sel_hi:[0,1,1]
	v_pk_fma_f32 v[172:173], v[130:131], v[48:49], v[172:173] op_sel_hi:[0,1,1]
	v_fmac_f32_e32 v171, v17, v69
	v_fmac_f32_e32 v15, v16, v76
	v_add_f32_e32 v184, v170, v171
	v_pk_fma_f32 v[170:171], v[128:129], v[72:73], v[172:173] op_sel_hi:[0,1,1]
	v_pk_fma_f32 v[172:173], v[128:129], v[70:71], v[174:175] op_sel_hi:[0,1,1]
	v_fmac_f32_e32 v15, v17, v77
	v_add_f32_e32 v185, v169, v15
	s_waitcnt lgkmcnt(0)
	v_pk_fma_f32 v[14:15], v[126:127], v[78:79], v[172:173] op_sel_hi:[0,1,1]
	v_pk_fma_f32 v[16:17], v[126:127], v[80:81], v[170:171] op_sel_hi:[0,1,1]
	global_store_dwordx4 v[134:135], v[14:17], off offset:384 nt
	s_waitcnt vmcnt(23)
	s_nop 0
	v_mul_f32_e32 v14, v11, v35
	v_fmac_f32_e32 v14, v10, v34
	v_fmac_f32_e32 v14, v12, v36
	v_fmac_f32_e32 v14, v13, v37
	v_add_f32_e32 v186, v168, v14
	v_mul_f32_e32 v168, v11, v43
	v_fmac_f32_e32 v168, v10, v42
	v_fmac_f32_e32 v168, v12, v44
	v_pk_mul_f32 v[16:17], v[124:125], v[38:39] op_sel_hi:[0,1]
	v_fmac_f32_e32 v168, v13, v45
	v_pk_mul_f32 v[14:15], v[124:125], v[40:41] op_sel_hi:[0,1]
	v_pk_fma_f32 v[16:17], v[98:99], v[10:11], v[16:17] op_sel_hi:[0,1,1]
	v_add_f32_e32 v187, v167, v168
	v_mul_f32_e32 v167, v11, v67
	v_mul_f32_e32 v11, v11, v75
	v_pk_fma_f32 v[14:15], v[98:99], v[12:13], v[14:15] op_sel_hi:[0,1,1]
	v_fmac_f32_e32 v11, v10, v74
	v_pk_fma_f32 v[14:15], v[122:123], v[48:49], v[14:15] op_sel_hi:[0,1,1]
	v_pk_fma_f32 v[16:17], v[122:123], v[46:47], v[16:17] op_sel_hi:[0,1,1]
	v_fmac_f32_e32 v167, v10, v66
	v_fmac_f32_e32 v11, v12, v76
	v_fmac_f32_e32 v167, v12, v68
	v_pk_fma_f32 v[14:15], v[120:121], v[72:73], v[14:15] op_sel_hi:[0,1,1]
	v_pk_fma_f32 v[16:17], v[120:121], v[70:71], v[16:17] op_sel_hi:[0,1,1]
	v_fmac_f32_e32 v11, v13, v77
	v_fmac_f32_e32 v167, v13, v69
	v_add_f32_e32 v165, v165, v11
	v_pk_fma_f32 v[12:13], v[118:119], v[80:81], v[14:15] op_sel_hi:[0,1,1]
	v_pk_fma_f32 v[10:11], v[118:119], v[78:79], v[16:17] op_sel_hi:[0,1,1]
	global_store_dwordx4 v[140:141], v[10:13], off offset:384 nt
	s_waitcnt vmcnt(23)
	v_mul_f32_e32 v14, v7, v43
	v_fmac_f32_e32 v14, v6, v42
	v_mul_f32_e32 v10, v7, v35
	v_fmac_f32_e32 v10, v6, v34
	v_fmac_f32_e32 v10, v8, v36
	v_fmac_f32_e32 v14, v8, v44
	v_fmac_f32_e32 v10, v9, v37
	v_pk_mul_f32 v[12:13], v[116:117], v[38:39] op_sel_hi:[0,1]
	v_fmac_f32_e32 v14, v9, v45
	v_add_f32_e32 v189, v164, v10
	v_pk_mul_f32 v[10:11], v[116:117], v[40:41] op_sel_hi:[0,1]
	v_pk_fma_f32 v[12:13], v[98:99], v[6:7], v[12:13] op_sel_hi:[0,1,1]
	v_add_f32_e32 v190, v163, v14
	v_mul_f32_e32 v14, v7, v67
	v_mul_f32_e32 v7, v7, v75
	v_pk_fma_f32 v[10:11], v[98:99], v[8:9], v[10:11] op_sel_hi:[0,1,1]
	v_fmac_f32_e32 v7, v6, v74
	v_pk_fma_f32 v[10:11], v[114:115], v[48:49], v[10:11] op_sel_hi:[0,1,1]
	v_pk_fma_f32 v[12:13], v[114:115], v[46:47], v[12:13] op_sel_hi:[0,1,1]
	v_fmac_f32_e32 v14, v6, v66
	v_fmac_f32_e32 v7, v8, v76
	v_fmac_f32_e32 v14, v8, v68
	v_pk_fma_f32 v[10:11], v[112:113], v[72:73], v[10:11] op_sel_hi:[0,1,1]
	v_pk_fma_f32 v[12:13], v[112:113], v[70:71], v[12:13] op_sel_hi:[0,1,1]
	v_fmac_f32_e32 v7, v9, v77
	v_fmac_f32_e32 v14, v9, v69
	v_add_f32_e32 v192, v161, v7
	v_pk_fma_f32 v[8:9], v[110:111], v[80:81], v[10:11] op_sel_hi:[0,1,1]
	v_pk_fma_f32 v[6:7], v[110:111], v[78:79], v[12:13] op_sel_hi:[0,1,1]
	global_store_dwordx4 v[138:139], v[6:9], off offset:384 nt
	s_waitcnt vmcnt(23)
	v_mul_f32_e32 v10, v3, v43
	v_fmac_f32_e32 v10, v2, v42
	v_mul_f32_e32 v6, v3, v35
	v_fmac_f32_e32 v6, v2, v34
	v_fmac_f32_e32 v6, v4, v36
	v_fmac_f32_e32 v10, v4, v44
	v_fmac_f32_e32 v6, v5, v37
	v_pk_mul_f32 v[8:9], v[108:109], v[38:39] op_sel_hi:[0,1]
	v_fmac_f32_e32 v10, v5, v45
	v_add_f32_e32 v193, v159, v6
	v_pk_mul_f32 v[6:7], v[108:109], v[40:41] op_sel_hi:[0,1]
	v_pk_fma_f32 v[8:9], v[98:99], v[2:3], v[8:9] op_sel_hi:[0,1,1]
	v_add_f32_e32 v194, v158, v10
	v_mul_f32_e32 v10, v3, v67
	v_mul_f32_e32 v3, v3, v75
	v_pk_fma_f32 v[6:7], v[98:99], v[4:5], v[6:7] op_sel_hi:[0,1,1]
	v_fmac_f32_e32 v3, v2, v74
	v_pk_fma_f32 v[6:7], v[106:107], v[48:49], v[6:7] op_sel_hi:[0,1,1]
	v_pk_fma_f32 v[8:9], v[106:107], v[46:47], v[8:9] op_sel_hi:[0,1,1]
	v_fmac_f32_e32 v10, v2, v66
	v_fmac_f32_e32 v3, v4, v76
	v_fmac_f32_e32 v10, v4, v68
	v_pk_fma_f32 v[6:7], v[104:105], v[72:73], v[6:7] op_sel_hi:[0,1,1]
	v_pk_fma_f32 v[8:9], v[104:105], v[70:71], v[8:9] op_sel_hi:[0,1,1]
	v_fmac_f32_e32 v3, v5, v77
	v_fmac_f32_e32 v10, v5, v69
	v_add_f32_e32 v196, v156, v3
	v_pk_fma_f32 v[4:5], v[0:1], v[80:81], v[6:7] op_sel_hi:[0,1,1]
	v_pk_fma_f32 v[2:3], v[0:1], v[78:79], v[8:9] op_sel_hi:[0,1,1]
	global_store_dwordx4 v[136:137], v[2:5], off offset:384 nt
	v_add_f32_e32 v188, v166, v167
	v_add_f32_e32 v191, v162, v14
	v_add_f32_e32 v195, v157, v10
	global_load_dwordx4 v[46:49], v[142:143], off offset:768 nt
	global_load_dwordx4 v[42:45], v[148:149], off offset:768 nt
	global_load_dwordx4 v[38:41], v[152:153], off offset:768 nt
	global_load_dwordx4 v[34:37], v[150:151], off offset:768 nt
	global_load_dwordx4 v[14:17], v[142:143], off offset:896 nt
	global_load_dwordx4 v[10:13], v[148:149], off offset:896 nt
	global_load_dwordx4 v[6:9], v[152:153], off offset:896 nt
	global_load_dwordx4 v[2:5], v[150:151], off offset:896 nt
	ds_read_b128 v[66:69], v123 offset:512
	ds_read_b128 v[70:73], v123 offset:4608
	ds_read_b128 v[74:77], v123 offset:1536
	ds_read_b128 v[78:81], v123 offset:5632
	ds_read_b128 v[166:169], v123 offset:2560
	ds_read_b128 v[170:173], v123 offset:6656
	ds_read_b128 v[174:177], v123 offset:3584
	ds_read_b128 v[178:181], v123 offset:7680
	s_waitcnt vmcnt(23) lgkmcnt(7)
; #define LAS __attribute__((address_space(3)))
; __device__ __forceinline__ void mlstm_sample_unit(const Frame& F, int b, int h) {
;     ...
;     for (int hh = 0; hh < 4; ++hh) {
;         if (hh < 3) {
; #pragma unroll
;             for (int i2 = 0; i2 < 2; ++i2)
; #pragma unroll
;                 for (int rg = 0; rg < 4; ++rg) c[(hh + 1) & 1][i2][rg] = __builtin_nontemporal_load((const f32x4*)(c0b + rg * 2048 + ((hh + 1) * 2 + i2) * 32)); }
; #pragma unroll
;         for (int i2 = 0; i2 < 2; ++i2) { const int it = hh * 2 + i2; const int d = it * 32 + seg * 4;
;             f32x4 q[4], k[4];
; #pragma unroll
;             for (int t = 0; t < 4; ++t) { q[t] = *(const LAS f32x4*)(sq + t * 256 + d); k[t] = *(const LAS f32x4*)(sk + t * 256 + d); }
; #pragma unroll
;             for (int rg = 0; rg < 4; ++rg) { const f32x4 cv = c[hh & 1][i2][rg]; f32x4 nv = cv * decay;
; #pragma unroll
;                 for (int t = 0; t < 4; ++t) { acc[rg][t] += cv[0] * q[t][0] + cv[1] * q[t][1] + cv[2] * q[t][2] + cv[3] * q[t][3]; nv += k[t] * gv[rg][t]; }
;                 __builtin_nontemporal_store(nv, (f32x4*)(c1b + rg * 2048 + it * 32)); } }
;     }
	v_mul_f32_e32 v142, v63, v67
	s_waitcnt lgkmcnt(5)
	v_mul_f32_e32 v150, v63, v75
	v_fmac_f32_e32 v142, v62, v66
	v_fmac_f32_e32 v150, v62, v74
	v_fmac_f32_e32 v142, v64, v68
	v_fmac_f32_e32 v150, v64, v76
	v_fmac_f32_e32 v142, v65, v69
	v_pk_mul_f32 v[148:149], v[132:133], v[70:71] op_sel_hi:[0,1]
	v_fmac_f32_e32 v150, v65, v77
	v_add_f32_e32 v164, v182, v142
	v_pk_mul_f32 v[142:143], v[132:133], v[72:73] op_sel_hi:[0,1]
	v_pk_fma_f32 v[148:149], v[98:99], v[62:63], v[148:149] op_sel_hi:[0,1,1]
	v_add_f32_e32 v163, v183, v150
	s_waitcnt lgkmcnt(3)
	v_mul_f32_e32 v150, v63, v167
	s_waitcnt lgkmcnt(1)
	v_mul_f32_e32 v63, v63, v175
	v_pk_fma_f32 v[142:143], v[98:99], v[64:65], v[142:143] op_sel_hi:[0,1,1]
	v_fmac_f32_e32 v63, v62, v174
	v_pk_fma_f32 v[148:149], v[130:131], v[78:79], v[148:149] op_sel_hi:[0,1,1]
	v_pk_fma_f32 v[142:143], v[130:131], v[80:81], v[142:143] op_sel_hi:[0,1,1]
	v_fmac_f32_e32 v150, v62, v166
	v_fmac_f32_e32 v63, v64, v176
	v_fmac_f32_e32 v150, v64, v168
	v_pk_fma_f32 v[142:143], v[128:129], v[172:173], v[142:143] op_sel_hi:[0,1,1]
	v_pk_fma_f32 v[148:149], v[128:129], v[170:171], v[148:149] op_sel_hi:[0,1,1]
	v_fmac_f32_e32 v63, v65, v177
	v_fmac_f32_e32 v150, v65, v169
	v_add_f32_e32 v161, v185, v63
	s_waitcnt lgkmcnt(0)
	v_pk_fma_f32 v[62:63], v[126:127], v[178:179], v[148:149] op_sel_hi:[0,1,1]
	v_pk_fma_f32 v[64:65], v[126:127], v[180:181], v[142:143] op_sel_hi:[0,1,1]
	global_store_dwordx4 v[134:135], v[62:65], off offset:512 nt
	s_waitcnt vmcnt(23)
	v_mul_f32_e32 v142, v59, v75
	v_fmac_f32_e32 v142, v58, v74
	v_mul_f32_e32 v62, v59, v67
	v_fmac_f32_e32 v62, v58, v66
	v_fmac_f32_e32 v62, v60, v68
	v_fmac_f32_e32 v142, v60, v76
	v_fmac_f32_e32 v62, v61, v69
	v_pk_mul_f32 v[64:65], v[124:125], v[70:71] op_sel_hi:[0,1]
	v_fmac_f32_e32 v142, v61, v77
	v_add_f32_e32 v159, v186, v62
	v_pk_mul_f32 v[62:63], v[124:125], v[72:73] op_sel_hi:[0,1]
	v_pk_fma_f32 v[64:65], v[98:99], v[58:59], v[64:65] op_sel_hi:[0,1,1]
	v_add_f32_e32 v158, v187, v142
	v_mul_f32_e32 v142, v59, v167
	v_mul_f32_e32 v59, v59, v175
	v_pk_fma_f32 v[62:63], v[98:99], v[60:61], v[62:63] op_sel_hi:[0,1,1]
	v_fmac_f32_e32 v59, v58, v174
	v_pk_fma_f32 v[62:63], v[122:123], v[80:81], v[62:63] op_sel_hi:[0,1,1]
	v_pk_fma_f32 v[64:65], v[122:123], v[78:79], v[64:65] op_sel_hi:[0,1,1]
	v_fmac_f32_e32 v142, v58, v166
	v_fmac_f32_e32 v59, v60, v176
	v_fmac_f32_e32 v142, v60, v168
	v_pk_fma_f32 v[62:63], v[120:121], v[172:173], v[62:63] op_sel_hi:[0,1,1]
	v_pk_fma_f32 v[64:65], v[120:121], v[170:171], v[64:65] op_sel_hi:[0,1,1]
	v_fmac_f32_e32 v59, v61, v177
	v_fmac_f32_e32 v142, v61, v169
	v_add_f32_e32 v156, v165, v59
	v_pk_fma_f32 v[60:61], v[118:119], v[180:181], v[62:63] op_sel_hi:[0,1,1]
	v_pk_fma_f32 v[58:59], v[118:119], v[178:179], v[64:65] op_sel_hi:[0,1,1]
	global_store_dwordx4 v[140:141], v[58:61], off offset:512 nt
	s_waitcnt vmcnt(23)
	v_mul_f32_e32 v62, v55, v75
	v_fmac_f32_e32 v62, v54, v74
	v_mul_f32_e32 v58, v55, v67
	v_fmac_f32_e32 v58, v54, v66
	v_fmac_f32_e32 v58, v56, v68
	v_fmac_f32_e32 v62, v56, v76
	v_fmac_f32_e32 v58, v57, v69
	v_pk_mul_f32 v[60:61], v[116:117], v[70:71] op_sel_hi:[0,1]
	v_fmac_f32_e32 v62, v57, v77
	v_add_f32_e32 v153, v189, v58
	v_pk_mul_f32 v[58:59], v[116:117], v[72:73] op_sel_hi:[0,1]
	v_pk_fma_f32 v[60:61], v[98:99], v[54:55], v[60:61] op_sel_hi:[0,1,1]
	v_add_f32_e32 v152, v190, v62
	v_mul_f32_e32 v62, v55, v167
	v_mul_f32_e32 v55, v55, v175
	v_pk_fma_f32 v[58:59], v[98:99], v[56:57], v[58:59] op_sel_hi:[0,1,1]
	v_fmac_f32_e32 v55, v54, v174
	v_pk_fma_f32 v[58:59], v[114:115], v[80:81], v[58:59] op_sel_hi:[0,1,1]
	v_pk_fma_f32 v[60:61], v[114:115], v[78:79], v[60:61] op_sel_hi:[0,1,1]
	v_fmac_f32_e32 v62, v54, v166
	v_fmac_f32_e32 v55, v56, v176
	v_fmac_f32_e32 v62, v56, v168
	v_pk_fma_f32 v[58:59], v[112:113], v[172:173], v[58:59] op_sel_hi:[0,1,1]
	v_pk_fma_f32 v[60:61], v[112:113], v[170:171], v[60:61] op_sel_hi:[0,1,1]
	v_fmac_f32_e32 v55, v57, v177
	v_add_f32_e32 v162, v184, v150
	v_fmac_f32_e32 v62, v57, v169
	v_add_f32_e32 v150, v192, v55
	v_pk_fma_f32 v[56:57], v[110:111], v[180:181], v[58:59] op_sel_hi:[0,1,1]
	v_pk_fma_f32 v[54:55], v[110:111], v[178:179], v[60:61] op_sel_hi:[0,1,1]
	global_store_dwordx4 v[138:139], v[54:57], off offset:512 nt
	s_waitcnt vmcnt(23)
	v_mul_f32_e32 v58, v51, v75
	v_fmac_f32_e32 v58, v50, v74
	v_mul_f32_e32 v54, v51, v67
	v_fmac_f32_e32 v54, v50, v66
	v_fmac_f32_e32 v54, v52, v68
	v_fmac_f32_e32 v58, v52, v76
	v_fmac_f32_e32 v54, v53, v69
	v_pk_mul_f32 v[56:57], v[108:109], v[70:71] op_sel_hi:[0,1]
	v_fmac_f32_e32 v58, v53, v77
	v_add_f32_e32 v149, v193, v54
	v_pk_mul_f32 v[54:55], v[108:109], v[72:73] op_sel_hi:[0,1]
	v_pk_fma_f32 v[56:57], v[98:99], v[50:51], v[56:57] op_sel_hi:[0,1,1]
	v_add_f32_e32 v148, v194, v58
	v_mul_f32_e32 v58, v51, v167
	v_mul_f32_e32 v51, v51, v175
	v_pk_fma_f32 v[54:55], v[98:99], v[52:53], v[54:55] op_sel_hi:[0,1,1]
	v_fmac_f32_e32 v51, v50, v174
	v_pk_fma_f32 v[54:55], v[106:107], v[80:81], v[54:55] op_sel_hi:[0,1,1]
	v_pk_fma_f32 v[56:57], v[106:107], v[78:79], v[56:57] op_sel_hi:[0,1,1]
	v_fmac_f32_e32 v58, v50, v166
	v_fmac_f32_e32 v51, v52, v176
	v_fmac_f32_e32 v58, v52, v168
	v_pk_fma_f32 v[54:55], v[104:105], v[172:173], v[54:55] op_sel_hi:[0,1,1]
	v_pk_fma_f32 v[56:57], v[104:105], v[170:171], v[56:57] op_sel_hi:[0,1,1]
	v_fmac_f32_e32 v51, v53, v177
	v_add_f32_e32 v157, v188, v142
	v_fmac_f32_e32 v58, v53, v169
	v_add_f32_e32 v142, v196, v51
	v_pk_fma_f32 v[52:53], v[0:1], v[180:181], v[54:55] op_sel_hi:[0,1,1]
	v_pk_fma_f32 v[50:51], v[0:1], v[178:179], v[56:57] op_sel_hi:[0,1,1]
	global_store_dwordx4 v[136:137], v[50:53], off offset:512 nt
	v_add_f32_e32 v151, v191, v62
	v_add_f32_e32 v143, v195, v58
	ds_read_b128 v[50:53], v123 offset:640
	ds_read_b128 v[54:57], v123 offset:4736
	ds_read_b128 v[58:61], v123 offset:1664
	ds_read_b128 v[62:65], v123 offset:5760
	ds_read_b128 v[66:69], v123 offset:2688
	ds_read_b128 v[70:73], v123 offset:6784
	ds_read_b128 v[74:77], v123 offset:3712
	ds_read_b128 v[78:81], v123 offset:7808
	s_waitcnt vmcnt(23) lgkmcnt(5)
; #define LAS __attribute__((address_space(3)))
; __device__ __forceinline__ void mlstm_sample_unit(const Frame& F, int b, int h) {
;     ...
;     for (int hh = 0; hh < 4; ++hh) {
;         if (hh < 3) {
; #pragma unroll
;             for (int i2 = 0; i2 < 2; ++i2)
; #pragma unroll
;                 for (int rg = 0; rg < 4; ++rg) c[(hh + 1) & 1][i2][rg] = __builtin_nontemporal_load((const f32x4*)(c0b + rg * 2048 + ((hh + 1) * 2 + i2) * 32)); }
; #pragma unroll
;         for (int i2 = 0; i2 < 2; ++i2) { const int it = hh * 2 + i2; const int d = it * 32 + seg * 4;
;             f32x4 q[4], k[4];
; #pragma unroll
;             for (int t = 0; t < 4; ++t) { q[t] = *(const LAS f32x4*)(sq + t * 256 + d); k[t] = *(const LAS f32x4*)(sk + t * 256 + d); }
; #pragma unroll
;             for (int rg = 0; rg < 4; ++rg) { const f32x4 cv = c[hh & 1][i2][rg]; f32x4 nv = cv * decay;
; #pragma unroll
;                 for (int t = 0; t < 4; ++t) { acc[rg][t] += cv[0] * q[t][0] + cv[1] * q[t][1] + cv[2] * q[t][2] + cv[3] * q[t][3]; nv += k[t] * gv[rg][t]; }
;                 __builtin_nontemporal_store(nv, (f32x4*)(c1b + rg * 2048 + it * 32)); } }
;     }
	v_mul_f32_e32 v169, v31, v59
	v_mul_f32_e32 v165, v31, v51
	v_fmac_f32_e32 v169, v30, v58
	v_fmac_f32_e32 v165, v30, v50
	v_fmac_f32_e32 v169, v32, v60
	v_fmac_f32_e32 v165, v32, v52
	v_fmac_f32_e32 v169, v33, v61
	v_fmac_f32_e32 v165, v33, v53
	v_pk_mul_f32 v[166:167], v[132:133], v[54:55] op_sel_hi:[0,1]
	v_add_f32_e32 v169, v163, v169
	s_waitcnt lgkmcnt(3)
	v_mul_f32_e32 v163, v31, v67
	v_add_f32_e32 v168, v164, v165
	v_pk_mul_f32 v[164:165], v[132:133], v[56:57] op_sel_hi:[0,1]
	v_pk_fma_f32 v[166:167], v[98:99], v[30:31], v[166:167] op_sel_hi:[0,1,1]
	v_fmac_f32_e32 v163, v30, v66
	s_waitcnt lgkmcnt(1)
	v_mul_f32_e32 v31, v31, v75
	v_pk_fma_f32 v[164:165], v[98:99], v[32:33], v[164:165] op_sel_hi:[0,1,1]
	v_fmac_f32_e32 v163, v32, v68
	v_fmac_f32_e32 v31, v30, v74
	v_pk_fma_f32 v[166:167], v[130:131], v[62:63], v[166:167] op_sel_hi:[0,1,1]
	v_pk_fma_f32 v[164:165], v[130:131], v[64:65], v[164:165] op_sel_hi:[0,1,1]
	v_fmac_f32_e32 v163, v33, v69
	v_fmac_f32_e32 v31, v32, v76
	v_add_f32_e32 v170, v162, v163
	v_pk_fma_f32 v[162:163], v[128:129], v[72:73], v[164:165] op_sel_hi:[0,1,1]
	v_pk_fma_f32 v[164:165], v[128:129], v[70:71], v[166:167] op_sel_hi:[0,1,1]
	v_fmac_f32_e32 v31, v33, v77
	v_add_f32_e32 v161, v161, v31
	s_waitcnt lgkmcnt(0)
	v_pk_fma_f32 v[30:31], v[126:127], v[78:79], v[164:165] op_sel_hi:[0,1,1]
	v_pk_fma_f32 v[32:33], v[126:127], v[80:81], v[162:163] op_sel_hi:[0,1,1]
	global_store_dwordx4 v[134:135], v[30:33], off offset:640 nt
	s_waitcnt vmcnt(23)
	v_mul_f32_e32 v162, v27, v59
	v_fmac_f32_e32 v162, v26, v58
	v_mul_f32_e32 v30, v27, v51
	v_fmac_f32_e32 v30, v26, v50
	v_fmac_f32_e32 v30, v28, v52
	v_fmac_f32_e32 v162, v28, v60
	v_fmac_f32_e32 v30, v29, v53
	v_pk_mul_f32 v[32:33], v[124:125], v[54:55] op_sel_hi:[0,1]
	v_fmac_f32_e32 v162, v29, v61
	v_add_f32_e32 v159, v159, v30
	v_pk_mul_f32 v[30:31], v[124:125], v[56:57] op_sel_hi:[0,1]
	v_pk_fma_f32 v[32:33], v[98:99], v[26:27], v[32:33] op_sel_hi:[0,1,1]
	v_add_f32_e32 v158, v158, v162
	v_mul_f32_e32 v162, v27, v67
	v_mul_f32_e32 v27, v27, v75
	v_pk_fma_f32 v[30:31], v[98:99], v[28:29], v[30:31] op_sel_hi:[0,1,1]
	v_fmac_f32_e32 v27, v26, v74
	v_pk_fma_f32 v[30:31], v[122:123], v[64:65], v[30:31] op_sel_hi:[0,1,1]
	v_pk_fma_f32 v[32:33], v[122:123], v[62:63], v[32:33] op_sel_hi:[0,1,1]
	v_fmac_f32_e32 v162, v26, v66
	v_fmac_f32_e32 v27, v28, v76
	v_fmac_f32_e32 v162, v28, v68
	v_pk_fma_f32 v[30:31], v[120:121], v[72:73], v[30:31] op_sel_hi:[0,1,1]
	v_pk_fma_f32 v[32:33], v[120:121], v[70:71], v[32:33] op_sel_hi:[0,1,1]
	v_fmac_f32_e32 v27, v29, v77
	v_fmac_f32_e32 v162, v29, v69
	v_add_f32_e32 v156, v156, v27
	v_pk_fma_f32 v[28:29], v[118:119], v[80:81], v[30:31] op_sel_hi:[0,1,1]
	v_pk_fma_f32 v[26:27], v[118:119], v[78:79], v[32:33] op_sel_hi:[0,1,1]
	global_store_dwordx4 v[140:141], v[26:29], off offset:640 nt
	s_waitcnt vmcnt(23)
	v_mul_f32_e32 v30, v23, v59
	v_fmac_f32_e32 v30, v22, v58
	v_mul_f32_e32 v26, v23, v51
	v_fmac_f32_e32 v26, v22, v50
	v_fmac_f32_e32 v26, v24, v52
	v_fmac_f32_e32 v30, v24, v60
	v_fmac_f32_e32 v26, v25, v53
	v_pk_mul_f32 v[28:29], v[116:117], v[54:55] op_sel_hi:[0,1]
	v_fmac_f32_e32 v30, v25, v61
	v_add_f32_e32 v153, v153, v26
	v_pk_mul_f32 v[26:27], v[116:117], v[56:57] op_sel_hi:[0,1]
	v_pk_fma_f32 v[28:29], v[98:99], v[22:23], v[28:29] op_sel_hi:[0,1,1]
	v_add_f32_e32 v152, v152, v30
	v_mul_f32_e32 v30, v23, v67
	v_mul_f32_e32 v23, v23, v75
	v_pk_fma_f32 v[26:27], v[98:99], v[24:25], v[26:27] op_sel_hi:[0,1,1]
	v_fmac_f32_e32 v23, v22, v74
	v_pk_fma_f32 v[26:27], v[114:115], v[64:65], v[26:27] op_sel_hi:[0,1,1]
	v_pk_fma_f32 v[28:29], v[114:115], v[62:63], v[28:29] op_sel_hi:[0,1,1]
	v_fmac_f32_e32 v30, v22, v66
	v_fmac_f32_e32 v23, v24, v76
	v_fmac_f32_e32 v30, v24, v68
	v_pk_fma_f32 v[26:27], v[112:113], v[72:73], v[26:27] op_sel_hi:[0,1,1]
	v_pk_fma_f32 v[28:29], v[112:113], v[70:71], v[28:29] op_sel_hi:[0,1,1]
	v_fmac_f32_e32 v23, v25, v77
	v_fmac_f32_e32 v30, v25, v69
	v_add_f32_e32 v150, v150, v23
	v_pk_fma_f32 v[24:25], v[110:111], v[80:81], v[26:27] op_sel_hi:[0,1,1]
	v_pk_fma_f32 v[22:23], v[110:111], v[78:79], v[28:29] op_sel_hi:[0,1,1]
	global_store_dwordx4 v[138:139], v[22:25], off offset:640 nt
	s_waitcnt vmcnt(23)
	v_mul_f32_e32 v26, v19, v59
	v_fmac_f32_e32 v26, v18, v58
	v_mul_f32_e32 v22, v19, v51
	v_fmac_f32_e32 v22, v18, v50
	v_fmac_f32_e32 v22, v20, v52
	v_fmac_f32_e32 v26, v20, v60
	v_fmac_f32_e32 v22, v21, v53
	v_pk_mul_f32 v[24:25], v[108:109], v[54:55] op_sel_hi:[0,1]
	v_fmac_f32_e32 v26, v21, v61
	v_add_f32_e32 v149, v149, v22
	v_pk_mul_f32 v[22:23], v[108:109], v[56:57] op_sel_hi:[0,1]
	v_pk_fma_f32 v[24:25], v[98:99], v[18:19], v[24:25] op_sel_hi:[0,1,1]
	v_add_f32_e32 v59, v148, v26
	v_mul_f32_e32 v26, v19, v67
	v_mul_f32_e32 v19, v19, v75
	v_pk_fma_f32 v[22:23], v[98:99], v[20:21], v[22:23] op_sel_hi:[0,1,1]
	v_fmac_f32_e32 v19, v18, v74
	v_pk_fma_f32 v[22:23], v[106:107], v[64:65], v[22:23] op_sel_hi:[0,1,1]
	v_pk_fma_f32 v[24:25], v[106:107], v[62:63], v[24:25] op_sel_hi:[0,1,1]
	v_fmac_f32_e32 v26, v18, v66
	v_fmac_f32_e32 v19, v20, v76
	v_fmac_f32_e32 v26, v20, v68
	v_pk_fma_f32 v[22:23], v[104:105], v[72:73], v[22:23] op_sel_hi:[0,1,1]
	v_pk_fma_f32 v[24:25], v[104:105], v[70:71], v[24:25] op_sel_hi:[0,1,1]
	v_fmac_f32_e32 v19, v21, v77
	v_fmac_f32_e32 v26, v21, v69
	v_add_f32_e32 v142, v142, v19
	v_pk_fma_f32 v[20:21], v[0:1], v[80:81], v[22:23] op_sel_hi:[0,1,1]
	v_pk_fma_f32 v[18:19], v[0:1], v[78:79], v[24:25] op_sel_hi:[0,1,1]
	global_store_dwordx4 v[136:137], v[18:21], off offset:640 nt
	v_add_f32_e32 v151, v151, v30
	v_add_f32_e32 v143, v143, v26
	ds_read_b128 v[18:21], v123 offset:768
	ds_read_b128 v[22:25], v123 offset:4864
	ds_read_b128 v[26:29], v123 offset:1792
	ds_read_b128 v[30:33], v123 offset:5888
	ds_read_b128 v[66:69], v123 offset:2816
	ds_read_b128 v[70:73], v123 offset:6912
	ds_read_b128 v[74:77], v123 offset:3840
	ds_read_b128 v[78:81], v123 offset:7936
	s_waitcnt vmcnt(15) lgkmcnt(7)
; #define LAS __attribute__((address_space(3)))
; __device__ __forceinline__ void mlstm_sample_unit(const Frame& F, int b, int h) {
;     ...
;     for (int hh = 0; hh < 4; ++hh) {
;         if (hh < 3) {
; #pragma unroll
;             for (int i2 = 0; i2 < 2; ++i2)
; #pragma unroll
;                 for (int rg = 0; rg < 4; ++rg) c[(hh + 1) & 1][i2][rg] = __builtin_nontemporal_load((const f32x4*)(c0b + rg * 2048 + ((hh + 1) * 2 + i2) * 32)); }
; #pragma unroll
;         for (int i2 = 0; i2 < 2; ++i2) { const int it = hh * 2 + i2; const int d = it * 32 + seg * 4;
;             f32x4 q[4], k[4];
; #pragma unroll
;             for (int t = 0; t < 4; ++t) { q[t] = *(const LAS f32x4*)(sq + t * 256 + d); k[t] = *(const LAS f32x4*)(sk + t * 256 + d); }
; #pragma unroll
;             for (int rg = 0; rg < 4; ++rg) { const f32x4 cv = c[hh & 1][i2][rg]; f32x4 nv = cv * decay;
; #pragma unroll
;                 for (int t = 0; t < 4; ++t) { acc[rg][t] += cv[0] * q[t][0] + cv[1] * q[t][1] + cv[2] * q[t][2] + cv[3] * q[t][3]; nv += k[t] * gv[rg][t]; }
;                 __builtin_nontemporal_store(nv, (f32x4*)(c1b + rg * 2048 + it * 32)); } }
;     }
	v_mul_f32_e32 v50, v47, v19
	s_waitcnt lgkmcnt(5)
	v_mul_f32_e32 v54, v47, v27
	v_fmac_f32_e32 v50, v46, v18
	v_fmac_f32_e32 v54, v46, v26
	v_fmac_f32_e32 v50, v48, v20
	v_fmac_f32_e32 v54, v48, v28
	v_fmac_f32_e32 v50, v49, v21
	v_pk_mul_f32 v[52:53], v[132:133], v[22:23] op_sel_hi:[0,1]
	v_fmac_f32_e32 v54, v49, v29
	v_add_f32_e32 v65, v168, v50
	v_pk_mul_f32 v[50:51], v[132:133], v[24:25] op_sel_hi:[0,1]
	v_pk_fma_f32 v[52:53], v[98:99], v[46:47], v[52:53] op_sel_hi:[0,1,1]
	v_add_f32_e32 v64, v169, v54
	s_waitcnt lgkmcnt(3)
	v_mul_f32_e32 v54, v47, v67
	s_waitcnt lgkmcnt(1)
	v_mul_f32_e32 v47, v47, v75
	v_pk_fma_f32 v[50:51], v[98:99], v[48:49], v[50:51] op_sel_hi:[0,1,1]
	v_fmac_f32_e32 v47, v46, v74
	v_pk_fma_f32 v[52:53], v[130:131], v[30:31], v[52:53] op_sel_hi:[0,1,1]
	v_pk_fma_f32 v[50:51], v[130:131], v[32:33], v[50:51] op_sel_hi:[0,1,1]
	v_fmac_f32_e32 v54, v46, v66
	v_fmac_f32_e32 v47, v48, v76
	v_fmac_f32_e32 v54, v48, v68
	v_pk_fma_f32 v[50:51], v[128:129], v[72:73], v[50:51] op_sel_hi:[0,1,1]
	v_pk_fma_f32 v[52:53], v[128:129], v[70:71], v[52:53] op_sel_hi:[0,1,1]
	v_fmac_f32_e32 v47, v49, v77
	v_fmac_f32_e32 v54, v49, v69
	v_add_f32_e32 v62, v161, v47
	s_waitcnt lgkmcnt(0)
	v_pk_fma_f32 v[46:47], v[126:127], v[78:79], v[52:53] op_sel_hi:[0,1,1]
	v_pk_fma_f32 v[48:49], v[126:127], v[80:81], v[50:51] op_sel_hi:[0,1,1]
	global_store_dwordx4 v[134:135], v[46:49], off offset:768 nt
	s_waitcnt vmcnt(15)
	v_mul_f32_e32 v50, v43, v27
	v_fmac_f32_e32 v50, v42, v26
	v_mul_f32_e32 v46, v43, v19
	v_fmac_f32_e32 v46, v42, v18
	v_fmac_f32_e32 v46, v44, v20
	v_fmac_f32_e32 v50, v44, v28
	v_fmac_f32_e32 v46, v45, v21
	v_pk_mul_f32 v[48:49], v[124:125], v[22:23] op_sel_hi:[0,1]
	v_fmac_f32_e32 v50, v45, v29
	v_add_f32_e32 v61, v159, v46
	v_pk_mul_f32 v[46:47], v[124:125], v[24:25] op_sel_hi:[0,1]
	v_pk_fma_f32 v[48:49], v[98:99], v[42:43], v[48:49] op_sel_hi:[0,1,1]
	v_add_f32_e32 v60, v158, v50
	v_mul_f32_e32 v50, v43, v67
	v_mul_f32_e32 v43, v43, v75
	v_pk_fma_f32 v[46:47], v[98:99], v[44:45], v[46:47] op_sel_hi:[0,1,1]
	v_fmac_f32_e32 v43, v42, v74
	v_pk_fma_f32 v[46:47], v[122:123], v[32:33], v[46:47] op_sel_hi:[0,1,1]
	v_pk_fma_f32 v[48:49], v[122:123], v[30:31], v[48:49] op_sel_hi:[0,1,1]
	v_fmac_f32_e32 v50, v42, v66
	v_fmac_f32_e32 v43, v44, v76
	v_fmac_f32_e32 v50, v44, v68
	v_pk_fma_f32 v[46:47], v[120:121], v[72:73], v[46:47] op_sel_hi:[0,1,1]
	v_pk_fma_f32 v[48:49], v[120:121], v[70:71], v[48:49] op_sel_hi:[0,1,1]
	v_fmac_f32_e32 v43, v45, v77
	v_fmac_f32_e32 v50, v45, v69
	v_add_f32_e32 v57, v156, v43
	v_pk_fma_f32 v[44:45], v[118:119], v[80:81], v[46:47] op_sel_hi:[0,1,1]
	v_pk_fma_f32 v[42:43], v[118:119], v[78:79], v[48:49] op_sel_hi:[0,1,1]
	global_store_dwordx4 v[140:141], v[42:45], off offset:768 nt
	s_waitcnt vmcnt(15)
	v_mul_f32_e32 v46, v39, v27
	v_fmac_f32_e32 v46, v38, v26
	v_mul_f32_e32 v42, v39, v19
	s_waitcnt vmcnt(14)
	v_mul_f32_e32 v19, v35, v19
	v_fmac_f32_e32 v42, v38, v18
	v_fmac_f32_e32 v19, v34, v18
	v_fmac_f32_e32 v42, v40, v20
	v_fmac_f32_e32 v19, v36, v20
	v_fmac_f32_e32 v42, v41, v21
	v_pk_mul_f32 v[44:45], v[116:117], v[22:23] op_sel_hi:[0,1]
	v_fmac_f32_e32 v19, v37, v21
	v_pk_mul_f32 v[20:21], v[108:109], v[22:23] op_sel_hi:[0,1]
	v_mul_f32_e32 v22, v35, v27
	v_fmac_f32_e32 v22, v34, v26
	v_fmac_f32_e32 v22, v36, v28
	v_fmac_f32_e32 v22, v37, v29
	v_add_f32_e32 v51, v59, v22
	v_mul_f32_e32 v22, v35, v67
	v_fmac_f32_e32 v22, v34, v66
	v_fmac_f32_e32 v46, v40, v28
	v_pk_fma_f32 v[20:21], v[98:99], v[34:35], v[20:21] op_sel_hi:[0,1,1]
	v_fmac_f32_e32 v22, v36, v68
	v_add_f32_e32 v157, v157, v162
	v_fmac_f32_e32 v46, v41, v29
	v_pk_fma_f32 v[20:21], v[106:107], v[30:31], v[20:21] op_sel_hi:[0,1,1]
	v_fmac_f32_e32 v22, v37, v69
	v_add_f32_e32 v58, v157, v50
	v_add_f32_e32 v56, v153, v42
	v_pk_mul_f32 v[42:43], v[116:117], v[24:25] op_sel_hi:[0,1]
	v_pk_fma_f32 v[44:45], v[98:99], v[38:39], v[44:45] op_sel_hi:[0,1,1]
	v_add_f32_e32 v55, v152, v46
	v_mul_f32_e32 v46, v39, v67
	v_mul_f32_e32 v39, v39, v75
	v_add_f32_e32 v52, v149, v19
	v_pk_mul_f32 v[18:19], v[108:109], v[24:25] op_sel_hi:[0,1]
	v_add_f32_e32 v50, v143, v22
	v_pk_fma_f32 v[22:23], v[104:105], v[70:71], v[20:21] op_sel_hi:[0,1,1]
	v_mul_f32_e32 v20, v35, v75
	v_pk_fma_f32 v[42:43], v[98:99], v[40:41], v[42:43] op_sel_hi:[0,1,1]
	v_fmac_f32_e32 v39, v38, v74
	v_pk_fma_f32 v[18:19], v[98:99], v[36:37], v[18:19] op_sel_hi:[0,1,1]
	v_fmac_f32_e32 v20, v34, v74
	v_pk_fma_f32 v[42:43], v[114:115], v[32:33], v[42:43] op_sel_hi:[0,1,1]
	v_pk_fma_f32 v[44:45], v[114:115], v[30:31], v[44:45] op_sel_hi:[0,1,1]
	v_fmac_f32_e32 v46, v38, v66
	v_fmac_f32_e32 v39, v40, v76
	v_pk_fma_f32 v[18:19], v[106:107], v[32:33], v[18:19] op_sel_hi:[0,1,1]
	v_fmac_f32_e32 v20, v36, v76
	v_fmac_f32_e32 v46, v40, v68
	v_pk_fma_f32 v[42:43], v[112:113], v[72:73], v[42:43] op_sel_hi:[0,1,1]
	v_pk_fma_f32 v[44:45], v[112:113], v[70:71], v[44:45] op_sel_hi:[0,1,1]
	v_fmac_f32_e32 v39, v41, v77
	v_pk_fma_f32 v[18:19], v[104:105], v[72:73], v[18:19] op_sel_hi:[0,1,1]
	v_fmac_f32_e32 v20, v37, v77
	v_fmac_f32_e32 v46, v41, v69
	v_add_f32_e32 v53, v150, v39
	v_pk_fma_f32 v[40:41], v[110:111], v[80:81], v[42:43] op_sel_hi:[0,1,1]
	v_pk_fma_f32 v[38:39], v[110:111], v[78:79], v[44:45] op_sel_hi:[0,1,1]
	v_add_f32_e32 v59, v142, v20
	v_pk_fma_f32 v[20:21], v[0:1], v[80:81], v[18:19] op_sel_hi:[0,1,1]
	v_pk_fma_f32 v[18:19], v[0:1], v[78:79], v[22:23] op_sel_hi:[0,1,1]
	global_store_dwordx4 v[138:139], v[38:41], off offset:768 nt
	global_store_dwordx4 v[136:137], v[18:21], off offset:768 nt
	v_add_f32_e32 v63, v170, v54
	v_add_f32_e32 v54, v151, v46
	ds_read_b128 v[18:21], v123 offset:896
	ds_read_b128 v[22:25], v123 offset:4992
	ds_read_b128 v[26:29], v123 offset:1920
	ds_read_b128 v[30:33], v123 offset:6016
	ds_read_b128 v[34:37], v123 offset:2944
	ds_read_b128 v[38:41], v123 offset:7040
	ds_read_b128 v[42:45], v123 offset:3968
	ds_read_b128 v[46:49], v123 offset:8064
	s_waitcnt vmcnt(15) lgkmcnt(7)
; #define LAS __attribute__((address_space(3)))
; __device__ __forceinline__ unsigned cvt_pk_bf16(float lo, float hi) { unsigned r; asm volatile("v_cvt_pk_bf16_f32 %0, %1, %2" : "=v"(r) : "v"(lo), "v"(hi)); return r; }
; __device__ __forceinline__ float bf2f(bf16_t h) { return __uint_as_float((unsigned)h << 16); }
; __device__ __forceinline__ float sigmoidf_(float x) { return 1.f / (1.f + __expf(-x)); }
; __device__ __forceinline__ void mlstm_sample_unit(const Frame& F, int b, int h) {
;     ...
;         for (int i2 = 0; i2 < 2; ++i2) { const int it = hh * 2 + i2; const int d = it * 32 + seg * 4;
;             f32x4 q[4], k[4];
; #pragma unroll
;             for (int t = 0; t < 4; ++t) { q[t] = *(const LAS f32x4*)(sq + t * 256 + d); k[t] = *(const LAS f32x4*)(sk + t * 256 + d); }
; #pragma unroll
;             for (int rg = 0; rg < 4; ++rg) { const f32x4 cv = c[hh & 1][i2][rg]; f32x4 nv = cv * decay;
; #pragma unroll
;                 for (int t = 0; t < 4; ++t) { acc[rg][t] += cv[0] * q[t][0] + cv[1] * q[t][1] + cv[2] * q[t][2] + cv[3] * q[t][3]; nv += k[t] * gv[rg][t]; }
;                 __builtin_nontemporal_store(nv, (f32x4*)(c1b + rg * 2048 + it * 32)); } }
;     }
;     __syncthreads();
;     float hv[4][4], ssq[4] = {0.f, 0.f, 0.f, 0.f};
; #pragma unroll
;     for (int rg = 0; rg < 4; ++rg)
; #pragma unroll
;         for (int t = 0; t < 4; ++t) { float a = acc[rg][t]; a += __shfl_xor(a, 1); a += __shfl_xor(a, 2); a += __shfl_xor(a, 4);
;     ...
;         for (int t = 0; t < 4; ++t) if (seg == ((rg * 4 + t) & 7)) { const int vr = w * 32 + rg * 8 + r8; const size_t row = (size_t)(SP + b * 4 + t);
;             const float rms = rsqrtf(sS[32 + t] * (1.f / 256.f) + EPS); const float og = sigmoidf_(bf2f(P[row * NIN + C_MO + h * 256 + vr]));
;             MIX[row * D + 1024 + h * 256 + vr] = (bf16_t)(cvt_pk_bf16(hv[rg][t] * rms * F.in[18][h * 256 + vr] * og, 0.f) & 0xffff); }
	v_mul_f32_e32 v66, v15, v19
	v_fmac_f32_e32 v66, v14, v18
	v_fmac_f32_e32 v66, v16, v20
	v_fmac_f32_e32 v66, v17, v21
	v_add_f32_e32 v70, v65, v66
	s_waitcnt lgkmcnt(5)
	v_mul_f32_e32 v65, v15, v27
	v_fmac_f32_e32 v65, v14, v26
	v_pk_mul_f32 v[68:69], v[132:133], v[22:23] op_sel_hi:[0,1]
	v_fmac_f32_e32 v65, v16, v28
	v_pk_fma_f32 v[68:69], v[98:99], v[14:15], v[68:69] op_sel_hi:[0,1,1]
	v_fmac_f32_e32 v65, v17, v29
	v_pk_mul_f32 v[66:67], v[132:133], v[24:25] op_sel_hi:[0,1]
	v_add_f32_e32 v71, v64, v65
	s_waitcnt lgkmcnt(4)
	v_pk_fma_f32 v[64:65], v[130:131], v[30:31], v[68:69] op_sel_hi:[0,1,1]
	s_waitcnt lgkmcnt(3)
	v_mul_f32_e32 v68, v15, v35
	s_waitcnt lgkmcnt(1)
	v_mul_f32_e32 v15, v15, v43
	v_pk_fma_f32 v[66:67], v[98:99], v[16:17], v[66:67] op_sel_hi:[0,1,1]
	v_fmac_f32_e32 v15, v14, v42
	v_pk_fma_f32 v[66:67], v[130:131], v[32:33], v[66:67] op_sel_hi:[0,1,1]
	v_fmac_f32_e32 v68, v14, v34
	v_fmac_f32_e32 v15, v16, v44
	v_fmac_f32_e32 v68, v16, v36
	v_pk_fma_f32 v[66:67], v[128:129], v[40:41], v[66:67] op_sel_hi:[0,1,1]
	v_pk_fma_f32 v[64:65], v[128:129], v[38:39], v[64:65] op_sel_hi:[0,1,1]
	v_fmac_f32_e32 v15, v17, v45
	v_fmac_f32_e32 v68, v17, v37
	v_add_f32_e32 v62, v62, v15
	s_waitcnt lgkmcnt(0)
	v_pk_fma_f32 v[14:15], v[126:127], v[46:47], v[64:65] op_sel_hi:[0,1,1]
	v_pk_fma_f32 v[16:17], v[126:127], v[48:49], v[66:67] op_sel_hi:[0,1,1]
	global_store_dwordx4 v[134:135], v[14:17], off offset:896 nt
	s_waitcnt vmcnt(15)
	v_mul_f32_e32 v64, v11, v27
	v_fmac_f32_e32 v64, v10, v26
	v_mul_f32_e32 v14, v11, v19
	v_fmac_f32_e32 v14, v10, v18
	v_fmac_f32_e32 v14, v12, v20
	v_fmac_f32_e32 v64, v12, v28
	v_fmac_f32_e32 v14, v13, v21
	v_pk_mul_f32 v[16:17], v[124:125], v[22:23] op_sel_hi:[0,1]
	v_fmac_f32_e32 v64, v13, v29
	v_add_f32_e32 v61, v61, v14
	v_pk_mul_f32 v[14:15], v[124:125], v[24:25] op_sel_hi:[0,1]
	v_pk_fma_f32 v[16:17], v[98:99], v[10:11], v[16:17] op_sel_hi:[0,1,1]
	v_add_f32_e32 v60, v60, v64
	v_mul_f32_e32 v64, v11, v35
	v_mul_f32_e32 v11, v11, v43
	v_pk_fma_f32 v[14:15], v[98:99], v[12:13], v[14:15] op_sel_hi:[0,1,1]
	v_fmac_f32_e32 v11, v10, v42
	v_pk_fma_f32 v[14:15], v[122:123], v[32:33], v[14:15] op_sel_hi:[0,1,1]
	v_pk_fma_f32 v[16:17], v[122:123], v[30:31], v[16:17] op_sel_hi:[0,1,1]
	v_fmac_f32_e32 v64, v10, v34
	v_fmac_f32_e32 v11, v12, v44
	v_fmac_f32_e32 v64, v12, v36
	v_pk_fma_f32 v[14:15], v[120:121], v[40:41], v[14:15] op_sel_hi:[0,1,1]
	v_pk_fma_f32 v[16:17], v[120:121], v[38:39], v[16:17] op_sel_hi:[0,1,1]
	v_fmac_f32_e32 v11, v13, v45
	v_fmac_f32_e32 v64, v13, v37
	v_add_f32_e32 v57, v57, v11
	v_pk_fma_f32 v[12:13], v[118:119], v[48:49], v[14:15] op_sel_hi:[0,1,1]
	v_pk_fma_f32 v[10:11], v[118:119], v[46:47], v[16:17] op_sel_hi:[0,1,1]
	global_store_dwordx4 v[140:141], v[10:13], off offset:896 nt
	s_waitcnt vmcnt(15)
	v_mul_f32_e32 v14, v7, v27
	v_fmac_f32_e32 v14, v6, v26
	v_mul_f32_e32 v10, v7, v19
	v_fmac_f32_e32 v10, v6, v18
	v_fmac_f32_e32 v10, v8, v20
	v_fmac_f32_e32 v14, v8, v28
	v_fmac_f32_e32 v10, v9, v21
	v_pk_mul_f32 v[12:13], v[116:117], v[22:23] op_sel_hi:[0,1]
	v_fmac_f32_e32 v14, v9, v29
	v_add_f32_e32 v56, v56, v10
	v_pk_mul_f32 v[10:11], v[116:117], v[24:25] op_sel_hi:[0,1]
	v_pk_fma_f32 v[12:13], v[98:99], v[6:7], v[12:13] op_sel_hi:[0,1,1]
	v_add_f32_e32 v55, v55, v14
	v_mul_f32_e32 v14, v7, v35
	v_mul_f32_e32 v7, v7, v43
	v_pk_fma_f32 v[10:11], v[98:99], v[8:9], v[10:11] op_sel_hi:[0,1,1]
	v_fmac_f32_e32 v7, v6, v42
	v_pk_fma_f32 v[10:11], v[114:115], v[32:33], v[10:11] op_sel_hi:[0,1,1]
	v_pk_fma_f32 v[12:13], v[114:115], v[30:31], v[12:13] op_sel_hi:[0,1,1]
	v_fmac_f32_e32 v14, v6, v34
	v_fmac_f32_e32 v7, v8, v44
	v_fmac_f32_e32 v14, v8, v36
	v_pk_fma_f32 v[10:11], v[112:113], v[40:41], v[10:11] op_sel_hi:[0,1,1]
	v_pk_fma_f32 v[12:13], v[112:113], v[38:39], v[12:13] op_sel_hi:[0,1,1]
	v_fmac_f32_e32 v7, v9, v45
	v_fmac_f32_e32 v14, v9, v37
	v_add_f32_e32 v53, v53, v7
	v_pk_fma_f32 v[8:9], v[110:111], v[48:49], v[10:11] op_sel_hi:[0,1,1]
	v_pk_fma_f32 v[6:7], v[110:111], v[46:47], v[12:13] op_sel_hi:[0,1,1]
	global_store_dwordx4 v[138:139], v[6:9], off offset:896 nt
	s_waitcnt vmcnt(15)
	v_mul_f32_e32 v10, v3, v27
	v_fmac_f32_e32 v10, v2, v26
	v_mul_f32_e32 v6, v3, v19
	v_fmac_f32_e32 v6, v2, v18
	v_fmac_f32_e32 v6, v4, v20
	v_fmac_f32_e32 v10, v4, v28
	v_fmac_f32_e32 v6, v5, v21
	v_pk_mul_f32 v[8:9], v[108:109], v[22:23] op_sel_hi:[0,1]
	v_fmac_f32_e32 v10, v5, v29
	v_add_f32_e32 v52, v52, v6
	v_pk_mul_f32 v[6:7], v[108:109], v[24:25] op_sel_hi:[0,1]
	v_pk_fma_f32 v[8:9], v[98:99], v[2:3], v[8:9] op_sel_hi:[0,1,1]
	v_add_f32_e32 v51, v51, v10
	v_mul_f32_e32 v10, v3, v35
	v_mul_f32_e32 v3, v3, v43
	v_pk_fma_f32 v[6:7], v[98:99], v[4:5], v[6:7] op_sel_hi:[0,1,1]
	v_fmac_f32_e32 v3, v2, v42
	v_pk_fma_f32 v[6:7], v[106:107], v[32:33], v[6:7] op_sel_hi:[0,1,1]
	v_pk_fma_f32 v[8:9], v[106:107], v[30:31], v[8:9] op_sel_hi:[0,1,1]
	v_fmac_f32_e32 v10, v2, v34
	v_fmac_f32_e32 v3, v4, v44
	v_fmac_f32_e32 v10, v4, v36
	v_pk_fma_f32 v[6:7], v[104:105], v[40:41], v[6:7] op_sel_hi:[0,1,1]
	v_pk_fma_f32 v[8:9], v[104:105], v[38:39], v[8:9] op_sel_hi:[0,1,1]
	v_fmac_f32_e32 v3, v5, v45
	v_fmac_f32_e32 v10, v5, v37
	v_add_f32_e32 v45, v59, v3
	v_pk_fma_f32 v[4:5], v[0:1], v[48:49], v[6:7] op_sel_hi:[0,1,1]
	v_pk_fma_f32 v[2:3], v[0:1], v[46:47], v[8:9] op_sel_hi:[0,1,1]
	ds_bpermute_b32 v0, v109, v70
	global_store_dwordx4 v[136:137], v[2:5], off offset:896 nt
	v_add_f32_e32 v54, v54, v14
	v_add_f32_e32 v50, v50, v10
	s_waitcnt lgkmcnt(0)
	v_add_f32_e32 v0, v70, v0
	ds_bpermute_b32 v2, v107, v0
	s_mul_hi_i32 vcc_hi, s54, 0x2c00
	s_mul_i32 vcc_lo, s54, 0x2c00
	s_add_u32 s28, s44, vcc_lo
	s_addc_u32 s29, s45, vcc_hi
	s_lshl_b32 vcc_lo, s30, 1
	s_add_u32 s28, s28, vcc_lo
	s_addc_u32 s29, s29, 0
	v_readlane_b32 s0, v245, 25
	v_readlane_b32 s1, v245, 26
	v_and_b32_e32 v207, 3, v144
	v_bfe_u32 v208, v144, 2, 1
	v_mul_u32_u24_e32 v209, 0x2c00, v207
	v_lshl_add_u32 v209, v208, 4, v209
	v_lshlrev_b32_e32 v210, 1, v84
	v_add3_u32 v212, v210, v209, s76
	v_mov_b32_e32 v213, 0
	v_lshl_add_u64 v[212:213], s[28:29], 0, v[212:213]
	global_load_ushort v203, v[212:213], off offset:1024
	global_load_ushort v204, v[212:213], off offset:1056
	v_add_u32_e32 v210, s30, v84
	v_mov_b32_e32 v211, 0
	v_lshl_add_u64 v[210:211], v[210:211], 2, s[0:1]
	v_lshlrev_b32_e32 v214, 5, v208
	v_mov_b32_e32 v215, 0
	v_lshl_add_u64 v[210:211], v[210:211], 0, v[214:215]
	global_load_dword v205, v[210:211], off
	global_load_dword v206, v[210:211], off offset:64
	s_barrier
; __device__ __forceinline__ void mlstm_sample_unit(const Frame& F, int b, int h) {
;     ...
;         for (int t = 0; t < 4; ++t) { float a = acc[rg][t]; a += __shfl_xor(a, 1); a += __shfl_xor(a, 2); a += __shfl_xor(a, 4);
;             float num = sS[40 + t] * a;
; #pragma unroll
;             for (int s2 = 0; s2 < 4; ++s2) num += sS[48 + t * 4 + s2] * sv[s2 * 256 + w * 32 + rg * 8 + r8];
;             hv[rg][t] = num / sS[44 + t]; if (seg == 0) ssq[t] += hv[rg][t] * hv[rg][t]; }
	s_waitcnt lgkmcnt(0)
	v_add_f32_e32 v63, v63, v68
	v_add_f32_e32 v58, v58, v64
	v_add_f32_e32 v0, v0, v2
	ds_bpermute_b32 v2, v105, v0
	s_waitcnt lgkmcnt(0)
	v_add_f32_e32 v0, v0, v2
	ds_read_b128 v[6:9], v1 offset:12448
	ds_read_b128 v[2:5], v1 offset:12464
	ds_read_b128 v[14:17], v1 offset:12480
	ds_read_b128 v[10:13], v1 offset:12496
	ds_read2_b32 v[26:27], v155 offset1:8
	ds_read2_b32 v[28:29], v154 offset1:8
	ds_read2_b32 v[30:31], v147 offset1:8
	ds_read2_b32 v[32:33], v95 offset1:8
	s_waitcnt lgkmcnt(3)
	v_mul_f32_e32 v18, v14, v26
	v_fmac_f32_e32 v18, v6, v0
	s_waitcnt lgkmcnt(2)
	v_fmac_f32_e32 v18, v15, v28
	s_waitcnt lgkmcnt(1)
	v_fmac_f32_e32 v18, v16, v30
	s_waitcnt lgkmcnt(0)
	v_fmac_f32_e32 v18, v17, v32
	v_div_scale_f32 v0, s[0:1], v2, v2, v18
	v_rcp_f32_e32 v19, v0
	s_nop 0
	v_fma_f32 v20, -v0, v19, 1.0
	v_fmac_f32_e32 v19, v20, v19
	v_div_scale_f32 v20, vcc, v18, v2, v18
	v_mul_f32_e32 v21, v20, v19
	v_fma_f32 v22, -v0, v21, v20
	v_fmac_f32_e32 v21, v22, v19
	v_fma_f32 v0, -v0, v21, v20
	v_div_fmas_f32 v0, v0, v19, v21
	v_div_fixup_f32 v43, v0, v2, v18
	ds_bpermute_b32 v0, v109, v71
	s_waitcnt lgkmcnt(0)
	v_add_f32_e32 v0, v71, v0
	ds_bpermute_b32 v18, v107, v0
	s_waitcnt lgkmcnt(0)
	v_add_f32_e32 v0, v0, v18
	ds_bpermute_b32 v18, v105, v0
	s_waitcnt lgkmcnt(0)
	v_add_f32_e32 v0, v0, v18
	v_mul_f32_e32 v18, v26, v10
	v_fmac_f32_e32 v18, v7, v0
	v_fmac_f32_e32 v18, v28, v11
	v_fmac_f32_e32 v18, v30, v12
	v_fmac_f32_e32 v18, v32, v13
	v_div_scale_f32 v0, s[0:1], v3, v3, v18
	v_rcp_f32_e32 v19, v0
	s_nop 0
	v_fma_f32 v20, -v0, v19, 1.0
	v_fmac_f32_e32 v19, v20, v19
	v_div_scale_f32 v20, vcc, v18, v3, v18
	v_mul_f32_e32 v21, v20, v19
	v_fma_f32 v22, -v0, v21, v20
	v_fmac_f32_e32 v21, v22, v19
	v_fma_f32 v0, -v0, v21, v20
	v_div_fmas_f32 v0, v0, v19, v21
	v_div_fixup_f32 v44, v0, v3, v18
	ds_bpermute_b32 v0, v109, v63
	s_waitcnt lgkmcnt(0)
	v_add_f32_e32 v0, v63, v0
	ds_bpermute_b32 v18, v107, v0
	s_waitcnt lgkmcnt(0)
	v_add_f32_e32 v0, v0, v18
	ds_bpermute_b32 v18, v105, v0
	s_waitcnt lgkmcnt(0)
	v_add_f32_e32 v0, v0, v18
	ds_read_b128 v[18:21], v1 offset:12512
	s_waitcnt lgkmcnt(0)
	v_mul_f32_e32 v22, v26, v18
	v_fmac_f32_e32 v22, v8, v0
	v_fmac_f32_e32 v22, v28, v19
	v_fmac_f32_e32 v22, v30, v20
	v_fmac_f32_e32 v22, v32, v21
	v_div_scale_f32 v0, s[0:1], v4, v4, v22
	v_rcp_f32_e32 v23, v0
	s_nop 0
	v_fma_f32 v24, -v0, v23, 1.0
	v_fmac_f32_e32 v23, v24, v23
	v_div_scale_f32 v24, vcc, v22, v4, v22
	v_mul_f32_e32 v25, v24, v23
	v_fma_f32 v34, -v0, v25, v24
	v_fmac_f32_e32 v25, v34, v23
	v_fma_f32 v0, -v0, v25, v24
	v_div_fmas_f32 v0, v0, v23, v25
	v_div_fixup_f32 v42, v0, v4, v22
	ds_bpermute_b32 v0, v109, v62
	s_waitcnt lgkmcnt(0)
	v_add_f32_e32 v0, v62, v0
	ds_bpermute_b32 v22, v107, v0
	s_waitcnt lgkmcnt(0)
	v_add_f32_e32 v0, v0, v22
	ds_bpermute_b32 v22, v105, v0
	s_waitcnt lgkmcnt(0)
	v_add_f32_e32 v0, v0, v22
	ds_read_b128 v[22:25], v1 offset:12528
	s_waitcnt lgkmcnt(0)
	v_mul_f32_e32 v26, v26, v22
	v_fmac_f32_e32 v26, v9, v0
	v_fmac_f32_e32 v26, v28, v23
	v_fmac_f32_e32 v26, v30, v24
	v_fmac_f32_e32 v26, v32, v25
	v_div_scale_f32 v0, s[0:1], v5, v5, v26
	v_rcp_f32_e32 v28, v0
	s_nop 0
	v_fma_f32 v30, -v0, v28, 1.0
	v_fmac_f32_e32 v28, v30, v28
	v_div_scale_f32 v30, vcc, v26, v5, v26
	v_mul_f32_e32 v32, v30, v28
	v_fma_f32 v34, -v0, v32, v30
	v_fmac_f32_e32 v32, v34, v28
	v_fma_f32 v0, -v0, v32, v30
	v_div_fmas_f32 v0, v0, v28, v32
	v_div_fixup_f32 v41, v0, v5, v26
	ds_bpermute_b32 v0, v109, v61
	s_waitcnt lgkmcnt(0)
	v_add_f32_e32 v0, v61, v0
	ds_bpermute_b32 v26, v107, v0
	s_waitcnt lgkmcnt(0)
	v_add_f32_e32 v0, v0, v26
	ds_bpermute_b32 v26, v105, v0
	s_waitcnt lgkmcnt(0)
	v_add_f32_e32 v0, v0, v26
	v_mul_f32_e32 v0, v6, v0
	v_fmac_f32_e32 v0, v14, v27
	v_fmac_f32_e32 v0, v15, v29
	v_fmac_f32_e32 v0, v16, v31
	v_fmac_f32_e32 v0, v17, v33
	v_div_scale_f32 v26, s[0:1], v2, v2, v0
	v_rcp_f32_e32 v28, v26
	s_nop 0
	v_fma_f32 v30, -v26, v28, 1.0
	v_fmac_f32_e32 v28, v30, v28
	v_div_scale_f32 v30, vcc, v0, v2, v0
	v_mul_f32_e32 v32, v30, v28
	v_fma_f32 v34, -v26, v32, v30
	v_fmac_f32_e32 v32, v34, v28
	v_fma_f32 v26, -v26, v32, v30
	v_div_fmas_f32 v26, v26, v28, v32
	v_div_fixup_f32 v40, v26, v2, v0
	ds_bpermute_b32 v26, v109, v60
	v_mul_f32_e32 v0, v40, v40
	v_fmac_f32_e32 v0, v43, v43
	s_waitcnt lgkmcnt(0)
	v_add_f32_e32 v26, v60, v26
	ds_bpermute_b32 v28, v107, v26
	s_waitcnt lgkmcnt(0)
	v_add_f32_e32 v26, v26, v28
	ds_bpermute_b32 v28, v105, v26
	s_waitcnt lgkmcnt(0)
	v_add_f32_e32 v26, v26, v28
	v_mul_f32_e32 v26, v7, v26
	v_fmac_f32_e32 v26, v10, v27
	v_fmac_f32_e32 v26, v11, v29
	v_fmac_f32_e32 v26, v12, v31
	v_fmac_f32_e32 v26, v13, v33
	v_div_scale_f32 v28, s[0:1], v3, v3, v26
	v_rcp_f32_e32 v30, v28
	s_nop 0
	v_fma_f32 v32, -v28, v30, 1.0
	v_fmac_f32_e32 v30, v32, v30
	v_div_scale_f32 v32, vcc, v26, v3, v26
	v_mul_f32_e32 v34, v32, v30
	v_fma_f32 v35, -v28, v34, v32
	v_fmac_f32_e32 v34, v35, v30
	v_fma_f32 v28, -v28, v34, v32
	v_div_fmas_f32 v28, v28, v30, v34
	v_div_fixup_f32 v39, v28, v3, v26
	ds_bpermute_b32 v26, v109, v58
	v_mul_f32_e32 v46, v39, v39
	v_fmac_f32_e32 v46, v44, v44
	s_waitcnt lgkmcnt(0)
	v_add_f32_e32 v26, v58, v26
	ds_bpermute_b32 v28, v107, v26
	s_waitcnt lgkmcnt(0)
	v_add_f32_e32 v26, v26, v28
	ds_bpermute_b32 v28, v105, v26
	s_waitcnt lgkmcnt(0)
	v_add_f32_e32 v26, v26, v28
	v_mul_f32_e32 v26, v8, v26
	v_fmac_f32_e32 v26, v18, v27
	v_fmac_f32_e32 v26, v19, v29
	v_fmac_f32_e32 v26, v20, v31
	v_fmac_f32_e32 v26, v21, v33
	v_div_scale_f32 v28, s[0:1], v4, v4, v26
	v_rcp_f32_e32 v30, v28
	s_nop 0
	v_fma_f32 v32, -v28, v30, 1.0
	v_fmac_f32_e32 v30, v32, v30
	v_div_scale_f32 v32, vcc, v26, v4, v26
	v_mul_f32_e32 v34, v32, v30
	v_fma_f32 v35, -v28, v34, v32
	v_fmac_f32_e32 v34, v35, v30
	v_fma_f32 v28, -v28, v34, v32
	v_div_fmas_f32 v28, v28, v30, v34
	v_div_fixup_f32 v38, v28, v4, v26
	ds_bpermute_b32 v26, v109, v57
	v_mul_f32_e32 v47, v38, v38
	v_fmac_f32_e32 v47, v42, v42
	s_waitcnt lgkmcnt(0)
; __device__ __forceinline__ void mlstm_sample_unit(const Frame& F, int b, int h) {
;     ...
;         for (int t = 0; t < 4; ++t) { float a = acc[rg][t]; a += __shfl_xor(a, 1); a += __shfl_xor(a, 2); a += __shfl_xor(a, 4);
;             float num = sS[40 + t] * a;
; #pragma unroll
;             for (int s2 = 0; s2 < 4; ++s2) num += sS[48 + t * 4 + s2] * sv[s2 * 256 + w * 32 + rg * 8 + r8];
;             hv[rg][t] = num / sS[44 + t]; if (seg == 0) ssq[t] += hv[rg][t] * hv[rg][t]; }
	v_add_f32_e32 v26, v57, v26
	ds_bpermute_b32 v28, v107, v26
	s_waitcnt lgkmcnt(0)
	v_add_f32_e32 v26, v26, v28
	ds_bpermute_b32 v28, v105, v26
	s_waitcnt lgkmcnt(0)
	v_add_f32_e32 v26, v26, v28
	v_mul_f32_e32 v26, v9, v26
	v_fmac_f32_e32 v26, v22, v27
	v_fmac_f32_e32 v26, v23, v29
	v_fmac_f32_e32 v26, v24, v31
	v_fmac_f32_e32 v26, v25, v33
	v_div_scale_f32 v27, s[0:1], v5, v5, v26
	v_rcp_f32_e32 v28, v27
	ds_read2_b32 v[32:33], v95 offset0:16 offset1:24
	v_fma_f32 v29, -v27, v28, 1.0
	v_fmac_f32_e32 v28, v29, v28
	v_div_scale_f32 v29, vcc, v26, v5, v26
	v_mul_f32_e32 v30, v29, v28
	v_fma_f32 v31, -v27, v30, v29
	v_fmac_f32_e32 v30, v31, v28
	v_fma_f32 v27, -v27, v30, v29
	v_div_fmas_f32 v27, v27, v28, v30
	v_div_fixup_f32 v37, v27, v5, v26
	ds_bpermute_b32 v26, v109, v56
	ds_read2_b32 v[28:29], v154 offset0:16 offset1:24
	ds_read2_b32 v[30:31], v147 offset0:16 offset1:24
	v_mul_f32_e32 v48, v37, v37
	v_fmac_f32_e32 v48, v41, v41
	s_waitcnt lgkmcnt(2)
	v_add_f32_e32 v26, v56, v26
	ds_bpermute_b32 v27, v107, v26
	s_waitcnt lgkmcnt(0)
	v_add_f32_e32 v26, v26, v27
	ds_bpermute_b32 v27, v105, v26
	s_waitcnt lgkmcnt(0)
	v_add_f32_e32 v26, v26, v27
	v_mul_f32_e32 v34, v6, v26
	ds_read2_b32 v[26:27], v155 offset0:16 offset1:24
	s_waitcnt lgkmcnt(0)
	v_fmac_f32_e32 v34, v14, v26
	v_fmac_f32_e32 v34, v15, v28
	v_fmac_f32_e32 v34, v16, v30
	v_fmac_f32_e32 v34, v17, v32
	v_div_scale_f32 v35, s[0:1], v2, v2, v34
	v_rcp_f32_e32 v36, v35
	s_nop 0
	v_fma_f32 v49, -v35, v36, 1.0
	v_fmac_f32_e32 v36, v49, v36
	v_div_scale_f32 v49, vcc, v34, v2, v34
	v_mul_f32_e32 v56, v49, v36
	v_fma_f32 v57, -v35, v56, v49
	v_fmac_f32_e32 v56, v57, v36
	v_fma_f32 v35, -v35, v56, v49
	v_div_fmas_f32 v35, v35, v36, v56
	v_div_fixup_f32 v36, v35, v2, v34
	ds_bpermute_b32 v34, v109, v55
	v_fmac_f32_e32 v0, v36, v36
	s_waitcnt lgkmcnt(0)
	v_add_f32_e32 v34, v55, v34
	ds_bpermute_b32 v35, v107, v34
	s_waitcnt lgkmcnt(0)
	v_add_f32_e32 v34, v34, v35
	ds_bpermute_b32 v35, v105, v34
	s_waitcnt lgkmcnt(0)
	v_add_f32_e32 v34, v34, v35
	v_mul_f32_e32 v34, v7, v34
	v_fmac_f32_e32 v34, v10, v26
	v_fmac_f32_e32 v34, v11, v28
	v_fmac_f32_e32 v34, v12, v30
	v_fmac_f32_e32 v34, v13, v32
	v_div_scale_f32 v35, s[0:1], v3, v3, v34
	v_rcp_f32_e32 v49, v35
	s_nop 0
	v_fma_f32 v55, -v35, v49, 1.0
	v_fmac_f32_e32 v49, v55, v49
	v_div_scale_f32 v55, vcc, v34, v3, v34
	v_mul_f32_e32 v56, v55, v49
	v_fma_f32 v57, -v35, v56, v55
	v_fmac_f32_e32 v56, v57, v49
	v_fma_f32 v35, -v35, v56, v55
	v_div_fmas_f32 v35, v35, v49, v56
	v_div_fixup_f32 v35, v35, v3, v34
	ds_bpermute_b32 v34, v109, v54
	v_fmac_f32_e32 v46, v35, v35
	s_waitcnt lgkmcnt(0)
	v_add_f32_e32 v34, v54, v34
	ds_bpermute_b32 v49, v107, v34
	s_waitcnt lgkmcnt(0)
	v_add_f32_e32 v34, v34, v49
	ds_bpermute_b32 v49, v105, v34
	s_waitcnt lgkmcnt(0)
	v_add_f32_e32 v34, v34, v49
	v_mul_f32_e32 v34, v8, v34
	v_fmac_f32_e32 v34, v18, v26
	v_fmac_f32_e32 v34, v19, v28
	v_fmac_f32_e32 v34, v20, v30
	v_fmac_f32_e32 v34, v21, v32
	v_div_scale_f32 v49, s[0:1], v4, v4, v34
	v_rcp_f32_e32 v54, v49
	s_nop 0
	v_fma_f32 v55, -v49, v54, 1.0
	v_fmac_f32_e32 v54, v55, v54
	v_div_scale_f32 v55, vcc, v34, v4, v34
	v_mul_f32_e32 v56, v55, v54
	v_fma_f32 v57, -v49, v56, v55
	v_fmac_f32_e32 v56, v57, v54
	v_fma_f32 v49, -v49, v56, v55
	v_div_fmas_f32 v49, v49, v54, v56
	v_div_fixup_f32 v34, v49, v4, v34
	ds_bpermute_b32 v49, v109, v53
	v_fmac_f32_e32 v47, v34, v34
	s_waitcnt lgkmcnt(0)
	v_add_f32_e32 v49, v53, v49
	ds_bpermute_b32 v53, v107, v49
	s_waitcnt lgkmcnt(0)
	v_add_f32_e32 v49, v49, v53
	ds_bpermute_b32 v53, v105, v49
	s_waitcnt lgkmcnt(0)
	v_add_f32_e32 v49, v49, v53
	v_mul_f32_e32 v49, v9, v49
	v_fmac_f32_e32 v49, v22, v26
	v_fmac_f32_e32 v49, v23, v28
	v_fmac_f32_e32 v49, v24, v30
	v_fmac_f32_e32 v49, v25, v32
	v_div_scale_f32 v26, s[0:1], v5, v5, v49
	v_rcp_f32_e32 v28, v26
	s_nop 0
	v_fma_f32 v30, -v26, v28, 1.0
	v_fmac_f32_e32 v28, v30, v28
	v_div_scale_f32 v30, vcc, v49, v5, v49
	v_mul_f32_e32 v32, v30, v28
	v_fma_f32 v53, -v26, v32, v30
	v_fmac_f32_e32 v32, v53, v28
	v_fma_f32 v26, -v26, v32, v30
	v_div_fmas_f32 v26, v26, v28, v32
	ds_bpermute_b32 v28, v109, v52
	v_div_fixup_f32 v26, v26, v5, v49
	v_fmac_f32_e32 v48, v26, v26
	s_waitcnt lgkmcnt(0)
	v_add_f32_e32 v28, v52, v28
	ds_bpermute_b32 v30, v107, v28
	s_waitcnt lgkmcnt(0)
	v_add_f32_e32 v28, v28, v30
	ds_bpermute_b32 v30, v105, v28
	s_waitcnt lgkmcnt(0)
; __device__ __forceinline__ void lds_add(LAS float* p, float v) { __hip_atomic_fetch_add(p, v, __ATOMIC_RELAXED, __HIP_MEMORY_SCOPE_WORKGROUP); }
; __device__ __forceinline__ void mlstm_sample_unit(const Frame& F, int b, int h) {
;     ...
;         for (int t = 0; t < 4; ++t) { float a = acc[rg][t]; a += __shfl_xor(a, 1); a += __shfl_xor(a, 2); a += __shfl_xor(a, 4);
;             float num = sS[40 + t] * a;
; #pragma unroll
;             for (int s2 = 0; s2 < 4; ++s2) num += sS[48 + t * 4 + s2] * sv[s2 * 256 + w * 32 + rg * 8 + r8];
;             hv[rg][t] = num / sS[44 + t]; if (seg == 0) ssq[t] += hv[rg][t] * hv[rg][t]; }
; #pragma unroll
;     for (int t = 0; t < 4; ++t) { ssq[t] = wave_sum(ssq[t]); }
;     if (lane == 0) {
; #pragma unroll
;         for (int t = 0; t < 4; ++t) lds_add(&sS[32 + t], ssq[t]); }
	v_add_f32_e32 v28, v28, v30
	v_mul_f32_e32 v6, v6, v28
	v_fmac_f32_e32 v6, v14, v27
	v_fmac_f32_e32 v6, v15, v29
	v_fmac_f32_e32 v6, v16, v31
	v_fmac_f32_e32 v6, v17, v33
	v_div_scale_f32 v14, s[0:1], v2, v2, v6
	v_rcp_f32_e32 v15, v14
	s_nop 0
	v_fma_f32 v16, -v14, v15, 1.0
	v_fmac_f32_e32 v15, v16, v15
	v_div_scale_f32 v16, vcc, v6, v2, v6
	v_mul_f32_e32 v17, v16, v15
	v_fma_f32 v28, -v14, v17, v16
	v_fmac_f32_e32 v17, v28, v15
	v_fma_f32 v14, -v14, v17, v16
	v_div_fmas_f32 v14, v14, v15, v17
	v_div_fixup_f32 v14, v14, v2, v6
	ds_bpermute_b32 v2, v109, v51
	v_fmac_f32_e32 v0, v14, v14
	v_cndmask_b32_e64 v0, 0, v0, s[8:9]
	s_waitcnt lgkmcnt(0)
	v_add_f32_e32 v2, v51, v2
	ds_bpermute_b32 v6, v107, v2
	s_waitcnt lgkmcnt(0)
	v_add_f32_e32 v2, v2, v6
	ds_bpermute_b32 v6, v105, v2
	s_waitcnt lgkmcnt(0)
	v_add_f32_e32 v2, v2, v6
	v_mul_f32_e32 v2, v7, v2
	v_fmac_f32_e32 v2, v10, v27
	v_fmac_f32_e32 v2, v11, v29
	v_fmac_f32_e32 v2, v12, v31
	v_fmac_f32_e32 v2, v13, v33
	v_div_scale_f32 v6, s[0:1], v3, v3, v2
	v_rcp_f32_e32 v7, v6
	s_nop 0
	v_fma_f32 v10, -v6, v7, 1.0
	v_fmac_f32_e32 v7, v10, v7
	v_div_scale_f32 v10, vcc, v2, v3, v2
	v_mul_f32_e32 v11, v10, v7
	v_fma_f32 v12, -v6, v11, v10
	v_fmac_f32_e32 v11, v12, v7
	v_fma_f32 v6, -v6, v11, v10
	v_div_fmas_f32 v6, v6, v7, v11
	v_div_fixup_f32 v10, v6, v3, v2
	ds_bpermute_b32 v3, v109, v50
	v_fmac_f32_e32 v46, v10, v10
	v_cndmask_b32_e64 v2, 0, v46, s[8:9]
	s_waitcnt lgkmcnt(0)
	v_add_f32_e32 v3, v50, v3
	ds_bpermute_b32 v6, v107, v3
	s_waitcnt lgkmcnt(0)
	v_add_f32_e32 v3, v3, v6
	ds_bpermute_b32 v6, v105, v3
	s_waitcnt lgkmcnt(0)
	v_add_f32_e32 v3, v3, v6
	v_mul_f32_e32 v3, v8, v3
	v_fmac_f32_e32 v3, v18, v27
	v_fmac_f32_e32 v3, v19, v29
	v_fmac_f32_e32 v3, v20, v31
	v_fmac_f32_e32 v3, v21, v33
	v_div_scale_f32 v6, s[0:1], v4, v4, v3
	v_rcp_f32_e32 v7, v6
	s_nop 0
	v_fma_f32 v8, -v6, v7, 1.0
	v_fmac_f32_e32 v7, v8, v7
	v_div_scale_f32 v8, vcc, v3, v4, v3
	v_mul_f32_e32 v11, v8, v7
	v_fma_f32 v12, -v6, v11, v8
	v_fmac_f32_e32 v11, v12, v7
	v_fma_f32 v6, -v6, v11, v8
	v_div_fmas_f32 v6, v6, v7, v11
	v_div_fixup_f32 v8, v6, v4, v3
	ds_bpermute_b32 v3, v109, v45
	v_fmac_f32_e32 v47, v8, v8
	v_cndmask_b32_e64 v4, 0, v47, s[8:9]
	s_waitcnt lgkmcnt(0)
	v_add_f32_e32 v3, v45, v3
	ds_bpermute_b32 v6, v107, v3
	s_waitcnt lgkmcnt(0)
	v_add_f32_e32 v3, v3, v6
	ds_bpermute_b32 v6, v105, v3
	s_waitcnt lgkmcnt(0)
	v_add_f32_e32 v3, v3, v6
	v_mul_f32_e32 v3, v9, v3
	v_fmac_f32_e32 v3, v22, v27
	v_fmac_f32_e32 v3, v23, v29
	v_fmac_f32_e32 v3, v24, v31
	v_fmac_f32_e32 v3, v25, v33
	v_div_scale_f32 v6, s[0:1], v5, v5, v3
	v_rcp_f32_e32 v7, v6
	s_nop 0
	v_fma_f32 v9, -v6, v7, 1.0
	v_fmac_f32_e32 v7, v9, v7
	v_div_scale_f32 v9, vcc, v3, v5, v3
	v_mul_f32_e32 v11, v9, v7
	v_fma_f32 v12, -v6, v11, v9
	v_fmac_f32_e32 v11, v12, v7
	v_fma_f32 v6, -v6, v11, v9
	v_div_fmas_f32 v6, v6, v7, v11
	v_div_fixup_f32 v9, v6, v5, v3
	ds_bpermute_b32 v3, v111, v0
	v_fmac_f32_e32 v48, v9, v9
	v_cndmask_b32_e64 v7, 0, v48, s[8:9]
	ds_bpermute_b32 v6, v111, v4
	ds_bpermute_b32 v11, v111, v7
	s_waitcnt lgkmcnt(2)
	v_add_f32_e32 v0, v0, v3
	ds_bpermute_b32 v3, v83, v0
	s_waitcnt lgkmcnt(2)
	v_add_f32_e32 v4, v4, v6
	s_waitcnt lgkmcnt(1)
	v_add_f32_e32 v7, v7, v11
	ds_bpermute_b32 v6, v83, v4
	s_waitcnt lgkmcnt(1)
	v_add_f32_e32 v0, v0, v3
	ds_bpermute_b32 v3, v99, v0
	ds_bpermute_b32 v11, v83, v7
	s_waitcnt lgkmcnt(2)
	v_add_f32_e32 v4, v4, v6
	ds_bpermute_b32 v6, v99, v4
	s_waitcnt lgkmcnt(2)
	v_add_f32_e32 v0, v0, v3
	ds_bpermute_b32 v3, v105, v0
	s_waitcnt lgkmcnt(2)
	v_add_f32_e32 v7, v7, v11
	ds_bpermute_b32 v11, v99, v7
	s_waitcnt lgkmcnt(2)
	v_add_f32_e32 v4, v4, v6
	ds_bpermute_b32 v6, v105, v4
	s_waitcnt lgkmcnt(2)
	v_add_f32_e32 v0, v0, v3
	ds_bpermute_b32 v3, v107, v0
	s_waitcnt lgkmcnt(2)
	v_add_f32_e32 v7, v7, v11
	ds_bpermute_b32 v11, v105, v7
	s_waitcnt lgkmcnt(2)
	v_add_f32_e32 v4, v4, v6
	ds_bpermute_b32 v6, v107, v4
	s_waitcnt lgkmcnt(2)
	v_add_f32_e32 v3, v0, v3
	ds_bpermute_b32 v0, v111, v2
	s_waitcnt lgkmcnt(2)
	v_add_f32_e32 v7, v7, v11
	ds_bpermute_b32 v11, v107, v7
	s_waitcnt lgkmcnt(2)
	v_add_f32_e32 v4, v4, v6
	ds_bpermute_b32 v5, v109, v3
	s_waitcnt lgkmcnt(2)
	v_add_f32_e32 v0, v2, v0
	ds_bpermute_b32 v2, v83, v0
	s_waitcnt lgkmcnt(2)
	v_add_f32_e32 v7, v7, v11
	ds_bpermute_b32 v6, v109, v4
	ds_bpermute_b32 v11, v109, v7
	s_waitcnt lgkmcnt(2)
	v_add_f32_e32 v0, v0, v2
	ds_bpermute_b32 v2, v99, v0
	s_waitcnt lgkmcnt(0)
	v_add_f32_e32 v0, v0, v2
	ds_bpermute_b32 v2, v105, v0
	s_waitcnt lgkmcnt(0)
	v_add_f32_e32 v0, v0, v2
	ds_bpermute_b32 v2, v107, v0
	s_waitcnt lgkmcnt(0)
	v_add_f32_e32 v0, v0, v2
	ds_bpermute_b32 v2, v109, v0
	s_and_saveexec_b64 s[0:1], s[10:11]
	s_cbranch_execz .LBB0_580
	s_mov_b64 s[42:43], exec
	v_add_f32_e32 v5, v3, v5
	v_bfrev_b32_e32 v3, 1

; __device__ __forceinline__ void mlstm_sample_unit(const Frame& F, int b, int h) {
;     ...
;     if (tid < 256) { float nn = decay * F.in[5][(size_t)bh * 256 + tid];
; #pragma unroll
;         for (int s2 = 0; s2 < 4; ++s2) nn += gs[s2] * sk[s2 * 256 + tid];
;         F.out[O_NS + (size_t)bh * 256 + tid] = nn; }
.LBB0_580:
	s_or_b64 exec, exec, s[0:1]
	s_and_saveexec_b64 s[0:1], s[36:37]
	s_cbranch_execz .LBB0_582
	s_waitcnt lgkmcnt(0)
	ds_read2st64_b32 v[2:3], v113 offset0:16 offset1:20
	ds_read2st64_b32 v[4:5], v113 offset0:24 offset1:28
	v_readlane_b32 s12, v245, 21
	v_readlane_b32 s26, v245, 35
	v_readlane_b32 s27, v245, 36
	s_add_u32 s28, s26, s62
	s_waitcnt lgkmcnt(1)
	v_pk_mul_f32 v[2:3], v[102:103], v[2:3]
	v_mov_b32_e32 v95, v1
	s_addc_u32 s29, s27, s63
	v_lshl_add_u64 v[6:7], s[28:29], 0, v[94:95]
	s_waitcnt lgkmcnt(0)
	v_pk_mul_f32 v[4:5], v[100:101], v[4:5]
	v_add_co_u32_e32 v6, vcc, 0xe541000, v6
	v_readlane_b32 s13, v245, 22
	s_nop 0
	v_addc_co_u32_e32 v7, vcc, 0, v7, vcc
	v_readlane_b32 s14, v245, 23
	v_readlane_b32 s15, v245, 24
	v_readlane_b32 s16, v245, 25
	v_readlane_b32 s17, v245, 26
	v_readlane_b32 s18, v245, 27
	v_readlane_b32 s19, v245, 28
	v_readlane_b32 s20, v245, 29
	v_readlane_b32 s21, v245, 30
	v_readlane_b32 s22, v245, 31
	v_readlane_b32 s23, v245, 32
	v_readlane_b32 s24, v245, 33
	v_readlane_b32 s25, v245, 34
	v_fma_f32 v0, v98, v202, v2
	v_add_f32_e32 v0, v0, v3
	v_add_f32_e32 v0, v0, v4
	v_add_f32_e32 v0, v0, v5
	global_store_dword v[6:7], v0, off offset:16

; __device__ __forceinline__ unsigned cvt_pk_bf16(float lo, float hi) { unsigned r; asm volatile("v_cvt_pk_bf16_f32 %0, %1, %2" : "=v"(r) : "v"(lo), "v"(hi)); return r; }
; __device__ __forceinline__ float bf2f(bf16_t h) { return __uint_as_float((unsigned)h << 16); }
; __device__ __forceinline__ float sigmoidf_(float x) { return 1.f / (1.f + __expf(-x)); }
; __device__ __forceinline__ void mlstm_sample_unit(const Frame& F, int b, int h) {
;     ...
; #pragma unroll
;     for (int rg = 0; rg < 4; ++rg)
; #pragma unroll
;         for (int t = 0; t < 4; ++t) if (seg == ((rg * 4 + t) & 7)) { const int vr = w * 32 + rg * 8 + r8; const size_t row = (size_t)(SP + b * 4 + t);
;             const float rms = rsqrtf(sS[32 + t] * (1.f / 256.f) + EPS); const float og = sigmoidf_(bf2f(P[row * NIN + C_MO + h * 256 + vr]));
;             MIX[row * D + 1024 + h * 256 + vr] = (bf16_t)(cvt_pk_bf16(hv[rg][t] * rms * F.in[18][h * 256 + vr] * og, 0.f) & 0xffff); }
.LBB0_584:
	s_or_b64 exec, exec, s[0:1]
	v_readlane_b32 s12, v245, 21
	v_add_u32_e32 v0, s30, v84
	s_lshl_b32 s30, s30, 1
	v_readlane_b32 s16, v245, 25
	v_readlane_b32 s17, v245, 26
	s_waitcnt lgkmcnt(0)
	v_lshl_add_u64 v[2:3], v[92:93], 0, s[30:31]
	s_mul_hi_i32 s43, s54, 0x2c00
	s_mul_i32 s64, s54, 0x2c00
	v_lshlrev_b32_e32 v6, 1, v84
	v_lshl_add_u64 v[4:5], v[0:1], 2, s[16:17]
	s_barrier
	v_readlane_b32 s13, v245, 22
	v_readlane_b32 s14, v245, 23
	v_readlane_b32 s15, v245, 24
	v_readlane_b32 s18, v245, 27
	v_readlane_b32 s19, v245, 28
	v_readlane_b32 s20, v245, 29
	v_readlane_b32 s21, v245, 30
	v_readlane_b32 s22, v245, 31
	v_readlane_b32 s23, v245, 32
	v_readlane_b32 s24, v245, 33
	v_readlane_b32 s25, v245, 34
	v_readlane_b32 s26, v245, 35
	v_readlane_b32 s27, v245, 36
	s_lshl_b64 s[56:57], s[54:55], 12
	v_and_b32_e32 v45, 3, v144
	v_bfe_u32 v46, v144, 2, 1
	v_mul_u32_u24_e32 v47, 0x2c00, v45
	v_lshl_add_u32 v47, v46, 4, v47
	v_lshlrev_b32_e32 v48, 12, v45
	v_lshl_add_u32 v48, v46, 4, v48
	v_lshlrev_b32_e32 v50, 2, v45
	ds_read_b32 v51, v50 offset:12416
	v_mov_b32_e32 v49, 0
	v_lshl_add_u64 v[60:61], v[2:3], 0, v[48:49]
	v_lshl_add_u64 v[60:61], v[60:61], 0, s[56:57]
	v_mov_b32_e32 v62, v37
	v_cndmask_b32_e64 v62, v62, v38, s[52:53]
	v_cndmask_b32_e64 v62, v62, v39, s[96:97]
	v_cndmask_b32_e64 v62, v62, v40, s[66:67]
	v_cndmask_b32_e64 v62, v62, v41, s[58:59]
	v_cndmask_b32_e64 v62, v62, v42, s[50:51]
	v_cndmask_b32_e64 v62, v62, v44, s[40:41]
	v_cndmask_b32_e64 v62, v62, v43, s[8:9]
	v_mov_b32_e32 v63, v9
	v_cndmask_b32_e64 v63, v63, v8, s[52:53]
	v_cndmask_b32_e64 v63, v63, v10, s[96:97]
	v_cndmask_b32_e64 v63, v63, v14, s[66:67]
	v_cndmask_b32_e64 v63, v63, v26, s[58:59]
	v_cndmask_b32_e64 v63, v63, v34, s[50:51]
	v_cndmask_b32_e64 v63, v63, v35, s[40:41]
	v_cndmask_b32_e64 v63, v63, v36, s[8:9]
	s_waitcnt lgkmcnt(0)
	v_fmamk_f32 v51, v51, 0x3b800000, v131
	v_mul_f32_e32 v64, 0x4b800000, v51
	v_cmp_gt_f32_e32 vcc, s82, v51
	s_nop 1
	v_cndmask_b32_e32 v51, v51, v64, vcc
	v_rsq_f32_e32 v51, v51
	s_nop 0
	v_mul_f32_e32 v64, 0x45800000, v51
	v_cndmask_b32_e32 v51, v51, v64, vcc
	v_mul_f32_e32 v62, v62, v51
	v_mul_f32_e32 v63, v63, v51
	s_waitcnt vmcnt(0)
	v_mul_f32_e32 v62, v205, v62
	v_mul_f32_e32 v63, v206, v63
	v_lshlrev_b32_e32 v203, 16, v203
	v_mul_f32_e32 v203, 0xbfb8aa3b, v203
	v_exp_f32_e32 v203, v203
	s_nop 0
	v_add_f32_e32 v203, 1.0, v203
	v_div_scale_f32 v65, s[0:1], v203, v203, 1.0
	v_rcp_f32_e32 v66, v65
	s_nop 0
	v_fma_f32 v67, -v65, v66, 1.0
	v_fmac_f32_e32 v66, v67, v66
	v_div_scale_f32 v67, vcc, 1.0, v203, 1.0
	v_mul_f32_e32 v68, v67, v66
	v_fma_f32 v69, -v65, v68, v67
	v_fmac_f32_e32 v68, v69, v66
	v_fma_f32 v65, -v65, v68, v67
	v_div_fmas_f32 v65, v65, v66, v68
	v_div_fixup_f32 v203, v65, v203, 1.0
	v_mul_f32_e32 v62, v203, v62
	v_cvt_pk_bf16_f32 v62, v62, v1
	global_store_short v[60:61], v62, off
	v_lshlrev_b32_e32 v204, 16, v204
	v_mul_f32_e32 v204, 0xbfb8aa3b, v204
	v_exp_f32_e32 v204, v204
	s_nop 0
	v_add_f32_e32 v204, 1.0, v204
	v_div_scale_f32 v65, s[0:1], v204, v204, 1.0
	v_rcp_f32_e32 v66, v65
	s_nop 0
	v_fma_f32 v67, -v65, v66, 1.0
	v_fmac_f32_e32 v66, v67, v66
	v_div_scale_f32 v67, vcc, 1.0, v204, 1.0
	v_mul_f32_e32 v68, v67, v66
	v_fma_f32 v69, -v65, v68, v67
	v_fmac_f32_e32 v68, v69, v66
	v_fma_f32 v65, -v65, v68, v67
	v_div_fmas_f32 v65, v65, v66, v68
	v_div_fixup_f32 v204, v65, v204, 1.0
	v_mul_f32_e32 v63, v204, v63
	v_cvt_pk_bf16_f32 v63, v63, v1
	global_store_short v[60:61], v63, off offset:32
	s_branch .LBB0_537
